# bundle: K2 staging on waves 4-7 + DPP/readlane row-pass reductions (P2, P7, P11) + SGPR-base K1/V loads in the MLA loop
# baseline (speedup 1.0000x reference)
; __device__ __forceinline__ unsigned pk2(float lo, float hi) { f32x2 v = {lo, hi}; bf16x2_t b = __builtin_convertvector(v, bf16x2_t); return __builtin_bit_cast(unsigned, b); }
; __device__ __forceinline__ float bf_lo(unsigned w) { return __uint_as_float(w << 16); }
; __device__ __forceinline__ float bf_hi(unsigned w) { return __uint_as_float(w & 0xffff0000u); }
; __device__ __forceinline__ float bf1(bf16_t w) { return __uint_as_float(((unsigned)w) << 16); }
; __device__ __forceinline__ f32x4 unpack4(u32x2 w) { return (f32x4){bf_lo(w.x), bf_hi(w.x), bf_lo(w.y), bf_hi(w.y)}; }
; __device__ __forceinline__ u32x2 pack4(f32x4 v) { u32x2 w; w.x = pk2(v[0], v[1]); w.y = pk2(v[2], v[3]); return w; }
; __global__ void __launch_bounds__(NTHREADS) mega(Args a) {
;     ...
;             const int rq = lane >> 4, ri = lane & 15;
;             const float t1 = bf1(pr[(size_t)rq * PRM + 1152 + ri]), t2 = bf1(pr[(size_t)rq * PRM + 1168 + ri]);
;             const float cs_ = CS[(size_t)(row0 + rq) * 32 + ri], sn = CS[(size_t)(row0 + rq) * 32 + 16 + ri];
;             f32x4 cqv[4]; float kv0[4], kv1[4], ssq[4], ssk[4];
; #pragma unroll
;             for (int q = 0; q < 4; ++q) { cqv[q] = unpack4(cqw[q]); kv0[q] = bf_lo(ckw[q]); kv1[q] = bf_hi(ckw[q]);
;                 ssq[q] = (cqv[q][0] * cqv[q][0] + cqv[q][1] * cqv[q][1]) + (cqv[q][2] * cqv[q][2] + cqv[q][3] * cqv[q][3]); ssk[q] = kv0[q] * kv0[q] + kv1[q] * kv1[q]; }
; #pragma unroll
;             for (int o = 1; o < 64; o <<= 1) {
; #pragma unroll
;                 for (int q = 0; q < 4; ++q) { ssq[q] += __shfl_xor(ssq[q], o); ssk[q] += __shfl_xor(ssk[q], o); } }
; #pragma unroll
;             for (int q = 0; q < 4; ++q) {
;                 const float rq_ = rsqrtf(ssq[q] * (1.f / 256.f) + EPS), rk_ = rsqrtf(ssk[q] * (1.f / 128.f) + EPS);
;                 ((u32x2*)(pr + (size_t)q * PRM + 768))[lane] = pack4(cqv[q] * rq_ * gq);
;                 ((unsigned*)(pr + (size_t)q * PRM + 1024))[lane] = pk2(kv0[q] * rk_ * gk[0], kv1[q] * rk_ * gk[1]);
;             }
.LBB0_461:
	s_mov_b64 s[0:1], 0x6400600
	v_lshl_add_u64 v[102:103], v[60:61], 0, s[0:1]
	s_mov_b64 s[0:1], 0x6400800
	v_lshl_add_u64 v[100:101], v[64:65], 0, s[0:1]
	s_mov_b64 s[0:1], 0x6401000
	v_lshl_add_u64 v[90:91], v[60:61], 0, s[0:1]
	s_mov_b64 s[0:1], 0x6401200
	v_lshl_add_u64 v[88:89], v[64:65], 0, s[0:1]
	s_mov_b64 s[0:1], 0x6401a00
	v_lshl_add_u64 v[76:77], v[60:61], 0, s[0:1]
	s_mov_b64 s[0:1], 0x6401c00
	v_lshl_add_u64 v[74:75], v[64:65], 0, s[0:1]
	s_mov_b64 s[0:1], 0x6402400
	v_lshl_add_u64 v[62:63], v[60:61], 0, s[0:1]
	s_mov_b64 s[0:1], 0x6402600
	v_lshl_add_u64 v[60:61], v[64:65], 0, s[0:1]
	v_lshl_add_u64 v[64:65], s[8:9], 0, v[26:27]
	v_add_co_u32_e32 v64, vcc, 0x6400000, v64
	s_waitcnt vmcnt(19)
	v_and_b32_e32 v111, 0xffff0000, v69
	v_addc_co_u32_e32 v65, vcc, 0, v65, vcc
	global_load_ushort v66, v[64:65], off offset:2304
	v_and_b32_e32 v110, 0xffff0000, v68
	global_load_ushort v64, v[64:65], off offset:2336
	s_waitcnt vmcnt(20)
	v_lshlrev_b32_e32 v106, 16, v81
	v_and_b32_e32 v107, 0xffff0000, v81
	v_lshlrev_b32_e32 v109, 16, v69
	v_lshlrev_b32_e32 v108, 16, v68
	v_pk_mul_f32 v[68:69], v[110:111], v[110:111]
	s_waitcnt vmcnt(17)
	v_lshlrev_b32_e32 v94, 16, v80
	v_pk_fma_f32 v[124:125], v[108:109], v[108:109], v[68:69]
	v_and_b32_e32 v95, 0xffff0000, v80
	v_pk_mul_f32 v[80:81], v[106:107], v[106:107]
	v_mov_b32_e32 v127, v124
	v_mov_b32_e32 v126, v80
	v_mov_b32_e32 v124, v81
	v_pk_add_f32 v[80:81], v[126:127], v[124:125]
	v_and_b32_e32 v99, 0xffff0000, v71
	v_and_b32_e32 v98, 0xffff0000, v70
	s_brev_b32 s0, 60
	v_lshlrev_b32_e32 v97, 16, v71
	s_nop 1
	v_add_f32_dpp v80, v80, v80 quad_perm:[1,0,3,2] row_mask:0xf bank_mask:0xf
	v_add_f32_dpp v81, v81, v81 quad_perm:[1,0,3,2] row_mask:0xf bank_mask:0xf
	v_lshlrev_b32_e32 v96, 16, v70
	v_pk_mul_f32 v[68:69], v[98:99], v[98:99]
	s_waitcnt vmcnt(15)
	v_and_b32_e32 v87, 0xffff0000, v73
	v_and_b32_e32 v86, 0xffff0000, v72
	s_nop 1
	v_add_f32_dpp v80, v80, v80 quad_perm:[2,3,0,1] row_mask:0xf bank_mask:0xf
	v_add_f32_dpp v81, v81, v81 quad_perm:[2,3,0,1] row_mask:0xf bank_mask:0xf
	s_mov_b32 s1, 0x3b800000
	v_pk_fma_f32 v[104:105], v[96:97], v[96:97], v[68:69]
	v_pk_mul_f32 v[68:69], v[86:87], v[86:87]
	v_mov_b32_e32 v128, v108
	s_nop 1
	v_add_f32_dpp v80, v80, v80 row_half_mirror row_mask:0xf bank_mask:0xf
	v_add_f32_dpp v81, v81, v81 row_half_mirror row_mask:0xf bank_mask:0xf
	v_mov_b32_e32 v129, v110
	v_mov_b32_e32 v110, v109
	s_waitcnt vmcnt(14)
	v_lshlrev_b32_e32 v82, 16, v83
	v_and_b32_e32 v83, 0xffff0000, v83
	s_nop 1
	v_add_f32_dpp v80, v80, v80 row_mirror row_mask:0xf bank_mask:0xf
	v_add_f32_dpp v81, v81, v81 row_mirror row_mask:0xf bank_mask:0xf
	s_waitcnt vmcnt(12)
	v_and_b32_e32 v71, 0xffff0000, v79
	v_and_b32_e32 v70, 0xffff0000, v78
	v_lshl_add_u64 v[22:23], v[22:23], 0, s[58:59]
	v_lshl_add_u64 v[24:25], v[24:25], 0, s[58:59]
	s_nop 1
	v_readlane_b32 s98, v80, 0
	v_readlane_b32 s99, v80, 16
	v_readlane_b32 s100, v80, 32
	v_readlane_b32 s101, v80, 48
	s_nop 1
	v_mov_b32_e32 v228, s98
	v_add_f32_e32 v228, s99, v228
	v_mov_b32_e32 v229, s100
	v_add_f32_e32 v229, s101, v229
	v_add_f32_e32 v80, v228, v229
	v_readlane_b32 s98, v81, 0
	v_readlane_b32 s99, v81, 16
	v_readlane_b32 s100, v81, 32
	v_readlane_b32 s101, v81, 48
	s_nop 1
	v_mov_b32_e32 v228, s98
	v_add_f32_e32 v228, s99, v228
	v_mov_b32_e32 v229, s100
	v_add_f32_e32 v229, s101, v229
	v_add_f32_e32 v81, v228, v229
	v_lshl_add_u64 v[26:27], v[26:27], 0, s[58:59]
	v_mov_b32_e32 v124, v80
	v_mov_b32_e32 v125, v81
	v_mov_b64_e32 v[80:81], s[36:37]
	v_pk_fma_f32 v[124:125], v[124:125], s[0:1], v[80:81] op_sel_hi:[1,1,0]
	s_waitcnt vmcnt(1)
	v_lshlrev_b32_e32 v112, 16, v66
	v_cmp_gt_f32_e64 s[6:7], s72, v125
	s_waitcnt vmcnt(0)
	v_lshlrev_b32_e32 v120, 16, v64
	v_add_u32_e32 v64, s14, v19
	v_ashrrev_i32_e32 v65, 31, v64
	v_lshlrev_b64 v[66:67], 5, v[64:65]
	v_or_b32_e32 v66, v66, v18
	v_lshl_add_u64 v[64:65], v[66:67], 2, s[10:11]
	global_load_dword v121, v[64:65], off
	v_or_b32_e32 v64, 16, v66
	v_mov_b32_e32 v65, v67
	v_lshl_add_u64 v[84:85], v[64:65], 2, s[10:11]
	global_load_dword v122, v[84:85], off
	v_lshlrev_b32_e32 v85, 16, v73
	v_lshlrev_b32_e32 v84, 16, v72
	v_pk_fma_f32 v[92:93], v[84:85], v[84:85], v[68:69]
	v_lshlrev_b32_e32 v68, 16, v123
	v_and_b32_e32 v69, 0xffff0000, v123
	v_mul_f32_e32 v123, 0x4b800000, v125
	v_cndmask_b32_e64 v123, v125, v123, s[6:7]
	v_rsq_f32_e32 v123, v123
	v_cmp_gt_f32_e32 vcc, s72, v124
	v_lshlrev_b32_e32 v73, 16, v79
	v_lshlrev_b32_e32 v72, 16, v78
	v_mul_f32_e32 v125, 0x45800000, v123
	v_cndmask_b32_e64 v126, v123, v125, s[6:7]
	v_pk_mul_f32 v[128:129], v[126:127], v[128:129] op_sel_hi:[0,1]
	v_pk_mul_f32 v[108:109], v[126:127], v[110:111] op_sel_hi:[0,1]
	v_pk_mul_f32 v[108:109], v[2:3], v[108:109]
	v_pk_mul_f32 v[110:111], v[0:1], v[128:129]
	v_pk_mul_f32 v[78:79], v[70:71], v[70:71]
	v_cvt_pk_bf16_f32 v110, v110, v111
	v_cvt_pk_bf16_f32 v111, v108, v109
	global_store_dwordx2 v[102:103], v[110:111], off
	v_mul_f32_e32 v102, 0x4b800000, v124
	v_cndmask_b32_e32 v102, v124, v102, vcc
	v_rsq_f32_e32 v102, v102
	v_pk_fma_f32 v[78:79], v[72:73], v[72:73], v[78:79]
	s_add_i32 s14, s14, s22
	s_cmpk_gt_i32 s14, 0x7fff
	v_mul_f32_e32 v103, 0x45800000, v102
	v_cndmask_b32_e32 v102, v102, v103, vcc
	v_pk_mul_f32 v[102:103], v[102:103], v[106:107] op_sel_hi:[0,1]
	v_pk_mul_f32 v[102:103], v[16:17], v[102:103]
	s_nop 0
	v_cvt_pk_bf16_f32 v102, v102, v103
	global_store_dword v[100:101], v102, off
	v_pk_mul_f32 v[100:101], v[94:95], v[94:95]
	v_mov_b32_e32 v103, v104
	v_mov_b32_e32 v102, v100
	v_mov_b32_e32 v104, v101
	v_pk_add_f32 v[100:101], v[102:103], v[104:105]
	v_mov_b32_e32 v104, v96
; __device__ __forceinline__ unsigned pk2(float lo, float hi) { f32x2 v = {lo, hi}; bf16x2_t b = __builtin_convertvector(v, bf16x2_t); return __builtin_bit_cast(unsigned, b); }
; __device__ __forceinline__ u32x2 pack4(f32x4 v) { u32x2 w; w.x = pk2(v[0], v[1]); w.y = pk2(v[2], v[3]); return w; }
; __global__ void __launch_bounds__(NTHREADS) mega(Args a) {
;     ...
;             for (int o = 1; o < 64; o <<= 1) {
; #pragma unroll
;                 for (int q = 0; q < 4; ++q) { ssq[q] += __shfl_xor(ssq[q], o); ssk[q] += __shfl_xor(ssk[q], o); } }
; #pragma unroll
;             for (int q = 0; q < 4; ++q) {
;                 const float rq_ = rsqrtf(ssq[q] * (1.f / 256.f) + EPS), rk_ = rsqrtf(ssk[q] * (1.f / 128.f) + EPS);
;                 ((u32x2*)(pr + (size_t)q * PRM + 768))[lane] = pack4(cqv[q] * rq_ * gq);
;                 ((unsigned*)(pr + (size_t)q * PRM + 1024))[lane] = pk2(kv0[q] * rk_ * gk[0], kv1[q] * rk_ * gk[1]);
;             }
	v_mov_b32_e32 v105, v98
	v_mov_b32_e32 v98, v97
	s_nop 1
	v_add_f32_dpp v100, v100, v100 quad_perm:[1,0,3,2] row_mask:0xf bank_mask:0xf
	v_add_f32_dpp v101, v101, v101 quad_perm:[1,0,3,2] row_mask:0xf bank_mask:0xf
	s_nop 1
	v_add_f32_dpp v100, v100, v100 quad_perm:[2,3,0,1] row_mask:0xf bank_mask:0xf
	v_add_f32_dpp v101, v101, v101 quad_perm:[2,3,0,1] row_mask:0xf bank_mask:0xf
	s_nop 1
	v_add_f32_dpp v100, v100, v100 row_half_mirror row_mask:0xf bank_mask:0xf
	v_add_f32_dpp v101, v101, v101 row_half_mirror row_mask:0xf bank_mask:0xf
	s_nop 1
	v_add_f32_dpp v100, v100, v100 row_mirror row_mask:0xf bank_mask:0xf
	v_add_f32_dpp v101, v101, v101 row_mirror row_mask:0xf bank_mask:0xf
	s_nop 1
	v_readlane_b32 s98, v100, 0
	v_readlane_b32 s99, v100, 16
	v_readlane_b32 s100, v100, 32
	v_readlane_b32 s101, v100, 48
	s_nop 1
	v_mov_b32_e32 v228, s98
	v_add_f32_e32 v228, s99, v228
	v_mov_b32_e32 v229, s100
	v_add_f32_e32 v229, s101, v229
	v_add_f32_e32 v100, v228, v229
	v_readlane_b32 s98, v101, 0
	v_readlane_b32 s99, v101, 16
	v_readlane_b32 s100, v101, 32
	v_readlane_b32 s101, v101, 48
	s_nop 1
	v_mov_b32_e32 v228, s98
	v_add_f32_e32 v228, s99, v228
	v_mov_b32_e32 v229, s100
	v_add_f32_e32 v229, s101, v229
	v_add_f32_e32 v101, v228, v229
	s_nop 0
	v_pk_fma_f32 v[100:101], v[100:101], s[0:1], v[80:81] op_sel_hi:[1,1,0]
	s_nop 0
	v_mul_f32_e32 v102, 0x4b800000, v101
	v_cmp_gt_f32_e64 s[6:7], s72, v101
	v_cmp_gt_f32_e32 vcc, s72, v100
	s_nop 0
	v_cndmask_b32_e64 v101, v101, v102, s[6:7]
	v_rsq_f32_e32 v101, v101
	s_nop 0
	v_mul_f32_e32 v102, 0x45800000, v101
	v_cndmask_b32_e64 v102, v101, v102, s[6:7]
	v_pk_mul_f32 v[104:105], v[102:103], v[104:105] op_sel_hi:[0,1]
	v_pk_mul_f32 v[96:97], v[102:103], v[98:99] op_sel_hi:[0,1]
	v_pk_mul_f32 v[96:97], v[2:3], v[96:97]
	v_pk_mul_f32 v[98:99], v[0:1], v[104:105]
	s_nop 0
	v_cvt_pk_bf16_f32 v98, v98, v99
	v_cvt_pk_bf16_f32 v99, v96, v97
	global_store_dwordx2 v[90:91], v[98:99], off
	v_mul_f32_e32 v90, 0x4b800000, v100
	v_cndmask_b32_e32 v90, v100, v90, vcc
	v_rsq_f32_e32 v90, v90
	s_nop 0
	v_mul_f32_e32 v91, 0x45800000, v90
	v_cndmask_b32_e32 v90, v90, v91, vcc
	v_pk_mul_f32 v[90:91], v[90:91], v[94:95] op_sel_hi:[0,1]
	v_pk_mul_f32 v[90:91], v[16:17], v[90:91]
	s_nop 0
	v_cvt_pk_bf16_f32 v90, v90, v91
	global_store_dword v[88:89], v90, off
	v_pk_mul_f32 v[88:89], v[82:83], v[82:83]
	v_mov_b32_e32 v91, v92
	v_mov_b32_e32 v90, v88
	v_mov_b32_e32 v92, v89
	v_pk_add_f32 v[88:89], v[90:91], v[92:93]
	v_mov_b32_e32 v92, v84
	v_mov_b32_e32 v93, v86
	v_mov_b32_e32 v86, v85
	s_nop 1
	v_add_f32_dpp v88, v88, v88 quad_perm:[1,0,3,2] row_mask:0xf bank_mask:0xf
	v_add_f32_dpp v89, v89, v89 quad_perm:[1,0,3,2] row_mask:0xf bank_mask:0xf
	s_nop 1
	v_add_f32_dpp v88, v88, v88 quad_perm:[2,3,0,1] row_mask:0xf bank_mask:0xf
	v_add_f32_dpp v89, v89, v89 quad_perm:[2,3,0,1] row_mask:0xf bank_mask:0xf
	s_nop 1
	v_add_f32_dpp v88, v88, v88 row_half_mirror row_mask:0xf bank_mask:0xf
	v_add_f32_dpp v89, v89, v89 row_half_mirror row_mask:0xf bank_mask:0xf
	s_nop 1
	v_add_f32_dpp v88, v88, v88 row_mirror row_mask:0xf bank_mask:0xf
	v_add_f32_dpp v89, v89, v89 row_mirror row_mask:0xf bank_mask:0xf
	s_nop 1
	v_readlane_b32 s98, v88, 0
	v_readlane_b32 s99, v88, 16
	v_readlane_b32 s100, v88, 32
	v_readlane_b32 s101, v88, 48
	s_nop 1
	v_mov_b32_e32 v228, s98
	v_add_f32_e32 v228, s99, v228
	v_mov_b32_e32 v229, s100
	v_add_f32_e32 v229, s101, v229
	v_add_f32_e32 v88, v228, v229
	v_readlane_b32 s98, v89, 0
	v_readlane_b32 s99, v89, 16
	v_readlane_b32 s100, v89, 32
	v_readlane_b32 s101, v89, 48
	s_nop 1
	v_mov_b32_e32 v228, s98
	v_add_f32_e32 v228, s99, v228
	v_mov_b32_e32 v229, s100
	v_add_f32_e32 v229, s101, v229
	v_add_f32_e32 v89, v228, v229
	s_nop 0
	v_pk_fma_f32 v[88:89], v[88:89], s[0:1], v[80:81] op_sel_hi:[1,1,0]
	s_nop 0
	v_mul_f32_e32 v90, 0x4b800000, v89
	v_cmp_gt_f32_e64 s[6:7], s72, v89
	v_cmp_gt_f32_e32 vcc, s72, v88
	s_nop 0
	v_cndmask_b32_e64 v89, v89, v90, s[6:7]
	v_rsq_f32_e32 v89, v89
	s_nop 0
	v_mul_f32_e32 v90, 0x45800000, v89
	v_cndmask_b32_e64 v90, v89, v90, s[6:7]
	v_pk_mul_f32 v[92:93], v[90:91], v[92:93] op_sel_hi:[0,1]
	v_pk_mul_f32 v[84:85], v[90:91], v[86:87] op_sel_hi:[0,1]
	v_pk_mul_f32 v[84:85], v[2:3], v[84:85]
	v_pk_mul_f32 v[86:87], v[0:1], v[92:93]
	s_nop 0
	v_cvt_pk_bf16_f32 v86, v86, v87
	v_cvt_pk_bf16_f32 v87, v84, v85
	global_store_dwordx2 v[76:77], v[86:87], off
	v_mul_f32_e32 v76, 0x4b800000, v88
	v_cndmask_b32_e32 v76, v88, v76, vcc
	v_rsq_f32_e32 v76, v76
	s_nop 0
	v_mul_f32_e32 v77, 0x45800000, v76
	v_cndmask_b32_e32 v76, v76, v77, vcc
	v_pk_mul_f32 v[76:77], v[76:77], v[82:83] op_sel_hi:[0,1]
	v_pk_mul_f32 v[76:77], v[16:17], v[76:77]
	s_nop 0
	v_cvt_pk_bf16_f32 v76, v76, v77
	global_store_dword v[74:75], v76, off
	v_pk_mul_f32 v[74:75], v[68:69], v[68:69]
	v_mov_b32_e32 v77, v78
	v_mov_b32_e32 v76, v74
	v_mov_b32_e32 v78, v75
	v_pk_add_f32 v[74:75], v[76:77], v[78:79]
	v_mov_b32_e32 v78, v72
	v_mov_b32_e32 v79, v70
	v_mov_b32_e32 v70, v73
	s_nop 1
	v_add_f32_dpp v74, v74, v74 quad_perm:[1,0,3,2] row_mask:0xf bank_mask:0xf
	v_add_f32_dpp v75, v75, v75 quad_perm:[1,0,3,2] row_mask:0xf bank_mask:0xf
	s_nop 1
	v_add_f32_dpp v74, v74, v74 quad_perm:[2,3,0,1] row_mask:0xf bank_mask:0xf
	v_add_f32_dpp v75, v75, v75 quad_perm:[2,3,0,1] row_mask:0xf bank_mask:0xf
	s_nop 1
	v_add_f32_dpp v74, v74, v74 row_half_mirror row_mask:0xf bank_mask:0xf
	v_add_f32_dpp v75, v75, v75 row_half_mirror row_mask:0xf bank_mask:0xf
	s_nop 1
	v_add_f32_dpp v74, v74, v74 row_mirror row_mask:0xf bank_mask:0xf
	v_add_f32_dpp v75, v75, v75 row_mirror row_mask:0xf bank_mask:0xf
	s_nop 1
	v_readlane_b32 s98, v74, 0
; __device__ __forceinline__ unsigned pk2(float lo, float hi) { f32x2 v = {lo, hi}; bf16x2_t b = __builtin_convertvector(v, bf16x2_t); return __builtin_bit_cast(unsigned, b); }
; __device__ __forceinline__ f32x4 unpack4(u32x2 w) { return (f32x4){bf_lo(w.x), bf_hi(w.x), bf_lo(w.y), bf_hi(w.y)}; }
; __device__ __forceinline__ u32x2 pack4(f32x4 v) { u32x2 w; w.x = pk2(v[0], v[1]); w.y = pk2(v[2], v[3]); return w; }
; __global__ void __launch_bounds__(NTHREADS) mega(Args a) {
;     ...
;             for (int q = 0; q < 4; ++q) {
;                 const float rq_ = rsqrtf(ssq[q] * (1.f / 256.f) + EPS), rk_ = rsqrtf(ssk[q] * (1.f / 128.f) + EPS);
;                 ((u32x2*)(pr + (size_t)q * PRM + 768))[lane] = pack4(cqv[q] * rq_ * gq);
;                 ((unsigned*)(pr + (size_t)q * PRM + 1024))[lane] = pk2(kv0[q] * rk_ * gk[0], kv1[q] * rk_ * gk[1]);
;             }
;             KR[(size_t)(row0 + rq) * 32 + ri] = (bf16_t)(pk2(t1 * cs_ - t2 * sn, 0.f) & 0xffffu);
;             KR[(size_t)(row0 + rq) * 32 + 16 + ri] = (bf16_t)(pk2(t2 * cs_ + t1 * sn, 0.f) & 0xffffu);
;             f32x4 prod[6];
; #pragma unroll
;             for (int k = 0; k < 6; ++k) prod[k] = unpack4(bcw[k]) * unpack4(bhw[k]);
; #pragma unroll
;             for (int q = 0; q < 4; ++q) { const f32x4 ob = unpack4(bbw[q]) * (prod[q] * w0 + prod[q + 1] * w1 + prod[q + 2] * w2);
;                 ((u32x2*)(MIX + (size_t)(row0 + q) * 1024 + 256))[lane] = pack4(ob); }
	v_readlane_b32 s99, v74, 16
	v_readlane_b32 s100, v74, 32
	v_readlane_b32 s101, v74, 48
	s_nop 1
	v_mov_b32_e32 v228, s98
	v_add_f32_e32 v228, s99, v228
	v_mov_b32_e32 v229, s100
	v_add_f32_e32 v229, s101, v229
	v_add_f32_e32 v74, v228, v229
	v_readlane_b32 s98, v75, 0
	v_readlane_b32 s99, v75, 16
	v_readlane_b32 s100, v75, 32
	v_readlane_b32 s101, v75, 48
	s_nop 1
	v_mov_b32_e32 v228, s98
	v_add_f32_e32 v228, s99, v228
	v_mov_b32_e32 v229, s100
	v_add_f32_e32 v229, s101, v229
	v_add_f32_e32 v75, v228, v229
	s_nop 0
	v_pk_fma_f32 v[74:75], v[74:75], s[0:1], v[80:81] op_sel_hi:[1,1,0]
	s_nop 0
	v_mul_f32_e32 v76, 0x4b800000, v75
	v_cmp_gt_f32_e64 s[6:7], s72, v75
	v_cmp_gt_f32_e32 vcc, s72, v74
	s_nop 0
	v_cndmask_b32_e64 v75, v75, v76, s[6:7]
	v_rsq_f32_e32 v75, v75
	s_nop 0
	v_mul_f32_e32 v76, 0x45800000, v75
	v_cndmask_b32_e64 v76, v75, v76, s[6:7]
	v_pk_mul_f32 v[78:79], v[76:77], v[78:79] op_sel_hi:[0,1]
	v_pk_mul_f32 v[70:71], v[76:77], v[70:71] op_sel_hi:[0,1]
	v_pk_mul_f32 v[70:71], v[2:3], v[70:71]
	v_pk_mul_f32 v[72:73], v[0:1], v[78:79]
	s_nop 0
	v_cvt_pk_bf16_f32 v72, v72, v73
	v_cvt_pk_bf16_f32 v73, v70, v71
	global_store_dwordx2 v[62:63], v[72:73], off
	v_mul_f32_e32 v62, 0x4b800000, v74
	v_cndmask_b32_e32 v62, v74, v62, vcc
	v_rsq_f32_e32 v62, v62
	s_nop 0
	v_mul_f32_e32 v63, 0x45800000, v62
	v_cndmask_b32_e32 v62, v62, v63, vcc
	v_pk_mul_f32 v[62:63], v[62:63], v[68:69] op_sel_hi:[0,1]
	v_pk_mul_f32 v[62:63], v[16:17], v[62:63]
	s_nop 0
	v_cvt_pk_bf16_f32 v62, v62, v63
	global_store_dword v[60:61], v62, off
	s_waitcnt vmcnt(8)
	v_mul_f32_e32 v60, v122, v120
	v_fma_f32 v60, v121, v112, -v60
	v_cvt_pk_bf16_f32 v62, v60, s0
	v_lshl_add_u64 v[60:61], v[66:67], 1, s[12:13]
	global_store_short v[60:61], v62, off
	v_mul_f32_e32 v60, v121, v120
	v_fmac_f32_e32 v60, v122, v112
	v_cvt_pk_bf16_f32 v62, v60, s0
	v_lshl_add_u64 v[60:61], v[64:65], 1, s[12:13]
	global_store_short v[60:61], v62, off
	v_lshlrev_b32_e32 v60, 16, v54
	v_and_b32_e32 v61, 0xffff0000, v54
	v_lshlrev_b32_e32 v54, 16, v55
	v_and_b32_e32 v55, 0xffff0000, v55
	v_lshlrev_b32_e32 v62, 16, v52
	v_and_b32_e32 v63, 0xffff0000, v52
	v_lshlrev_b32_e32 v52, 16, v53
	v_and_b32_e32 v53, 0xffff0000, v53
	v_pk_mul_f32 v[60:61], v[60:61], v[62:63]
	v_pk_mul_f32 v[52:53], v[54:55], v[52:53]
	v_lshlrev_b32_e32 v54, 16, v58
	v_and_b32_e32 v55, 0xffff0000, v58
	v_lshlrev_b32_e32 v58, 16, v59
	v_and_b32_e32 v59, 0xffff0000, v59
	v_lshlrev_b32_e32 v62, 16, v56
	v_and_b32_e32 v63, 0xffff0000, v56
	v_lshlrev_b32_e32 v56, 16, v57
	v_and_b32_e32 v57, 0xffff0000, v57
	v_pk_mul_f32 v[56:57], v[58:59], v[56:57]
	v_pk_mul_f32 v[54:55], v[54:55], v[62:63]
	v_lshlrev_b32_e32 v58, 16, v50
	v_and_b32_e32 v59, 0xffff0000, v50
	v_lshlrev_b32_e32 v50, 16, v51
	v_and_b32_e32 v51, 0xffff0000, v51
	v_lshlrev_b32_e32 v62, 16, v46
	v_and_b32_e32 v63, 0xffff0000, v46
	v_lshlrev_b32_e32 v46, 16, v47
	v_and_b32_e32 v47, 0xffff0000, v47
	v_pk_mul_f32 v[46:47], v[50:51], v[46:47]
	v_pk_mul_f32 v[50:51], v[58:59], v[62:63]
	v_lshlrev_b32_e32 v58, 16, v40
	v_and_b32_e32 v59, 0xffff0000, v40
	v_lshlrev_b32_e32 v40, 16, v41
	v_and_b32_e32 v41, 0xffff0000, v41
	v_lshlrev_b32_e32 v62, 16, v36
	v_and_b32_e32 v63, 0xffff0000, v36
	v_lshlrev_b32_e32 v36, 16, v37
	v_and_b32_e32 v37, 0xffff0000, v37
	v_pk_mul_f32 v[36:37], v[40:41], v[36:37]
	v_pk_mul_f32 v[40:41], v[58:59], v[62:63]
	v_lshlrev_b32_e32 v58, 16, v48
	v_and_b32_e32 v59, 0xffff0000, v48
	v_lshlrev_b32_e32 v48, 16, v49
	v_and_b32_e32 v49, 0xffff0000, v49
	v_lshlrev_b32_e32 v62, 16, v44
	v_and_b32_e32 v63, 0xffff0000, v44
	v_lshlrev_b32_e32 v44, 16, v45
	v_and_b32_e32 v45, 0xffff0000, v45
	v_pk_mul_f32 v[44:45], v[48:49], v[44:45]
	v_pk_mul_f32 v[48:49], v[58:59], v[62:63]
	v_lshlrev_b32_e32 v58, 16, v42
	v_and_b32_e32 v59, 0xffff0000, v42
	v_lshlrev_b32_e32 v42, 16, v43
	v_and_b32_e32 v43, 0xffff0000, v43
	v_lshlrev_b32_e32 v62, 16, v38
	v_and_b32_e32 v63, 0xffff0000, v38
	v_lshlrev_b32_e32 v38, 16, v39
	v_and_b32_e32 v39, 0xffff0000, v39
	v_pk_mul_f32 v[38:39], v[42:43], v[38:39]
	v_pk_mul_f32 v[42:43], v[58:59], v[62:63]
	v_pk_mul_f32 v[62:63], v[8:9], v[54:55]
	v_pk_mul_f32 v[64:65], v[10:11], v[56:57]
	v_pk_fma_f32 v[60:61], v[4:5], v[60:61], v[62:63]
	v_pk_fma_f32 v[52:53], v[6:7], v[52:53], v[64:65]
	v_lshlrev_b32_e32 v58, 16, v28
	v_and_b32_e32 v59, 0xffff0000, v28
	v_lshlrev_b32_e32 v28, 16, v29
	v_and_b32_e32 v29, 0xffff0000, v29
	v_pk_fma_f32 v[60:61], v[12:13], v[50:51], v[60:61]
	v_pk_fma_f32 v[52:53], v[14:15], v[46:47], v[52:53]
	v_pk_mul_f32 v[62:63], v[10:11], v[46:47]
	v_pk_mul_f32 v[28:29], v[52:53], v[28:29]
	v_pk_mul_f32 v[52:53], v[60:61], v[58:59]
	v_pk_mul_f32 v[60:61], v[8:9], v[50:51]
	v_cvt_pk_bf16_f32 v52, v52, v53
	v_cvt_pk_bf16_f32 v53, v28, v29
	v_lshl_add_u64 v[28:29], s[8:9], 0, v[20:21]
	v_add_co_u32_e32 v58, vcc, s23, v28
	v_pk_fma_f32 v[56:57], v[6:7], v[56:57], v[62:63]
	s_nop 0
	v_addc_co_u32_e32 v59, vcc, 0, v29, vcc
	v_pk_fma_f32 v[54:55], v[4:5], v[54:55], v[60:61]
	global_store_dwordx2 v[58:59], v[52:53], off offset:512
	v_lshlrev_b32_e32 v52, 16, v30
	v_and_b32_e32 v53, 0xffff0000, v30
	v_lshlrev_b32_e32 v30, 16, v31
	v_and_b32_e32 v31, 0xffff0000, v31
	v_pk_fma_f32 v[54:55], v[12:13], v[40:41], v[54:55]
	v_pk_fma_f32 v[56:57], v[14:15], v[36:37], v[56:57]
	v_pk_mul_f32 v[52:53], v[54:55], v[52:53]
	v_pk_mul_f32 v[30:31], v[56:57], v[30:31]
	v_cvt_pk_bf16_f32 v52, v52, v53
	v_cvt_pk_bf16_f32 v53, v30, v31
	global_store_dwordx2 v[58:59], v[52:53], off offset:2560
	v_pk_mul_f32 v[52:53], v[8:9], v[40:41]
	v_pk_mul_f32 v[54:55], v[10:11], v[36:37]
	v_pk_fma_f32 v[50:51], v[4:5], v[50:51], v[52:53]
	v_pk_fma_f32 v[46:47], v[6:7], v[46:47], v[54:55]
	v_lshlrev_b32_e32 v30, 16, v32
	v_and_b32_e32 v31, 0xffff0000, v32
	v_lshlrev_b32_e32 v32, 16, v33
	v_and_b32_e32 v33, 0xffff0000, v33
	v_pk_fma_f32 v[50:51], v[12:13], v[48:49], v[50:51]
	v_pk_fma_f32 v[46:47], v[14:15], v[44:45], v[46:47]
	v_pk_mul_f32 v[30:31], v[50:51], v[30:31]
	v_pk_mul_f32 v[32:33], v[46:47], v[32:33]
	v_add_co_u32_e32 v28, vcc, s70, v28
	v_cvt_pk_bf16_f32 v30, v30, v31
	v_cvt_pk_bf16_f32 v31, v32, v33
	v_addc_co_u32_e32 v29, vcc, 0, v29, vcc
	global_store_dwordx2 v[28:29], v[30:31], off offset:512
	v_lshlrev_b32_e32 v30, 16, v34
	v_and_b32_e32 v31, 0xffff0000, v34
	v_lshlrev_b32_e32 v32, 16, v35
	v_and_b32_e32 v33, 0xffff0000, v35
	v_pk_mul_f32 v[34:35], v[8:9], v[48:49]
	v_pk_mul_f32 v[44:45], v[10:11], v[44:45]
	v_pk_fma_f32 v[34:35], v[4:5], v[40:41], v[34:35]
	v_pk_fma_f32 v[36:37], v[6:7], v[36:37], v[44:45]
	v_pk_fma_f32 v[34:35], v[12:13], v[42:43], v[34:35]
	v_pk_fma_f32 v[36:37], v[14:15], v[38:39], v[36:37]
	v_pk_mul_f32 v[30:31], v[34:35], v[30:31]
	v_pk_mul_f32 v[32:33], v[36:37], v[32:33]
	v_cvt_pk_bf16_f32 v30, v30, v31
	v_cvt_pk_bf16_f32 v31, v32, v33
	v_lshl_add_u64 v[20:21], v[20:21], 0, s[52:53]
	global_store_dwordx2 v[28:29], v[30:31], off offset:2560
	s_cbranch_scc1 .LBB0_467

; __device__ __forceinline__ f32x4 unpack4(u32x2 w) { return (f32x4){bf_lo(w.x), bf_hi(w.x), bf_lo(w.y), bf_hi(w.y)}; }
; template <int NR, bool XIN16 = false, bool XOUT16 = false> ...
;     ...
;         if (XIN16) { const u32x2* xr = (const u32x2*)((const bf16_t*)xin + (size_t)(row + q * rstride) * DM) + lane;
; #pragma unroll
;             for (int j = 0; j < 4; ++j) xv[q][j] = unpack4(xr[64 * j]); }
;         else { const f32x4* xr = (const f32x4*)(xin + (size_t)(row + q * rstride) * DM) + lane;
; #pragma unroll
;             for (int j = 0; j < 4; ++j) xv[q][j] = xr[64 * j]; } }
;     if (y) {
; #pragma unroll
;         for (int q = 0; q < NR; ++q) { const u32x2* yr = (const u32x2*)(y + (size_t)(row + q * rstride) * DM) + lane;
; #pragma unroll
;             for (int j = 0; j < 4; ++j) yv[q][j] = unpack4(yr[64 * j]); }
;         f32x4 g[4], gy[4];
; #pragma unroll
;         for (int j = 0; j < 4; ++j) { g[j] = ((const f32x4*)gate)[lane + 64 * j]; gy[j] = ((const f32x4*)gainY)[lane + 64 * j]; }
.LBB0_1045:
	s_ashr_i32 s0, s12, 12
	s_mul_hi_i32 s1, s0, 0x6000
	s_mulk_i32 s0, 0x6000
	s_add_u32 s0, s23, s0
	s_addc_u32 s1, s24, s1
	s_add_u32 s20, s0, 0x2000
	s_addc_u32 s21, s1, 0
	s_add_u32 s6, s0, 0x4000
	s_addc_u32 s7, s1, 0
	s_add_u32 s18, s0, 0x3000
	s_addc_u32 s19, s1, 0
	s_and_b64 vcc, exec, s[14:15]
	v_lshl_add_u64 v[124:125], s[10:11], 0, v[112:113]
	v_lshlrev_b32_e32 v109, 4, v96
	v_lshlrev_b32_e32 v105, 4, v100
	v_lshlrev_b32_e32 v101, 4, v104
	v_lshlrev_b32_e32 v97, 4, v108
	s_cbranch_vccz .LBB0_1047
	v_lshl_add_u64 v[0:1], s[16:17], 0, v[112:113]
	v_add_co_u32_e32 v2, vcc, 0x4000000, v0
	s_mov_b32 s0, 0x4001000
	s_nop 0
	v_addc_co_u32_e32 v3, vcc, 0, v1, vcc
	v_add_co_u32_e64 v4, s[8:9], s0, v0
	v_add_co_u32_e32 v50, vcc, s28, v124
	s_nop 0
	v_addc_co_u32_e64 v5, s[8:9], 0, v1, s[8:9]
	v_addc_co_u32_e32 v51, vcc, 0, v125, vcc
	global_load_dwordx2 v[6:7], v[4:5], off
	global_load_dwordx2 v[0:1], v[2:3], off
	global_load_dwordx2 v[8:9], v[2:3], off offset:512
	global_load_dwordx2 v[10:11], v[2:3], off offset:1024
	global_load_dwordx2 v[12:13], v[2:3], off offset:1536
	global_load_dwordx2 v[14:15], v[2:3], off offset:2048
	global_load_dwordx2 v[16:17], v[2:3], off offset:2560
	global_load_dwordx2 v[18:19], v[2:3], off offset:3072
	s_nop 0
	global_load_dwordx2 v[2:3], v[2:3], off offset:3584
	s_nop 0
	global_load_dwordx2 v[20:21], v[4:5], off offset:512
	global_load_dwordx2 v[22:23], v[4:5], off offset:1024
	global_load_dwordx2 v[24:25], v[4:5], off offset:1536
	global_load_dwordx2 v[26:27], v[4:5], off offset:2048
	global_load_dwordx2 v[28:29], v[4:5], off offset:2560
	global_load_dwordx2 v[30:31], v[4:5], off offset:3072
	s_nop 0
	global_load_dwordx2 v[4:5], v[4:5], off offset:3584
	s_nop 0
	global_load_dwordx2 v[162:163], v[50:51], off offset:512
	global_load_dwordx2 v[164:165], v[50:51], off offset:1024
	global_load_dwordx2 v[44:45], v[50:51], off offset:1536
	v_add_co_u32_e32 v48, vcc, s29, v124
	s_mov_b32 s0, 0x7401000
	s_nop 0
	v_addc_co_u32_e32 v49, vcc, 0, v125, vcc
	global_load_dwordx2 v[166:167], v[48:49], off offset:-4096
	global_load_dwordx2 v[46:47], v[50:51], off offset:3584
	global_load_dwordx2 v[168:169], v[50:51], off offset:2560
	global_load_dwordx2 v[160:161], v[50:51], off offset:3072
	global_load_dwordx2 v[156:157], v[48:49], off
	global_load_dwordx2 v[56:57], v[48:49], off offset:1536
	global_load_dwordx2 v[152:153], v[48:49], off offset:512
	global_load_dwordx2 v[150:151], v[48:49], off offset:1024
	global_load_dwordx2 v[148:149], v[48:49], off offset:2048
	global_load_dwordx2 v[170:171], v[48:49], off offset:3584
	global_load_dwordx2 v[146:147], v[48:49], off offset:2560
	global_load_dwordx2 v[52:53], v[48:49], off offset:3072
	global_load_dwordx2 v[172:173], v[50:51], off offset:2048
	s_waitcnt vmcnt(30)
	v_lshlrev_b32_e32 v154, 16, v0
	v_and_b32_e32 v155, 0xffff0000, v0
	v_lshlrev_b32_e32 v158, 16, v1
	v_and_b32_e32 v159, 0xffff0000, v1
	s_waitcnt vmcnt(29)
	v_lshlrev_b32_e32 v142, 16, v8
	v_and_b32_e32 v143, 0xffff0000, v8
	v_lshlrev_b32_e32 v144, 16, v9
	v_and_b32_e32 v145, 0xffff0000, v9
	s_waitcnt vmcnt(28)
	v_lshlrev_b32_e32 v70, 16, v10
	s_waitcnt vmcnt(12)
	v_and_b32_e32 v209, 0xffff0000, v167
	v_and_b32_e32 v207, 0xffff0000, v166
	v_lshlrev_b32_e32 v208, 16, v167
	v_lshlrev_b32_e32 v206, 16, v166
	v_and_b32_e32 v203, 0xffff0000, v163
	v_lshlrev_b32_e32 v181, 16, v44
	v_and_b32_e32 v179, 0xffff0000, v44
	v_lshlrev_b32_e32 v182, 16, v45
	v_and_b32_e32 v183, 0xffff0000, v45
	s_waitcnt vmcnt(3)
	v_and_b32_e32 v45, 0xffff0000, v170
	v_mul_f32_e32 v44, v209, v209
	v_pk_fma_f32 v[166:167], v[208:209], v[208:209], v[44:45] op_sel_hi:[1,1,0]
	v_and_b32_e32 v202, 0xffff0000, v162
	v_mul_f32_e32 v44, v207, v207
	v_lshlrev_b32_e32 v201, 16, v163
	v_lshlrev_b32_e32 v200, 16, v162
	v_pk_mul_f32 v[162:163], v[202:203], v[202:203]
	v_lshlrev_b32_e32 v192, 16, v164
	v_and_b32_e32 v193, 0xffff0000, v164
	v_lshlrev_b32_e32 v198, 16, v165
	v_and_b32_e32 v199, 0xffff0000, v165
	v_pk_fma_f32 v[164:165], v[206:207], v[206:207], v[44:45] op_sel_hi:[1,1,0]
	v_lshlrev_b32_e32 v136, 16, v47
	v_and_b32_e32 v137, 0xffff0000, v47
	v_lshlrev_b32_e32 v77, 16, v56
	v_and_b32_e32 v89, 0xffff0000, v56
	v_lshlrev_b32_e32 v92, 16, v57
	v_and_b32_e32 v93, 0xffff0000, v57
	v_lshlrev_b32_e32 v47, 16, v170
	v_lshlrev_b32_e32 v56, 16, v171
	v_and_b32_e32 v57, 0xffff0000, v171
	v_pk_fma_f32 v[162:163], v[200:201], v[200:201], v[162:163]
	v_mov_b32_e32 v180, v164
	v_mov_b32_e32 v170, v166
	v_mov_b32_e32 v171, v181
	v_lshlrev_b32_e32 v135, 16, v46
	v_and_b32_e32 v133, 0xffff0000, v46
	v_mul_f32_e32 v46, v179, v179
	v_pk_add_f32 v[164:165], v[164:165], v[166:167]
	v_pk_mul_f32 v[166:167], v[180:181], v[170:171]
	v_pk_add_f32 v[162:163], v[162:163], v[162:163] op_sel:[0,1] op_sel_hi:[1,0]
	v_mov_b32_e32 v165, v167
	v_mov_b32_e32 v163, v46
	v_mul_f32_e32 v44, v193, v193
	v_pk_add_f32 v[162:163], v[164:165], v[162:163]
	v_pk_fma_f32 v[164:165], v[192:193], v[192:193], v[44:45] op_sel_hi:[1,1,0]
	v_mul_f32_e32 v44, v199, v199
	v_mul_f32_e32 v76, v182, v182
	v_mul_f32_e32 v88, v183, v183
	v_pk_fma_f32 v[166:167], v[198:199], v[198:199], v[44:45] op_sel_hi:[1,1,0]
	v_mov_b32_e32 v165, v76
	v_mov_b32_e32 v167, v88
	s_waitcnt vmcnt(0)
; __device__ __forceinline__ f32x4 unpack4(u32x2 w) { return (f32x4){bf_lo(w.x), bf_hi(w.x), bf_lo(w.y), bf_hi(w.y)}; }
; template <int NR, bool XIN16 = false, bool XOUT16 = false> ...
;     ...
;         for (int q = 0; q < NR; ++q) { const u32x2* yr = (const u32x2*)(y + (size_t)(row + q * rstride) * DM) + lane;
; #pragma unroll
;             for (int j = 0; j < 4; ++j) yv[q][j] = unpack4(yr[64 * j]); }
;         f32x4 g[4], gy[4];
; #pragma unroll
;         for (int j = 0; j < 4; ++j) { g[j] = ((const f32x4*)gate)[lane + 64 * j]; gy[j] = ((const f32x4*)gainY)[lane + 64 * j]; }
;         float ss[NR];
; #pragma unroll
;         for (int q = 0; q < NR; ++q) { ss[q] = 0.f;
; #pragma unroll
;             for (int j = 0; j < 4; ++j) ss[q] += (yv[q][j][0] * yv[q][j][0] + yv[q][j][1] * yv[q][j][1]) + (yv[q][j][2] * yv[q][j][2] + yv[q][j][3] * yv[q][j][3]); }
	v_and_b32_e32 v191, 0xffff0000, v173
	v_pk_add_f32 v[164:165], v[164:165], v[166:167]
	v_and_b32_e32 v189, 0xffff0000, v172
	v_lshlrev_b32_e32 v190, 16, v173
	v_mul_f32_e32 v44, v191, v191
	v_pk_add_f32 v[210:211], v[162:163], v[164:165]
	v_lshlrev_b32_e32 v188, 16, v172
	v_pk_fma_f32 v[162:163], v[190:191], v[190:191], v[44:45] op_sel_hi:[1,1,0]
	v_mul_f32_e32 v44, v189, v189
	v_lshlrev_b32_e32 v36, 16, v6
	v_and_b32_e32 v37, 0xffff0000, v6
	v_lshlrev_b32_e32 v40, 16, v7
	v_and_b32_e32 v71, 0xffff0000, v10
	v_lshlrev_b32_e32 v140, 16, v11
	v_and_b32_e32 v141, 0xffff0000, v11
	v_lshlrev_b32_e32 v84, 16, v12
	v_and_b32_e32 v85, 0xffff0000, v12
	v_lshlrev_b32_e32 v138, 16, v13
	v_and_b32_e32 v139, 0xffff0000, v13
	v_lshlrev_b32_e32 v128, 16, v14
	v_and_b32_e32 v129, 0xffff0000, v14
	v_lshlrev_b32_e32 v130, 16, v15
	v_and_b32_e32 v131, 0xffff0000, v15
	v_lshlrev_b32_e32 v94, 16, v16
	v_and_b32_e32 v95, 0xffff0000, v16
	v_lshlrev_b32_e32 v126, 16, v17
	v_and_b32_e32 v127, 0xffff0000, v17
	v_lshlrev_b32_e32 v80, 16, v18
	v_and_b32_e32 v81, 0xffff0000, v18
	v_lshlrev_b32_e32 v90, 16, v19
	v_and_b32_e32 v91, 0xffff0000, v19
	v_lshlrev_b32_e32 v68, 16, v2
	v_and_b32_e32 v69, 0xffff0000, v2
	v_lshlrev_b32_e32 v72, 16, v3
	v_and_b32_e32 v73, 0xffff0000, v3
	v_and_b32_e32 v41, 0xffff0000, v7
	v_lshlrev_b32_e32 v82, 16, v20
	v_and_b32_e32 v83, 0xffff0000, v20
	v_lshlrev_b32_e32 v86, 16, v21
	v_and_b32_e32 v87, 0xffff0000, v21
	v_lshlrev_b32_e32 v74, 16, v22
	v_and_b32_e32 v75, 0xffff0000, v22
	v_lshlrev_b32_e32 v78, 16, v23
	v_and_b32_e32 v79, 0xffff0000, v23
	v_lshlrev_b32_e32 v64, 16, v24
	v_and_b32_e32 v65, 0xffff0000, v24
	v_lshlrev_b32_e32 v66, 16, v25
	v_and_b32_e32 v67, 0xffff0000, v25
	v_lshlrev_b32_e32 v60, 16, v26
	v_and_b32_e32 v61, 0xffff0000, v26
	v_lshlrev_b32_e32 v62, 16, v27
	v_and_b32_e32 v63, 0xffff0000, v27
	v_lshlrev_b32_e32 v54, 16, v28
	v_and_b32_e32 v55, 0xffff0000, v28
	v_lshlrev_b32_e32 v58, 16, v29
	v_and_b32_e32 v59, 0xffff0000, v29
	v_lshlrev_b32_e32 v38, 16, v30
	v_and_b32_e32 v39, 0xffff0000, v30
	v_lshlrev_b32_e32 v42, 16, v31
	v_and_b32_e32 v43, 0xffff0000, v31
	v_lshlrev_b32_e32 v32, 16, v4
	v_and_b32_e32 v33, 0xffff0000, v4
	v_lshlrev_b32_e32 v34, 16, v5
	v_and_b32_e32 v35, 0xffff0000, v5
	global_load_dwordx4 v[24:27], v109, s[20:21]
	global_load_dwordx4 v[16:19], v105, s[20:21]
	global_load_dwordx4 v[28:31], v[98:99], off
	global_load_dwordx4 v[20:23], v[102:103], off
	global_load_dwordx4 v[8:11], v101, s[20:21]
	global_load_dwordx4 v[0:3], v97, s[20:21]
	global_load_dwordx4 v[12:15], v[106:107], off
	global_load_dwordx4 v[4:7], v[110:111], off
	v_and_b32_e32 v187, 0xffff0000, v169
	v_and_b32_e32 v186, 0xffff0000, v168
	v_lshlrev_b32_e32 v174, 16, v160
	v_and_b32_e32 v175, 0xffff0000, v160
	v_lshlrev_b32_e32 v176, 16, v161
	v_and_b32_e32 v177, 0xffff0000, v161
	v_pk_fma_f32 v[160:161], v[188:189], v[188:189], v[44:45] op_sel_hi:[1,1,0]
	v_lshlrev_b32_e32 v185, 16, v169
	v_lshlrev_b32_e32 v184, 16, v168
	v_pk_mul_f32 v[164:165], v[186:187], v[186:187]
	v_mov_b32_e32 v134, v160
	v_mov_b32_e32 v166, v162
	v_mov_b32_e32 v167, v135
	v_pk_fma_f32 v[164:165], v[184:185], v[184:185], v[164:165]
	v_pk_add_f32 v[160:161], v[160:161], v[162:163]
	v_pk_mul_f32 v[162:163], v[134:135], v[166:167]
	v_mul_f32_e32 v46, v133, v133
	v_mov_b32_e32 v161, v163
	v_pk_add_f32 v[162:163], v[164:165], v[164:165] op_sel:[0,1] op_sel_hi:[1,0]
	v_mul_f32_e32 v44, v175, v175
	v_mov_b32_e32 v163, v46
	v_pk_add_f32 v[160:161], v[160:161], v[162:163]
	v_pk_fma_f32 v[162:163], v[174:175], v[174:175], v[44:45] op_sel_hi:[1,1,0]
	v_mul_f32_e32 v44, v177, v177
	v_mul_f32_e32 v76, v136, v136
	v_mul_f32_e32 v88, v137, v137
	v_pk_fma_f32 v[164:165], v[176:177], v[176:177], v[44:45] op_sel_hi:[1,1,0]
	v_and_b32_e32 v173, 0xffff0000, v157
	v_mov_b32_e32 v163, v76
	v_mov_b32_e32 v165, v88
	v_and_b32_e32 v171, 0xffff0000, v156
	v_lshlrev_b32_e32 v172, 16, v157
	v_mul_f32_e32 v44, v173, v173
	v_pk_add_f32 v[162:163], v[162:163], v[164:165]
	v_lshlrev_b32_e32 v170, 16, v156
	v_pk_fma_f32 v[156:157], v[172:173], v[172:173], v[44:45] op_sel_hi:[1,1,0]
	v_and_b32_e32 v169, 0xffff0000, v153
	v_and_b32_e32 v168, 0xffff0000, v152
	v_mul_f32_e32 v44, v171, v171
	v_pk_add_f32 v[212:213], v[160:161], v[162:163]
	v_lshlrev_b32_e32 v165, 16, v153
	v_lshlrev_b32_e32 v164, 16, v152
	v_pk_mul_f32 v[152:153], v[168:169], v[168:169]
	v_lshlrev_b32_e32 v162, 16, v150
	v_and_b32_e32 v163, 0xffff0000, v150
	v_lshlrev_b32_e32 v166, 16, v151
	v_and_b32_e32 v167, 0xffff0000, v151
	v_pk_fma_f32 v[150:151], v[170:171], v[170:171], v[44:45] op_sel_hi:[1,1,0]
	v_pk_fma_f32 v[152:153], v[164:165], v[164:165], v[152:153]
	v_mov_b32_e32 v76, v150
	v_mov_b32_e32 v160, v156
	v_mov_b32_e32 v161, v77
	v_mul_f32_e32 v46, v89, v89
	v_pk_add_f32 v[150:151], v[150:151], v[156:157]
	v_pk_mul_f32 v[156:157], v[76:77], v[160:161]
	v_pk_add_f32 v[152:153], v[152:153], v[152:153] op_sel:[0,1] op_sel_hi:[1,0]
	v_mov_b32_e32 v151, v157
	v_mov_b32_e32 v153, v46
	v_mul_f32_e32 v44, v163, v163
	v_pk_add_f32 v[150:151], v[150:151], v[152:153]
	v_pk_fma_f32 v[152:153], v[162:163], v[162:163], v[44:45] op_sel_hi:[1,1,0]
	v_mul_f32_e32 v44, v167, v167
	v_mul_f32_e32 v88, v92, v92
	v_mul_f32_e32 v132, v93, v93
	v_pk_fma_f32 v[156:157], v[166:167], v[166:167], v[44:45] op_sel_hi:[1,1,0]
	v_mov_b32_e32 v153, v88
	v_mov_b32_e32 v157, v132
	v_pk_add_f32 v[152:153], v[152:153], v[156:157]
	v_and_b32_e32 v161, 0xffff0000, v149
	v_pk_add_f32 v[204:205], v[150:151], v[152:153]
	v_and_b32_e32 v157, 0xffff0000, v148
	v_lshlrev_b32_e32 v160, 16, v149
	v_mul_f32_e32 v44, v161, v161
	v_and_b32_e32 v153, 0xffff0000, v147
; __device__ __forceinline__ f32x4 unpack4(u32x2 w) { return (f32x4){bf_lo(w.x), bf_hi(w.x), bf_lo(w.y), bf_hi(w.y)}; }
; __device__ __forceinline__ u32x2 pack4(f32x4 v) { u32x2 w; w.x = pk2(v[0], v[1]); w.y = pk2(v[2], v[3]); return w; }
; template <int NR, bool XIN16 = false, bool XOUT16 = false> ...
;     ...
;         for (int q = 0; q < NR; ++q) { ss[q] = 0.f;
; #pragma unroll
;             for (int j = 0; j < 4; ++j) ss[q] += (yv[q][j][0] * yv[q][j][0] + yv[q][j][1] * yv[q][j][1]) + (yv[q][j][2] * yv[q][j][2] + yv[q][j][3] * yv[q][j][3]); }
; #pragma unroll
;         for (int o = 1; o < 64; o <<= 1) {
; #pragma unroll
;             for (int q = 0; q < NR; ++q) ss[q] += __shfl_xor(ss[q], o); }
; #pragma unroll
;         for (int q = 0; q < NR; ++q) { const float rstd = rsqrtf(ss[q] * (1.f / DM) + EPS);
;             if (XOUT16) { u32x2* xo = (u32x2*)((bf16_t*)xout + (size_t)(row + q * rstride) * DM) + lane;
; #pragma unroll
;                 for (int j = 0; j < 4; ++j) { xv[q][j] = xv[q][j] + g[j] * (yv[q][j] * rstd * gy[j]); xo[64 * j] = pack4(xv[q][j]); xv[q][j] = unpack4(pack4(xv[q][j])); } }
	v_and_b32_e32 v152, 0xffff0000, v146
	v_lshlrev_b32_e32 v156, 16, v148
	v_pk_fma_f32 v[214:215], v[160:161], v[160:161], v[44:45] op_sel_hi:[1,1,0]
	v_lshlrev_b32_e32 v149, 16, v147
	v_lshlrev_b32_e32 v148, 16, v146
	v_pk_mul_f32 v[146:147], v[152:153], v[152:153]
	v_mul_f32_e32 v44, v157, v157
	v_pk_fma_f32 v[216:217], v[148:149], v[148:149], v[146:147]
	v_lshlrev_b32_e32 v146, 16, v52
	v_and_b32_e32 v147, 0xffff0000, v52
	v_lshlrev_b32_e32 v150, 16, v53
	v_and_b32_e32 v151, 0xffff0000, v53
	v_pk_fma_f32 v[52:53], v[156:157], v[156:157], v[44:45] op_sel_hi:[1,1,0]
	v_mov_b32_e32 v218, v214
	v_mov_b32_e32 v46, v52
	v_mov_b32_e32 v219, v47
	v_pk_add_f32 v[52:53], v[52:53], v[214:215]
	v_pk_mul_f32 v[214:215], v[46:47], v[218:219]
	v_mul_f32_e32 v76, v45, v45
	v_mov_b32_e32 v53, v215
	v_pk_add_f32 v[214:215], v[216:217], v[216:217] op_sel:[0,1] op_sel_hi:[1,0]
	v_and_b32_e32 v46, 64, v240
	v_mov_b32_e32 v215, v76
	v_pk_add_f32 v[216:217], v[52:53], v[214:215]
	v_add_u32_e32 v46, 64, v46
	v_xor_b32_e32 v52, 1, v240
	v_cmp_lt_i32_e32 vcc, v52, v46
	v_mov_b32_e32 v53, v210
	v_mov_b32_e32 v210, v213
	v_cndmask_b32_e32 v52, v240, v52, vcc
	v_lshlrev_b32_e32 v180, 2, v52
	v_mov_b32_e32 v52, v212
	v_pk_add_f32 v[52:53], v[52:53], v[210:211]
	v_xor_b32_e32 v76, 2, v240
	v_cmp_lt_i32_e32 vcc, v76, v46
	v_mul_f32_e32 v44, v147, v147
	v_pk_fma_f32 v[220:221], v[146:147], v[146:147], v[44:45] op_sel_hi:[1,1,0]
	v_cndmask_b32_e32 v76, v240, v76, vcc
	v_lshlrev_b32_e32 v210, 2, v76
	s_nop 1
	v_add_f32_dpp v52, v52, v52 quad_perm:[1,0,3,2] row_mask:0xf bank_mask:0xf
	v_add_f32_dpp v53, v53, v53 quad_perm:[1,0,3,2] row_mask:0xf bank_mask:0xf
	v_xor_b32_e32 v76, 4, v240
	v_cmp_lt_i32_e32 vcc, v76, v46
	v_mul_f32_e32 v44, v151, v151
	v_pk_fma_f32 v[222:223], v[150:151], v[150:151], v[44:45] op_sel_hi:[1,1,0]
	v_cndmask_b32_e32 v76, v240, v76, vcc
	v_lshlrev_b32_e32 v211, 2, v76
	s_nop 1
	v_add_f32_dpp v52, v52, v52 quad_perm:[2,3,0,1] row_mask:0xf bank_mask:0xf
	v_add_f32_dpp v53, v53, v53 quad_perm:[2,3,0,1] row_mask:0xf bank_mask:0xf
	v_xor_b32_e32 v76, 8, v240
	v_cmp_lt_i32_e32 vcc, v76, v46
	v_mov_b32_e32 v178, v181
	v_mul_f32_e32 v88, v56, v56
	v_cndmask_b32_e32 v76, v240, v76, vcc
	v_lshlrev_b32_e32 v212, 2, v76
	s_nop 1
	v_add_f32_dpp v52, v52, v52 row_half_mirror row_mask:0xf bank_mask:0xf
	v_add_f32_dpp v53, v53, v53 row_half_mirror row_mask:0xf bank_mask:0xf
	v_xor_b32_e32 v76, 16, v240
	v_cmp_lt_i32_e32 vcc, v76, v46
	v_mul_f32_e32 v132, v57, v57
	v_mov_b32_e32 v221, v88
	v_cndmask_b32_e32 v76, v240, v76, vcc
	v_lshlrev_b32_e32 v213, 2, v76
	s_nop 1
	v_add_f32_dpp v52, v52, v52 row_mirror row_mask:0xf bank_mask:0xf
	v_add_f32_dpp v53, v53, v53 row_mirror row_mask:0xf bank_mask:0xf
	v_xor_b32_e32 v76, 32, v240
	v_cmp_lt_i32_e32 vcc, v76, v46
	v_mov_b32_e32 v223, v132
	v_pk_add_f32 v[220:221], v[220:221], v[222:223]
	v_cndmask_b32_e32 v46, v240, v76, vcc
	v_lshlrev_b32_e32 v214, 2, v46
	s_nop 1
	v_readlane_b32 s98, v52, 0
	v_readlane_b32 s99, v52, 16
	v_readlane_b32 s100, v52, 32
	v_readlane_b32 s101, v52, 48
	s_nop 1
	v_mov_b32_e32 v228, s98
	v_add_f32_e32 v228, s99, v228
	v_mov_b32_e32 v229, s100
	v_add_f32_e32 v229, s101, v229
	v_add_f32_e32 v52, v228, v229
	v_readlane_b32 s98, v53, 0
	v_readlane_b32 s99, v53, 16
	v_readlane_b32 s100, v53, 32
	v_readlane_b32 s101, v53, 48
	s_nop 1
	v_mov_b32_e32 v228, s98
	v_add_f32_e32 v228, s99, v228
	v_mov_b32_e32 v229, s100
	v_add_f32_e32 v229, s101, v229
	v_add_f32_e32 v53, v228, v229
	v_pk_add_f32 v[216:217], v[216:217], v[220:221]
	v_mov_b32_e32 v132, v135
	v_mov_b32_e32 v88, v77
	v_mov_b32_e32 v218, v52
	v_mov_b32_e32 v219, v53
	v_mov_b64_e32 v[52:53], s[36:37]
	v_pk_fma_f32 v[218:219], v[218:219], s[82:83], v[52:53] op_sel_hi:[1,0,0]
	s_nop 0
	v_mul_f32_e32 v44, 0x4b800000, v219
	v_cmp_gt_f32_e32 vcc, s72, v219
	s_nop 1
	v_cndmask_b32_e32 v44, v219, v44, vcc
	v_rsq_f32_e32 v44, v44
	s_nop 0
	v_mul_f32_e32 v46, 0x45800000, v44
	v_cndmask_b32_e32 v44, v44, v46, vcc
	v_pk_mul_f32 v[208:209], v[44:45], v[208:209] op_sel_hi:[0,1]
	s_waitcnt vmcnt(5)
	v_pk_mul_f32 v[208:209], v[30:31], v[208:209]
	v_pk_mul_f32 v[206:207], v[44:45], v[206:207] op_sel_hi:[0,1]
	v_pk_fma_f32 v[158:159], v[26:27], v[208:209], v[158:159]
	v_mov_b32_e32 v208, v201
	v_mov_b32_e32 v209, v203
	v_mov_b32_e32 v201, v202
	v_pk_mul_f32 v[208:209], v[44:45], v[208:209] op_sel_hi:[0,1]
	v_pk_mul_f32 v[200:201], v[44:45], v[200:201] op_sel_hi:[0,1]
	v_pk_mul_f32 v[206:207], v[28:29], v[206:207]
	s_waitcnt vmcnt(4)
	v_pk_mul_f32 v[200:201], v[20:21], v[200:201]
	v_pk_mul_f32 v[202:203], v[22:23], v[208:209]
	v_pk_fma_f32 v[154:155], v[24:25], v[206:207], v[154:155]
	v_add_co_u32_e32 v206, vcc, s84, v124
	v_pk_fma_f32 v[144:145], v[18:19], v[202:203], v[144:145]
	v_pk_fma_f32 v[142:143], v[16:17], v[200:201], v[142:143]
	v_addc_co_u32_e32 v207, vcc, 0, v125, vcc
	v_cvt_pk_bf16_f32 v142, v142, v143
	v_cvt_pk_bf16_f32 v143, v144, v145
	v_pk_mul_f32 v[144:145], v[44:45], v[198:199] op_sel_hi:[0,1]
	v_cvt_pk_bf16_f32 v154, v154, v155
	v_cvt_pk_bf16_f32 v155, v158, v159
	v_add_co_u32_e32 v158, vcc, s0, v124
	s_waitcnt vmcnt(1)
	v_pk_mul_f32 v[144:145], v[14:15], v[144:145]
	v_addc_co_u32_e32 v159, vcc, 0, v125, vcc
	v_pk_fma_f32 v[144:145], v[10:11], v[144:145], v[140:141]
	v_pk_mul_f32 v[192:193], v[44:45], v[192:193] op_sel_hi:[0,1]
	v_cvt_pk_bf16_f32 v141, v144, v145
	v_pk_mul_f32 v[144:145], v[44:45], v[182:183] op_sel_hi:[0,1]
	v_pk_mul_f32 v[178:179], v[44:45], v[178:179] op_sel_hi:[0,1]
	v_mul_f32_e32 v44, 0x4b800000, v218
	v_cmp_gt_f32_e32 vcc, s72, v218
	s_waitcnt vmcnt(0)
; __device__ __forceinline__ f32x4 unpack4(u32x2 w) { return (f32x4){bf_lo(w.x), bf_hi(w.x), bf_lo(w.y), bf_hi(w.y)}; }
; __device__ __forceinline__ u32x2 pack4(f32x4 v) { u32x2 w; w.x = pk2(v[0], v[1]); w.y = pk2(v[2], v[3]); return w; }
; template <int NR, bool XIN16 = false, bool XOUT16 = false> ...
;     ...
;         for (int o = 1; o < 64; o <<= 1) {
; #pragma unroll
;             for (int q = 0; q < NR; ++q) ss[q] += __shfl_xor(ss[q], o); }
; #pragma unroll
;         for (int q = 0; q < NR; ++q) { const float rstd = rsqrtf(ss[q] * (1.f / DM) + EPS);
;             if (XOUT16) { u32x2* xo = (u32x2*)((bf16_t*)xout + (size_t)(row + q * rstride) * DM) + lane;
; #pragma unroll
;                 for (int j = 0; j < 4; ++j) { xv[q][j] = xv[q][j] + g[j] * (yv[q][j] * rstd * gy[j]); xo[64 * j] = pack4(xv[q][j]); xv[q][j] = unpack4(pack4(xv[q][j])); } }
	v_pk_mul_f32 v[178:179], v[4:5], v[178:179]
	v_pk_mul_f32 v[144:145], v[6:7], v[144:145]
	v_cndmask_b32_e32 v44, v218, v44, vcc
	v_rsq_f32_e32 v44, v44
	v_pk_fma_f32 v[138:139], v[2:3], v[144:145], v[138:139]
	v_pk_fma_f32 v[84:85], v[0:1], v[178:179], v[84:85]
	v_pk_mul_f32 v[192:193], v[12:13], v[192:193]
	v_mul_f32_e32 v46, 0x45800000, v44
	v_cndmask_b32_e32 v44, v44, v46, vcc
	v_cvt_pk_bf16_f32 v84, v84, v85
	v_cvt_pk_bf16_f32 v85, v138, v139
	v_pk_mul_f32 v[138:139], v[44:45], v[190:191] op_sel_hi:[0,1]
	v_pk_mul_f32 v[144:145], v[44:45], v[188:189] op_sel_hi:[0,1]
	v_pk_mul_f32 v[144:145], v[28:29], v[144:145]
	v_pk_mul_f32 v[138:139], v[30:31], v[138:139]
	v_pk_fma_f32 v[128:129], v[24:25], v[144:145], v[128:129]
	v_pk_fma_f32 v[130:131], v[26:27], v[138:139], v[130:131]
	v_cvt_pk_bf16_f32 v128, v128, v129
	v_cvt_pk_bf16_f32 v129, v130, v131
	v_mov_b32_e32 v130, v185
	v_mov_b32_e32 v131, v187
	v_pk_mul_f32 v[130:131], v[44:45], v[130:131] op_sel_hi:[0,1]
	v_mov_b32_e32 v185, v186
	v_pk_mul_f32 v[130:131], v[22:23], v[130:131]
	v_pk_mul_f32 v[138:139], v[44:45], v[184:185] op_sel_hi:[0,1]
	v_pk_fma_f32 v[126:127], v[18:19], v[130:131], v[126:127]
	v_mov_b32_e32 v130, v216
	v_mov_b32_e32 v131, v204
	v_mov_b32_e32 v204, v217
	v_pk_mul_f32 v[138:139], v[20:21], v[138:139]
	v_pk_add_f32 v[130:131], v[130:131], v[204:205]
	v_pk_fma_f32 v[94:95], v[16:17], v[138:139], v[94:95]
	v_cvt_pk_bf16_f32 v94, v94, v95
	v_cvt_pk_bf16_f32 v95, v126, v127
	v_pk_mul_f32 v[126:127], v[44:45], v[176:177] op_sel_hi:[0,1]
	v_pk_mul_f32 v[126:127], v[14:15], v[126:127]
	s_nop 1
	v_add_f32_dpp v130, v130, v130 quad_perm:[1,0,3,2] row_mask:0xf bank_mask:0xf
	v_add_f32_dpp v131, v131, v131 quad_perm:[1,0,3,2] row_mask:0xf bank_mask:0xf
	v_pk_fma_f32 v[90:91], v[10:11], v[126:127], v[90:91]
	v_pk_mul_f32 v[136:137], v[44:45], v[136:137] op_sel_hi:[0,1]
	v_cvt_pk_bf16_f32 v127, v90, v91
	v_pk_mul_f32 v[132:133], v[44:45], v[132:133] op_sel_hi:[0,1]
	s_nop 1
	v_add_f32_dpp v130, v130, v130 quad_perm:[2,3,0,1] row_mask:0xf bank_mask:0xf
	v_add_f32_dpp v131, v131, v131 quad_perm:[2,3,0,1] row_mask:0xf bank_mask:0xf
	v_pk_mul_f32 v[134:135], v[6:7], v[136:137]
	v_pk_mul_f32 v[132:133], v[4:5], v[132:133]
	v_pk_fma_f32 v[72:73], v[2:3], v[134:135], v[72:73]
	v_pk_fma_f32 v[68:69], v[0:1], v[132:133], v[68:69]
	s_nop 1
	v_add_f32_dpp v90, v130, v130 row_half_mirror row_mask:0xf bank_mask:0xf
	v_add_f32_dpp v91, v131, v131 row_half_mirror row_mask:0xf bank_mask:0xf
	v_cvt_pk_bf16_f32 v133, v72, v73
	v_pk_mul_f32 v[144:145], v[44:45], v[174:175] op_sel_hi:[0,1]
	v_cvt_pk_bf16_f32 v132, v68, v69
	global_store_dwordx2 v[206:207], v[132:133], off offset:3584
	s_nop 1
	v_add_f32_dpp v90, v90, v90 row_mirror row_mask:0xf bank_mask:0xf
	v_add_f32_dpp v91, v91, v91 row_mirror row_mask:0xf bank_mask:0xf
	v_lshlrev_b32_e32 v68, 16, v132
	v_and_b32_e32 v174, 0xffff0000, v132
	v_pk_mul_f32 v[144:145], v[12:13], v[144:145]
	v_pk_fma_f32 v[70:71], v[8:9], v[192:193], v[70:71]
	s_nop 1
	v_readlane_b32 s98, v90, 0
	v_readlane_b32 s99, v90, 16
	v_readlane_b32 s100, v90, 32
	v_readlane_b32 s101, v90, 48
	s_nop 1
	v_mov_b32_e32 v228, s98
	v_add_f32_e32 v228, s99, v228
	v_mov_b32_e32 v229, s100
	v_add_f32_e32 v229, s101, v229
	v_add_f32_e32 v90, v228, v229
	v_readlane_b32 s98, v91, 0
	v_readlane_b32 s99, v91, 16
	v_readlane_b32 s100, v91, 32
	v_readlane_b32 s101, v91, 48
	s_nop 1
	v_mov_b32_e32 v228, s98
	v_add_f32_e32 v228, s99, v228
	v_mov_b32_e32 v229, s100
	v_add_f32_e32 v229, s101, v229
	v_add_f32_e32 v91, v228, v229
	v_pk_fma_f32 v[80:81], v[8:9], v[144:145], v[80:81]
	v_cvt_pk_bf16_f32 v140, v70, v71
	v_cvt_pk_bf16_f32 v126, v80, v81
	global_store_dwordx2 v[158:159], v[154:155], off offset:-4096
	v_mov_b32_e32 v72, v90
	v_mov_b32_e32 v73, v91
	v_lshlrev_b32_e32 v90, 16, v133
	v_pk_fma_f32 v[130:131], v[72:73], s[82:83], v[52:53] op_sel_hi:[1,0,0]
	v_and_b32_e32 v91, 0xffff0000, v133
	v_mul_f32_e32 v44, 0x4b800000, v131
	v_cmp_gt_f32_e32 vcc, s72, v131
	global_store_dwordx2 v[206:207], v[142:143], off offset:512
	global_store_dwordx2 v[206:207], v[140:141], off offset:1024
	v_cndmask_b32_e32 v44, v131, v44, vcc
	v_rsq_f32_e32 v44, v44
	global_store_dwordx2 v[206:207], v[84:85], off offset:1536
	global_store_dwordx2 v[206:207], v[128:129], off offset:2048
	global_store_dwordx2 v[206:207], v[94:95], off offset:2560
	v_mul_f32_e32 v46, 0x45800000, v44
	v_cndmask_b32_e32 v44, v44, v46, vcc
	v_pk_mul_f32 v[132:133], v[44:45], v[170:171] op_sel_hi:[0,1]
	v_pk_mul_f32 v[72:73], v[44:45], v[172:173] op_sel_hi:[0,1]
	v_pk_mul_f32 v[132:133], v[28:29], v[132:133]
	v_pk_mul_f32 v[72:73], v[30:31], v[72:73]
	v_pk_fma_f32 v[36:37], v[24:25], v[132:133], v[36:37]
	v_pk_fma_f32 v[40:41], v[26:27], v[72:73], v[40:41]
	v_cvt_pk_bf16_f32 v138, v36, v37
	v_mov_b32_e32 v36, v165
	v_mov_b32_e32 v37, v169
	v_mov_b32_e32 v165, v168
	v_cvt_pk_bf16_f32 v139, v40, v41
	v_pk_mul_f32 v[36:37], v[44:45], v[36:37] op_sel_hi:[0,1]
	v_pk_mul_f32 v[40:41], v[44:45], v[164:165] op_sel_hi:[0,1]
	v_pk_mul_f32 v[40:41], v[20:21], v[40:41]
	v_pk_mul_f32 v[36:37], v[22:23], v[36:37]
	v_pk_fma_f32 v[40:41], v[16:17], v[40:41], v[82:83]
	v_pk_fma_f32 v[36:37], v[18:19], v[36:37], v[86:87]
	v_cvt_pk_bf16_f32 v86, v40, v41
	v_cvt_pk_bf16_f32 v87, v36, v37
	v_pk_mul_f32 v[36:37], v[44:45], v[166:167] op_sel_hi:[0,1]
	v_pk_mul_f32 v[40:41], v[44:45], v[162:163] op_sel_hi:[0,1]
	v_pk_mul_f32 v[40:41], v[12:13], v[40:41]
	v_pk_mul_f32 v[36:37], v[14:15], v[36:37]
	v_pk_fma_f32 v[40:41], v[8:9], v[40:41], v[74:75]
	v_pk_fma_f32 v[36:37], v[10:11], v[36:37], v[78:79]
	v_cvt_pk_bf16_f32 v74, v40, v41
	v_cvt_pk_bf16_f32 v75, v36, v37
; __device__ __forceinline__ f32x4 unpack4(u32x2 w) { return (f32x4){bf_lo(w.x), bf_hi(w.x), bf_lo(w.y), bf_hi(w.y)}; }
; __device__ __forceinline__ u32x2 pack4(f32x4 v) { u32x2 w; w.x = pk2(v[0], v[1]); w.y = pk2(v[2], v[3]); return w; }
; template <int NR, bool XIN16 = false, bool XOUT16 = false> ...
;     ...
;             if (XOUT16) { u32x2* xo = (u32x2*)((bf16_t*)xout + (size_t)(row + q * rstride) * DM) + lane;
; #pragma unroll
;                 for (int j = 0; j < 4; ++j) { xv[q][j] = xv[q][j] + g[j] * (yv[q][j] * rstd * gy[j]); xo[64 * j] = pack4(xv[q][j]); xv[q][j] = unpack4(pack4(xv[q][j])); } }
;             else { f32x4* xo = (f32x4*)(xout + (size_t)(row + q * rstride) * DM) + lane;
; #pragma unroll
;                 for (int j = 0; j < 4; ++j) { xv[q][j] = xv[q][j] + g[j] * (yv[q][j] * rstd * gy[j]); xo[64 * j] = xv[q][j]; } } }
;     }
;     if (hout) {
;         f32x4 gh[4], s1[4], s0[4];
; #pragma unroll
;         for (int j = 0; j < 4; ++j) { gh[j] = ((const f32x4*)gainH)[lane + 64 * j]; s1[j] = ((const f32x4*)sc)[lane + 64 * j]; s0[j] = ((const f32x4*)sh)[lane + 64 * j]; }
;         float ss[NR];
; #pragma unroll
;         for (int q = 0; q < NR; ++q) { ss[q] = 0.f;
; #pragma unroll
;             for (int j = 0; j < 4; ++j) ss[q] += (xv[q][j][0] * xv[q][j][0] + xv[q][j][1] * xv[q][j][1]) + (xv[q][j][2] * xv[q][j][2] + xv[q][j][3] * xv[q][j][3]); }
	v_pk_mul_f32 v[36:37], v[44:45], v[92:93] op_sel_hi:[0,1]
	v_pk_mul_f32 v[40:41], v[44:45], v[88:89] op_sel_hi:[0,1]
	v_pk_mul_f32 v[40:41], v[4:5], v[40:41]
	v_pk_mul_f32 v[36:37], v[6:7], v[36:37]
	v_pk_fma_f32 v[40:41], v[0:1], v[40:41], v[64:65]
	v_pk_fma_f32 v[36:37], v[2:3], v[36:37], v[66:67]
	v_cvt_pk_bf16_f32 v40, v40, v41
	v_cvt_pk_bf16_f32 v41, v36, v37
	v_mul_f32_e32 v36, 0x4b800000, v130
	v_cmp_gt_f32_e32 vcc, s72, v130
	global_store_dwordx2 v[158:159], v[40:41], off offset:1536
	v_lshlrev_b32_e32 v64, 16, v40
	v_cndmask_b32_e32 v36, v130, v36, vcc
	v_rsq_f32_e32 v36, v36
	v_and_b32_e32 v162, 0xffff0000, v40
	v_lshlrev_b32_e32 v66, 16, v41
	v_and_b32_e32 v67, 0xffff0000, v41
	v_mul_f32_e32 v37, 0x45800000, v36
	v_cndmask_b32_e32 v36, v36, v37, vcc
	v_pk_mul_f32 v[78:79], v[36:37], v[156:157] op_sel_hi:[0,1]
	v_pk_mul_f32 v[40:41], v[36:37], v[160:161] op_sel_hi:[0,1]
	v_pk_mul_f32 v[28:29], v[28:29], v[78:79]
	v_pk_mul_f32 v[30:31], v[30:31], v[40:41]
	v_pk_fma_f32 v[24:25], v[24:25], v[28:29], v[60:61]
	v_pk_fma_f32 v[26:27], v[26:27], v[30:31], v[62:63]
	v_cvt_pk_bf16_f32 v60, v24, v25
	v_mov_b32_e32 v24, v149
	v_mov_b32_e32 v25, v153
	v_mov_b32_e32 v149, v152
	v_cvt_pk_bf16_f32 v61, v26, v27
	v_pk_mul_f32 v[24:25], v[36:37], v[24:25] op_sel_hi:[0,1]
	v_pk_mul_f32 v[26:27], v[36:37], v[148:149] op_sel_hi:[0,1]
	v_pk_mul_f32 v[20:21], v[20:21], v[26:27]
	v_pk_mul_f32 v[22:23], v[22:23], v[24:25]
	v_pk_fma_f32 v[16:17], v[16:17], v[20:21], v[54:55]
	v_pk_fma_f32 v[18:19], v[18:19], v[22:23], v[58:59]
	v_cvt_pk_bf16_f32 v62, v16, v17
	v_cvt_pk_bf16_f32 v63, v18, v19
	v_pk_mul_f32 v[16:17], v[36:37], v[150:151] op_sel_hi:[0,1]
	v_pk_mul_f32 v[18:19], v[36:37], v[146:147] op_sel_hi:[0,1]
	v_pk_mul_f32 v[12:13], v[12:13], v[18:19]
	v_pk_mul_f32 v[14:15], v[14:15], v[16:17]
	v_pk_fma_f32 v[8:9], v[8:9], v[12:13], v[38:39]
	v_pk_fma_f32 v[10:11], v[10:11], v[14:15], v[42:43]
	v_mov_b32_e32 v44, v47
	v_cvt_pk_bf16_f32 v130, v8, v9
	v_cvt_pk_bf16_f32 v131, v10, v11
	v_pk_mul_f32 v[8:9], v[36:37], v[56:57] op_sel_hi:[0,1]
	v_pk_mul_f32 v[10:11], v[36:37], v[44:45] op_sel_hi:[0,1]
	v_pk_mul_f32 v[4:5], v[4:5], v[10:11]
	v_pk_mul_f32 v[6:7], v[6:7], v[8:9]
	v_pk_fma_f32 v[0:1], v[0:1], v[4:5], v[32:33]
	v_pk_fma_f32 v[2:3], v[2:3], v[6:7], v[34:35]
	v_cvt_pk_bf16_f32 v0, v0, v1
	v_cvt_pk_bf16_f32 v1, v2, v3
	global_store_dwordx2 v[206:207], v[126:127], off offset:3072
	global_store_dwordx2 v[158:159], v[138:139], off
	global_store_dwordx2 v[158:159], v[86:87], off offset:512
	global_store_dwordx2 v[158:159], v[74:75], off offset:1024
	global_store_dwordx2 v[158:159], v[60:61], off offset:2048
	global_store_dwordx2 v[158:159], v[62:63], off offset:2560
	global_store_dwordx2 v[158:159], v[130:131], off offset:3072
	global_store_dwordx2 v[158:159], v[0:1], off offset:3584
	v_lshlrev_b32_e32 v56, 16, v0
	v_and_b32_e32 v156, 0xffff0000, v0
	v_lshlrev_b32_e32 v58, 16, v1
	v_and_b32_e32 v59, 0xffff0000, v1
	global_load_dwordx4 v[40:43], v109, s[6:7]
	global_load_dwordx4 v[24:27], v109, s[18:19]
	global_load_dwordx4 v[28:31], v[114:115], off
	global_load_dwordx4 v[16:19], v[116:117], off
	global_load_dwordx4 v[44:47], v105, s[6:7]
	global_load_dwordx4 v[20:23], v105, s[18:19]
	global_load_dwordx4 v[32:35], v101, s[6:7]
	global_load_dwordx4 v[8:11], v101, s[18:19]
	global_load_dwordx4 v[12:15], v[118:119], off
	global_load_dwordx4 v[0:3], v[120:121], off
	global_load_dwordx4 v[36:39], v97, s[6:7]
	global_load_dwordx4 v[4:7], v97, s[18:19]
	v_and_b32_e32 v151, 0xffff0000, v155
	v_and_b32_e32 v150, 0xffff0000, v154
	v_and_b32_e32 v147, 0xffff0000, v143
	v_and_b32_e32 v146, 0xffff0000, v142
	v_lshlrev_b32_e32 v70, 16, v140
	v_and_b32_e32 v71, 0xffff0000, v140
	v_lshlrev_b32_e32 v76, 16, v84
	v_lshlrev_b32_e32 v149, 16, v155
	v_lshlrev_b32_e32 v148, 16, v154
	v_pk_mul_f32 v[78:79], v[150:151], v[150:151]
	v_lshlrev_b32_e32 v145, 16, v143
	v_lshlrev_b32_e32 v144, 16, v142
	v_pk_mul_f32 v[82:83], v[146:147], v[146:147]
	v_lshlrev_b32_e32 v142, 16, v141
	v_lshlrev_b32_e32 v72, 16, v74
	v_and_b32_e32 v73, 0xffff0000, v74
	v_pk_fma_f32 v[78:79], v[148:149], v[148:149], v[78:79]
	v_pk_fma_f32 v[82:83], v[144:145], v[144:145], v[82:83]
	v_mul_f32_e32 v77, v70, v70
	v_mul_f32_e32 v89, v71, v71
	v_and_b32_e32 v143, 0xffff0000, v141
	v_mul_f32_e32 v74, v142, v142
	v_mov_b32_e32 v88, v76
	v_and_b32_e32 v178, 0xffff0000, v84
	v_lshlrev_b32_e32 v84, 16, v85
	v_and_b32_e32 v85, 0xffff0000, v85
	v_pk_add_f32 v[78:79], v[78:79], v[78:79] op_sel_hi:[0,1]
	v_pk_add_f32 v[82:83], v[82:83], v[82:83] op_sel_hi:[0,1]
	v_pk_fma_f32 v[92:93], v[142:143], v[142:143], v[74:75] op_sel_hi:[1,1,0]
	v_pk_add_f32 v[88:89], v[76:77], v[88:89]
	v_mul_f32_e32 v92, v178, v178
	v_mul_f32_e32 v78, v84, v84
	v_mul_f32_e32 v82, v85, v85
	v_mul_f32_e32 v132, v76, v76
	v_mov_b32_e32 v133, v89
	v_pk_add_f32 v[88:89], v[132:133], v[92:93]
	v_pk_add_f32 v[78:79], v[78:79], v[82:83]
	v_and_b32_e32 v137, 0xffff0000, v129
	v_and_b32_e32 v136, 0xffff0000, v128
	v_and_b32_e32 v133, 0xffff0000, v95
	v_and_b32_e32 v132, 0xffff0000, v94
	v_lshlrev_b32_e32 v80, 16, v126
	v_and_b32_e32 v81, 0xffff0000, v126
	v_pk_add_f32 v[140:141], v[88:89], v[78:79]
	v_lshlrev_b32_e32 v135, 16, v129
	v_lshlrev_b32_e32 v134, 16, v128
	v_pk_mul_f32 v[78:79], v[136:137], v[136:137]
	v_lshlrev_b32_e32 v129, 16, v95
	v_lshlrev_b32_e32 v128, 16, v94
	v_pk_mul_f32 v[82:83], v[132:133], v[132:133]
	v_lshlrev_b32_e32 v126, 16, v127
	v_pk_fma_f32 v[78:79], v[134:135], v[134:135], v[78:79]
	v_pk_fma_f32 v[82:83], v[128:129], v[128:129], v[82:83]
	v_mul_f32_e32 v69, v80, v80
	v_mul_f32_e32 v89, v81, v81
	v_and_b32_e32 v127, 0xffff0000, v127
; __device__ __forceinline__ u32x2 pack4(f32x4 v) { u32x2 w; w.x = pk2(v[0], v[1]); w.y = pk2(v[2], v[3]); return w; }
; template <int NR, bool XIN16 = false, bool XOUT16 = false> ...
;     ...
;     if (hout) {
;         f32x4 gh[4], s1[4], s0[4];
; #pragma unroll
;         for (int j = 0; j < 4; ++j) { gh[j] = ((const f32x4*)gainH)[lane + 64 * j]; s1[j] = ((const f32x4*)sc)[lane + 64 * j]; s0[j] = ((const f32x4*)sh)[lane + 64 * j]; }
;         float ss[NR];
; #pragma unroll
;         for (int q = 0; q < NR; ++q) { ss[q] = 0.f;
; #pragma unroll
;             for (int j = 0; j < 4; ++j) ss[q] += (xv[q][j][0] * xv[q][j][0] + xv[q][j][1] * xv[q][j][1]) + (xv[q][j][2] * xv[q][j][2] + xv[q][j][3] * xv[q][j][3]); }
; #pragma unroll
;         for (int o = 1; o < 64; o <<= 1) {
; #pragma unroll
;             for (int q = 0; q < NR; ++q) ss[q] += __shfl_xor(ss[q], o); }
; #pragma unroll
;         for (int q = 0; q < NR; ++q) { const float rstd = rsqrtf(ss[q] * (1.f / DM) + EPS);
;             u32x2* ho = (u32x2*)(hout + (size_t)(row + q * rstride) * DM) + lane;
; #pragma unroll
;             for (int j = 0; j < 4; ++j) { const f32x4 hv = (xv[q][j] * rstd * gh[j]) * (1.f + s1[j]) + s0[j]; ho[64 * j] = pack4(hv); } }
	v_mul_f32_e32 v74, v126, v126
	v_mov_b32_e32 v88, v68
	v_pk_add_f32 v[78:79], v[78:79], v[78:79] op_sel_hi:[0,1]
	v_pk_add_f32 v[82:83], v[82:83], v[82:83] op_sel_hi:[0,1]
	v_pk_fma_f32 v[92:93], v[126:127], v[126:127], v[74:75] op_sel_hi:[1,1,0]
	v_pk_add_f32 v[88:89], v[68:69], v[88:89]
	v_mul_f32_e32 v92, v174, v174
	v_mul_f32_e32 v78, v90, v90
	v_mul_f32_e32 v82, v91, v91
	v_mul_f32_e32 v94, v68, v68
	v_mov_b32_e32 v95, v89
	v_pk_add_f32 v[88:89], v[94:95], v[92:93]
	v_pk_add_f32 v[78:79], v[78:79], v[82:83]
	v_lshlrev_b32_e32 v83, 16, v87
	v_lshlrev_b32_e32 v82, 16, v86
	v_and_b32_e32 v87, 0xffff0000, v87
	v_and_b32_e32 v86, 0xffff0000, v86
	v_pk_add_f32 v[154:155], v[88:89], v[78:79]
	v_pk_mul_f32 v[88:89], v[86:87], v[86:87]
	v_lshlrev_b32_e32 v93, 16, v139
	v_pk_fma_f32 v[88:89], v[82:83], v[82:83], v[88:89]
	v_lshlrev_b32_e32 v92, 16, v138
	v_and_b32_e32 v95, 0xffff0000, v139
	v_and_b32_e32 v94, 0xffff0000, v138
	v_pk_add_f32 v[138:139], v[88:89], v[88:89] op_sel_hi:[0,1]
	v_lshlrev_b32_e32 v88, 16, v75
	v_mul_f32_e32 v65, v72, v72
	v_mul_f32_e32 v153, v73, v73
	v_and_b32_e32 v89, 0xffff0000, v75
	v_mul_f32_e32 v74, v88, v88
	v_mov_b32_e32 v152, v64
	v_pk_fma_f32 v[74:75], v[88:89], v[88:89], v[74:75] op_sel_hi:[1,1,0]
	v_pk_add_f32 v[152:153], v[64:65], v[152:153]
	v_mul_f32_e32 v74, v162, v162
	v_mul_f32_e32 v158, v64, v64
	v_mov_b32_e32 v159, v153
	v_pk_add_f32 v[74:75], v[158:159], v[74:75]
	v_mov_b32_e32 v158, v154
	v_mov_b32_e32 v159, v140
	v_mov_b32_e32 v140, v155
	v_pk_add_f32 v[140:141], v[158:159], v[140:141]
	v_pk_mul_f32 v[78:79], v[94:95], v[94:95]
	v_mul_f32_e32 v138, v67, v67
	v_pk_fma_f32 v[78:79], v[92:93], v[92:93], v[78:79]
	v_lshlrev_b32_e32 v54, 16, v130
	s_nop 1
	v_add_f32_dpp v140, v140, v140 quad_perm:[1,0,3,2] row_mask:0xf bank_mask:0xf
	v_add_f32_dpp v141, v141, v141 quad_perm:[1,0,3,2] row_mask:0xf bank_mask:0xf
	v_pk_add_f32 v[78:79], v[78:79], v[78:79] op_sel_hi:[0,1]
	v_mul_f32_e32 v78, v66, v66
	v_pk_add_f32 v[78:79], v[78:79], v[138:139]
	v_and_b32_e32 v55, 0xffff0000, v130
	s_nop 1
	v_add_f32_dpp v140, v140, v140 quad_perm:[2,3,0,1] row_mask:0xf bank_mask:0xf
	v_add_f32_dpp v141, v141, v141 quad_perm:[2,3,0,1] row_mask:0xf bank_mask:0xf
	v_pk_add_f32 v[152:153], v[74:75], v[78:79]
	v_and_b32_e32 v79, 0xffff0000, v61
	v_and_b32_e32 v78, 0xffff0000, v60
	v_lshlrev_b32_e32 v75, 16, v61
	s_nop 1
	v_add_f32_dpp v140, v140, v140 row_half_mirror row_mask:0xf bank_mask:0xf
	v_add_f32_dpp v141, v141, v141 row_half_mirror row_mask:0xf bank_mask:0xf
	v_lshlrev_b32_e32 v74, 16, v60
	v_pk_mul_f32 v[60:61], v[78:79], v[78:79]
	v_lshlrev_b32_e32 v130, 16, v131
	v_pk_fma_f32 v[60:61], v[74:75], v[74:75], v[60:61]
	s_nop 1
	v_add_f32_dpp v140, v140, v140 row_mirror row_mask:0xf bank_mask:0xf
	v_add_f32_dpp v141, v141, v141 row_mirror row_mask:0xf bank_mask:0xf
	v_pk_add_f32 v[138:139], v[60:61], v[60:61] op_sel_hi:[0,1]
	v_lshlrev_b32_e32 v61, 16, v63
	v_lshlrev_b32_e32 v60, 16, v62
	v_and_b32_e32 v63, 0xffff0000, v63
	v_and_b32_e32 v62, 0xffff0000, v62
	v_pk_mul_f32 v[158:159], v[62:63], v[62:63]
	v_pk_fma_f32 v[158:159], v[60:61], v[60:61], v[158:159]
	v_mul_f32_e32 v57, v54, v54
	v_mul_f32_e32 v161, v55, v55
	v_and_b32_e32 v131, 0xffff0000, v131
	v_mul_f32_e32 v138, v130, v130
	v_mov_b32_e32 v160, v56
	v_pk_add_f32 v[158:159], v[158:159], v[158:159] op_sel_hi:[0,1]
	v_pk_fma_f32 v[164:165], v[130:131], v[130:131], v[138:139] op_sel_hi:[1,1,0]
	v_pk_add_f32 v[160:161], v[56:57], v[160:161]
	v_mul_f32_e32 v164, v156, v156
	v_mul_f32_e32 v138, v58, v58
	v_mul_f32_e32 v158, v59, v59
	v_mul_f32_e32 v166, v56, v56
	v_mov_b32_e32 v167, v161
	v_pk_add_f32 v[160:161], v[166:167], v[164:165]
	v_pk_add_f32 v[138:139], v[138:139], v[158:159]
	s_waitcnt vmcnt(7)
	v_pk_add_f32 v[46:47], v[46:47], 1.0 op_sel_hi:[1,0]
	v_pk_add_f32 v[158:159], v[160:161], v[138:139]
	v_pk_add_f32 v[138:139], v[42:43], 1.0 op_sel_hi:[1,0]
	s_nop 1
	v_readlane_b32 s98, v140, 0
	v_readlane_b32 s99, v140, 16
	v_readlane_b32 s100, v140, 32
	v_readlane_b32 s101, v140, 48
	s_nop 1
	v_mov_b32_e32 v228, s98
	v_add_f32_e32 v228, s99, v228
	v_mov_b32_e32 v229, s100
	v_add_f32_e32 v229, s101, v229
	v_add_f32_e32 v42, v228, v229
	v_readlane_b32 s98, v141, 0
	v_readlane_b32 s99, v141, 16
	v_readlane_b32 s100, v141, 32
	v_readlane_b32 s101, v141, 48
	s_nop 1
	v_mov_b32_e32 v228, s98
	v_add_f32_e32 v228, s99, v228
	v_mov_b32_e32 v229, s100
	v_add_f32_e32 v229, s101, v229
	v_add_f32_e32 v43, v228, v229
	v_pk_add_f32 v[140:141], v[40:41], 1.0 op_sel_hi:[1,0]
	s_waitcnt vmcnt(5)
	v_pk_add_f32 v[40:41], v[34:35], 1.0 op_sel_hi:[1,0]
	v_pk_add_f32 v[44:45], v[44:45], 1.0 op_sel_hi:[1,0]
	v_mov_b32_e32 v77, v178
	v_mov_b32_e32 v34, v42
	v_mov_b32_e32 v35, v43
	v_pk_add_f32 v[42:43], v[32:33], 1.0 op_sel_hi:[1,0]
	v_pk_fma_f32 v[154:155], v[34:35], s[82:83], v[52:53] op_sel_hi:[1,0,0]
	s_waitcnt vmcnt(1)
; __device__ __forceinline__ u32x2 pack4(f32x4 v) { u32x2 w; w.x = pk2(v[0], v[1]); w.y = pk2(v[2], v[3]); return w; }
; template <int NR, bool XIN16 = false, bool XOUT16 = false> ...
;     ...
;         for (int o = 1; o < 64; o <<= 1) {
; #pragma unroll
;             for (int q = 0; q < NR; ++q) ss[q] += __shfl_xor(ss[q], o); }
; #pragma unroll
;         for (int q = 0; q < NR; ++q) { const float rstd = rsqrtf(ss[q] * (1.f / DM) + EPS);
;             u32x2* ho = (u32x2*)(hout + (size_t)(row + q * rstride) * DM) + lane;
; #pragma unroll
;             for (int j = 0; j < 4; ++j) { const f32x4 hv = (xv[q][j] * rstd * gh[j]) * (1.f + s1[j]) + s0[j]; ho[64 * j] = pack4(hv); } }
	v_pk_add_f32 v[32:33], v[38:39], 1.0 op_sel_hi:[1,0]
	v_mul_f32_e32 v34, 0x4b800000, v155
	v_cmp_gt_f32_e32 vcc, s72, v155
	v_mov_b32_e32 v38, v149
	v_mov_b32_e32 v39, v151
	v_cndmask_b32_e32 v34, v155, v34, vcc
	v_rsq_f32_e32 v57, v34
	v_pk_add_f32 v[34:35], v[36:37], 1.0 op_sel_hi:[1,0]
	v_mov_b32_e32 v149, v150
	v_mov_b32_e32 v69, v174
	v_mul_f32_e32 v36, 0x45800000, v57
	v_cndmask_b32_e32 v36, v57, v36, vcc
	v_pk_mul_f32 v[38:39], v[36:37], v[38:39] op_sel_hi:[0,1]
	v_pk_mul_f32 v[148:149], v[36:37], v[148:149] op_sel_hi:[0,1]
	v_pk_mul_f32 v[148:149], v[28:29], v[148:149]
	v_pk_mul_f32 v[38:39], v[30:31], v[38:39]
	v_pk_fma_f32 v[148:149], v[140:141], v[148:149], v[24:25]
	v_pk_fma_f32 v[38:39], v[138:139], v[38:39], v[26:27]
	v_cvt_pk_bf16_f32 v148, v148, v149
	v_cvt_pk_bf16_f32 v149, v38, v39
	v_mov_b32_e32 v38, v145
	v_mov_b32_e32 v39, v147
	v_mov_b32_e32 v145, v146
	v_pk_mul_f32 v[38:39], v[36:37], v[38:39] op_sel_hi:[0,1]
	v_pk_mul_f32 v[144:145], v[36:37], v[144:145] op_sel_hi:[0,1]
	v_pk_mul_f32 v[144:145], v[16:17], v[144:145]
	v_pk_mul_f32 v[38:39], v[18:19], v[38:39]
	v_pk_fma_f32 v[144:145], v[44:45], v[144:145], v[20:21]
	v_pk_fma_f32 v[38:39], v[46:47], v[38:39], v[22:23]
	v_cvt_pk_bf16_f32 v144, v144, v145
	v_cvt_pk_bf16_f32 v145, v38, v39
	v_pk_mul_f32 v[38:39], v[36:37], v[142:143] op_sel_hi:[0,1]
	v_pk_mul_f32 v[70:71], v[36:37], v[70:71] op_sel_hi:[0,1]
	v_pk_mul_f32 v[70:71], v[12:13], v[70:71]
	v_pk_mul_f32 v[38:39], v[14:15], v[38:39]
	v_mul_f32_e32 v57, 0x4b800000, v154
	v_cmp_gt_f32_e32 vcc, s72, v154
	v_pk_fma_f32 v[38:39], v[40:41], v[38:39], v[10:11]
	v_pk_fma_f32 v[70:71], v[42:43], v[70:71], v[8:9]
	v_cndmask_b32_e32 v57, v154, v57, vcc
	v_cvt_pk_bf16_f32 v70, v70, v71
	v_cvt_pk_bf16_f32 v71, v38, v39
	v_pk_mul_f32 v[38:39], v[36:37], v[84:85] op_sel_hi:[0,1]
	v_pk_mul_f32 v[36:37], v[36:37], v[76:77] op_sel_hi:[0,1]
	v_rsq_f32_e32 v57, v57
	v_pk_mul_f32 v[36:37], v[0:1], v[36:37]
	v_pk_mul_f32 v[38:39], v[2:3], v[38:39]
	s_waitcnt vmcnt(0)
	v_pk_fma_f32 v[36:37], v[34:35], v[36:37], v[4:5]
	v_pk_fma_f32 v[38:39], v[32:33], v[38:39], v[6:7]
	v_cvt_pk_bf16_f32 v36, v36, v37
	v_cvt_pk_bf16_f32 v37, v38, v39
	global_store_dwordx2 v[50:51], v[36:37], off offset:1536
	v_mul_f32_e32 v36, 0x45800000, v57
	v_cndmask_b32_e32 v36, v57, v36, vcc
	v_mov_b32_e32 v38, v135
	v_mov_b32_e32 v39, v137
	v_mov_b32_e32 v135, v136
	global_store_dwordx2 v[50:51], v[70:71], off offset:1024
	v_pk_mul_f32 v[38:39], v[36:37], v[38:39] op_sel_hi:[0,1]
	v_pk_mul_f32 v[70:71], v[36:37], v[134:135] op_sel_hi:[0,1]
	v_pk_mul_f32 v[70:71], v[28:29], v[70:71]
	v_pk_mul_f32 v[38:39], v[30:31], v[38:39]
	v_pk_fma_f32 v[70:71], v[140:141], v[70:71], v[24:25]
	v_pk_fma_f32 v[38:39], v[138:139], v[38:39], v[26:27]
	v_cvt_pk_bf16_f32 v70, v70, v71
	v_cvt_pk_bf16_f32 v71, v38, v39
	global_store_dwordx2 v[50:51], v[70:71], off offset:2048
	v_mov_b32_e32 v70, v158
	v_mov_b32_e32 v71, v152
	v_mov_b32_e32 v152, v159
	v_pk_add_f32 v[70:71], v[70:71], v[152:153]
	v_mov_b32_e32 v38, v129
	v_mov_b32_e32 v39, v133
	v_mov_b32_e32 v129, v132
	v_pk_mul_f32 v[38:39], v[36:37], v[38:39] op_sel_hi:[0,1]
	s_nop 1
	v_add_f32_dpp v70, v70, v70 quad_perm:[1,0,3,2] row_mask:0xf bank_mask:0xf
	v_add_f32_dpp v71, v71, v71 quad_perm:[1,0,3,2] row_mask:0xf bank_mask:0xf
	v_pk_mul_f32 v[84:85], v[36:37], v[128:129] op_sel_hi:[0,1]
	v_pk_mul_f32 v[84:85], v[16:17], v[84:85]
	v_pk_mul_f32 v[38:39], v[18:19], v[38:39]
	v_pk_fma_f32 v[84:85], v[44:45], v[84:85], v[20:21]
	v_pk_fma_f32 v[38:39], v[46:47], v[38:39], v[22:23]
	v_cvt_pk_bf16_f32 v84, v84, v85
	v_cvt_pk_bf16_f32 v85, v38, v39
	s_nop 1
	v_add_f32_dpp v38, v70, v70 quad_perm:[2,3,0,1] row_mask:0xf bank_mask:0xf
	v_add_f32_dpp v39, v71, v71 quad_perm:[2,3,0,1] row_mask:0xf bank_mask:0xf
	v_pk_mul_f32 v[76:77], v[36:37], v[126:127] op_sel_hi:[0,1]
	v_pk_mul_f32 v[80:81], v[36:37], v[80:81] op_sel_hi:[0,1]
	v_pk_mul_f32 v[80:81], v[12:13], v[80:81]
	v_pk_mul_f32 v[76:77], v[14:15], v[76:77]
	s_nop 1
	v_add_f32_dpp v38, v38, v38 row_half_mirror row_mask:0xf bank_mask:0xf
	v_add_f32_dpp v39, v39, v39 row_half_mirror row_mask:0xf bank_mask:0xf
	v_pk_fma_f32 v[76:77], v[40:41], v[76:77], v[10:11]
	v_pk_fma_f32 v[80:81], v[42:43], v[80:81], v[8:9]
	global_store_dwordx2 v[50:51], v[144:145], off offset:512
	v_cvt_pk_bf16_f32 v80, v80, v81
	s_nop 1
	v_add_f32_dpp v38, v38, v38 row_mirror row_mask:0xf bank_mask:0xf
	v_add_f32_dpp v39, v39, v39 row_mirror row_mask:0xf bank_mask:0xf
	v_cvt_pk_bf16_f32 v81, v76, v77
	v_pk_mul_f32 v[76:77], v[36:37], v[90:91] op_sel_hi:[0,1]
	v_pk_mul_f32 v[36:37], v[36:37], v[68:69] op_sel_hi:[0,1]
	v_pk_mul_f32 v[36:37], v[0:1], v[36:37]
	s_nop 1
	v_readlane_b32 s98, v38, 0
	v_readlane_b32 s99, v38, 16
	v_readlane_b32 s100, v38, 32
	v_readlane_b32 s101, v38, 48
	s_nop 1
	v_mov_b32_e32 v228, s98
	v_add_f32_e32 v228, s99, v228
	v_mov_b32_e32 v229, s100
	v_add_f32_e32 v229, s101, v229
	v_add_f32_e32 v38, v228, v229
	v_readlane_b32 s98, v39, 0
	v_readlane_b32 s99, v39, 16
	v_readlane_b32 s100, v39, 32
	v_readlane_b32 s101, v39, 48
	s_nop 1
	v_mov_b32_e32 v228, s98
	v_add_f32_e32 v228, s99, v228
	v_mov_b32_e32 v229, s100
	v_add_f32_e32 v229, s101, v229
	v_add_f32_e32 v39, v228, v229
	v_pk_mul_f32 v[70:71], v[2:3], v[76:77]
	v_pk_fma_f32 v[36:37], v[34:35], v[36:37], v[4:5]
	v_pk_fma_f32 v[70:71], v[32:33], v[70:71], v[6:7]
	v_cvt_pk_bf16_f32 v36, v36, v37
	v_cvt_pk_bf16_f32 v37, v70, v71
	v_pk_fma_f32 v[38:39], v[38:39], s[82:83], v[52:53] op_sel_hi:[1,0,0]
	global_store_dwordx2 v[50:51], v[36:37], off offset:3584
	v_mul_f32_e32 v52, 0x4b800000, v39
	v_cmp_gt_f32_e32 vcc, s72, v39
; __device__ __forceinline__ u32x2 pack4(f32x4 v) { u32x2 w; w.x = pk2(v[0], v[1]); w.y = pk2(v[2], v[3]); return w; }
; template <int NR, bool XIN16 = false, bool XOUT16 = false> ...
;     ...
;         for (int q = 0; q < NR; ++q) { const float rstd = rsqrtf(ss[q] * (1.f / DM) + EPS);
;             u32x2* ho = (u32x2*)(hout + (size_t)(row + q * rstride) * DM) + lane;
; #pragma unroll
;             for (int j = 0; j < 4; ++j) { const f32x4 hv = (xv[q][j] * rstd * gh[j]) * (1.f + s1[j]) + s0[j]; ho[64 * j] = pack4(hv); } }
	global_store_dwordx2 v[50:51], v[84:85], off offset:2560
	global_store_dwordx2 v[50:51], v[80:81], off offset:3072
	v_cndmask_b32_e32 v39, v39, v52, vcc
	v_rsq_f32_e32 v39, v39
	v_mov_b32_e32 v50, v93
	v_mov_b32_e32 v51, v95
	v_mov_b32_e32 v93, v94
	v_mul_f32_e32 v36, 0x45800000, v39
	v_cndmask_b32_e32 v36, v39, v36, vcc
	v_pk_mul_f32 v[50:51], v[36:37], v[50:51] op_sel_hi:[0,1]
	v_pk_mul_f32 v[52:53], v[36:37], v[92:93] op_sel_hi:[0,1]
	v_pk_mul_f32 v[52:53], v[28:29], v[52:53]
	v_pk_mul_f32 v[50:51], v[30:31], v[50:51]
	v_pk_fma_f32 v[52:53], v[140:141], v[52:53], v[24:25]
	v_pk_fma_f32 v[50:51], v[138:139], v[50:51], v[26:27]
	v_cvt_pk_bf16_f32 v52, v52, v53
	v_cvt_pk_bf16_f32 v53, v50, v51
	v_mov_b32_e32 v50, v83
	v_mov_b32_e32 v51, v87
	v_mov_b32_e32 v83, v86
	global_store_dwordx2 v[48:49], v[52:53], off
	v_pk_mul_f32 v[50:51], v[36:37], v[50:51] op_sel_hi:[0,1]
	v_pk_mul_f32 v[52:53], v[36:37], v[82:83] op_sel_hi:[0,1]
	v_pk_mul_f32 v[52:53], v[16:17], v[52:53]
	v_pk_mul_f32 v[50:51], v[18:19], v[50:51]
	v_pk_fma_f32 v[52:53], v[44:45], v[52:53], v[20:21]
	v_pk_fma_f32 v[50:51], v[46:47], v[50:51], v[22:23]
	v_cvt_pk_bf16_f32 v52, v52, v53
	v_cvt_pk_bf16_f32 v53, v50, v51
	global_store_dwordx2 v[48:49], v[52:53], off offset:512
	v_pk_mul_f32 v[50:51], v[36:37], v[88:89] op_sel_hi:[0,1]
	v_pk_mul_f32 v[52:53], v[36:37], v[72:73] op_sel_hi:[0,1]
	v_pk_mul_f32 v[52:53], v[12:13], v[52:53]
	v_pk_mul_f32 v[50:51], v[14:15], v[50:51]
	v_mul_f32_e32 v39, 0x4b800000, v38
	v_cmp_gt_f32_e32 vcc, s72, v38
	v_pk_fma_f32 v[50:51], v[40:41], v[50:51], v[10:11]
	v_pk_fma_f32 v[52:53], v[42:43], v[52:53], v[8:9]
	v_mov_b32_e32 v65, v162
	v_cndmask_b32_e32 v38, v38, v39, vcc
	v_cvt_pk_bf16_f32 v52, v52, v53
	v_cvt_pk_bf16_f32 v53, v50, v51
	v_pk_mul_f32 v[50:51], v[36:37], v[66:67] op_sel_hi:[0,1]
	v_pk_mul_f32 v[36:37], v[36:37], v[64:65] op_sel_hi:[0,1]
	v_rsq_f32_e32 v38, v38
	v_pk_mul_f32 v[36:37], v[0:1], v[36:37]
	v_pk_mul_f32 v[50:51], v[2:3], v[50:51]
	v_pk_fma_f32 v[36:37], v[34:35], v[36:37], v[4:5]
	v_pk_fma_f32 v[50:51], v[32:33], v[50:51], v[6:7]
	v_cvt_pk_bf16_f32 v36, v36, v37
	v_cvt_pk_bf16_f32 v37, v50, v51
	global_store_dwordx2 v[48:49], v[36:37], off offset:1536
	v_mul_f32_e32 v36, 0x45800000, v38
	v_cndmask_b32_e32 v36, v38, v36, vcc
	v_mov_b32_e32 v38, v75
	v_mov_b32_e32 v39, v79
	v_mov_b32_e32 v75, v78
	v_pk_mul_f32 v[38:39], v[36:37], v[38:39] op_sel_hi:[0,1]
	v_pk_mul_f32 v[50:51], v[36:37], v[74:75] op_sel_hi:[0,1]
	v_pk_mul_f32 v[28:29], v[28:29], v[50:51]
	v_pk_mul_f32 v[30:31], v[30:31], v[38:39]
	v_pk_fma_f32 v[24:25], v[140:141], v[28:29], v[24:25]
	v_pk_fma_f32 v[26:27], v[138:139], v[30:31], v[26:27]
	v_cvt_pk_bf16_f32 v24, v24, v25
	v_cvt_pk_bf16_f32 v25, v26, v27
	global_store_dwordx2 v[48:49], v[24:25], off offset:2048
	v_mov_b32_e32 v24, v61
	v_mov_b32_e32 v25, v63
	v_mov_b32_e32 v61, v62
	v_pk_mul_f32 v[24:25], v[36:37], v[24:25] op_sel_hi:[0,1]
	v_pk_mul_f32 v[26:27], v[36:37], v[60:61] op_sel_hi:[0,1]
	v_pk_mul_f32 v[16:17], v[16:17], v[26:27]
	v_pk_mul_f32 v[18:19], v[18:19], v[24:25]
	v_pk_fma_f32 v[16:17], v[44:45], v[16:17], v[20:21]
	v_pk_fma_f32 v[18:19], v[46:47], v[18:19], v[22:23]
	v_cvt_pk_bf16_f32 v16, v16, v17
	v_cvt_pk_bf16_f32 v17, v18, v19
	global_store_dwordx2 v[48:49], v[16:17], off offset:2560
	v_pk_mul_f32 v[16:17], v[36:37], v[130:131] op_sel_hi:[0,1]
	v_pk_mul_f32 v[18:19], v[36:37], v[54:55] op_sel_hi:[0,1]
	v_pk_mul_f32 v[12:13], v[12:13], v[18:19]
	v_pk_mul_f32 v[14:15], v[14:15], v[16:17]
	v_pk_fma_f32 v[8:9], v[42:43], v[12:13], v[8:9]
	v_pk_fma_f32 v[10:11], v[40:41], v[14:15], v[10:11]
	v_cvt_pk_bf16_f32 v8, v8, v9
	v_cvt_pk_bf16_f32 v9, v10, v11
	v_mov_b32_e32 v57, v156
	global_store_dwordx2 v[48:49], v[8:9], off offset:3072
	v_pk_mul_f32 v[8:9], v[36:37], v[58:59] op_sel_hi:[0,1]
	v_pk_mul_f32 v[10:11], v[36:37], v[56:57] op_sel_hi:[0,1]
	v_pk_mul_f32 v[0:1], v[0:1], v[10:11]
	v_pk_mul_f32 v[2:3], v[2:3], v[8:9]
	v_pk_fma_f32 v[0:1], v[34:35], v[0:1], v[4:5]
	v_pk_fma_f32 v[2:3], v[32:33], v[2:3], v[6:7]
	v_cvt_pk_bf16_f32 v0, v0, v1
	v_cvt_pk_bf16_f32 v1, v2, v3
	global_store_dwordx2 v[48:49], v[148:149], off offset:-4096
	global_store_dwordx2 v[48:49], v[52:53], off offset:1024
	global_store_dwordx2 v[48:49], v[0:1], off offset:3584
	s_cbranch_execnz .LBB0_1044
	s_branch .LBB0_1048
; __device__ __forceinline__ f32x4 unpack4(u32x2 w) { return (f32x4){bf_lo(w.x), bf_hi(w.x), bf_lo(w.y), bf_hi(w.y)}; }
; template <int NR, bool XIN16 = false, bool XOUT16 = false> ...
;     ...
;     for (int q = 0; q < NR; ++q) {
;         if (XIN16) { const u32x2* xr = (const u32x2*)((const bf16_t*)xin + (size_t)(row + q * rstride) * DM) + lane;
; #pragma unroll
;             for (int j = 0; j < 4; ++j) xv[q][j] = unpack4(xr[64 * j]); }
;         else { const f32x4* xr = (const f32x4*)(xin + (size_t)(row + q * rstride) * DM) + lane;
; #pragma unroll
;             for (int j = 0; j < 4; ++j) xv[q][j] = xr[64 * j]; } }
;     if (y) {
; #pragma unroll
;         for (int q = 0; q < NR; ++q) { const u32x2* yr = (const u32x2*)(y + (size_t)(row + q * rstride) * DM) + lane;
; #pragma unroll
;             for (int j = 0; j < 4; ++j) yv[q][j] = unpack4(yr[64 * j]); }
;         f32x4 g[4], gy[4];
; #pragma unroll
;         for (int j = 0; j < 4; ++j) { g[j] = ((const f32x4*)gate)[lane + 64 * j]; gy[j] = ((const f32x4*)gainY)[lane + 64 * j]; }
;         float ss[NR];
; #pragma unroll
;         for (int q = 0; q < NR; ++q) { ss[q] = 0.f;
; #pragma unroll
;             for (int j = 0; j < 4; ++j) ss[q] += (yv[q][j][0] * yv[q][j][0] + yv[q][j][1] * yv[q][j][1]) + (yv[q][j][2] * yv[q][j][2] + yv[q][j][3] * yv[q][j][3]); }
.LBB0_1047:
.LBB0_1048:
	v_add_co_u32_e32 v0, vcc, 0x1000, v122
	global_load_dwordx4 v[92:95], v[122:123], off
	global_load_dwordx4 v[88:91], v[122:123], off offset:1024
	global_load_dwordx4 v[84:87], v[122:123], off offset:2048
	global_load_dwordx4 v[80:83], v[122:123], off offset:3072
	v_addc_co_u32_e32 v1, vcc, 0, v123, vcc
	global_load_dwordx4 v[76:79], v[0:1], off
	global_load_dwordx4 v[72:75], v[0:1], off offset:1024
	global_load_dwordx4 v[68:71], v[0:1], off offset:2048
	global_load_dwordx4 v[64:67], v[0:1], off offset:3072
	v_add_co_u32_e32 v0, vcc, 0x2000, v122
	s_mov_b32 s0, 0x7401000
	s_nop 0
	v_addc_co_u32_e32 v1, vcc, 0, v123, vcc
	global_load_dwordx4 v[28:31], v[0:1], off
	global_load_dwordx4 v[24:27], v[0:1], off offset:1024
	global_load_dwordx4 v[20:23], v[0:1], off offset:2048
	global_load_dwordx4 v[16:19], v[0:1], off offset:3072
	v_add_co_u32_e32 v0, vcc, 0x3000, v122
	s_nop 1
	v_addc_co_u32_e32 v1, vcc, 0, v123, vcc
	v_add_co_u32_e32 v128, vcc, 0x2400000, v124
	global_load_dwordx4 v[12:15], v[0:1], off
	global_load_dwordx4 v[8:11], v[0:1], off offset:1024
	global_load_dwordx4 v[4:7], v[0:1], off offset:2048
	s_nop 0
	global_load_dwordx4 v[0:3], v[0:1], off offset:3072
	v_addc_co_u32_e32 v129, vcc, 0, v125, vcc
	global_load_dwordx2 v[176:177], v[128:129], off
	global_load_dwordx2 v[168:169], v[128:129], off offset:512
	global_load_dwordx2 v[164:165], v[128:129], off offset:1024
	global_load_dwordx2 v[32:33], v[128:129], off offset:1536
	v_add_co_u32_e32 v126, vcc, s29, v124
	s_waitcnt vmcnt(3)
	v_and_b32_e32 v211, 0xffff0000, v177
	v_addc_co_u32_e32 v127, vcc, 0, v125, vcc
	s_waitcnt vmcnt(0)
	v_lshlrev_b32_e32 v153, 16, v32
	v_and_b32_e32 v151, 0xffff0000, v32
	v_lshlrev_b32_e32 v154, 16, v33
	v_and_b32_e32 v155, 0xffff0000, v33
	global_load_dwordx2 v[158:159], v[128:129], off offset:2048
	global_load_dwordx2 v[156:157], v[128:129], off offset:2560
	global_load_dwordx2 v[130:131], v[128:129], off offset:3072
	global_load_dwordx2 v[32:33], v[128:129], off offset:3584
	v_and_b32_e32 v209, 0xffff0000, v176
	v_lshlrev_b32_e32 v210, 16, v177
	v_mul_f32_e32 v132, v211, v211
	v_lshlrev_b32_e32 v208, 16, v176
	v_and_b32_e32 v207, 0xffff0000, v169
	v_and_b32_e32 v206, 0xffff0000, v168
	v_lshlrev_b32_e32 v201, 16, v169
	v_lshlrev_b32_e32 v200, 16, v168
	v_pk_mul_f32 v[168:169], v[206:207], v[206:207]
	v_lshlrev_b32_e32 v202, 16, v164
	v_and_b32_e32 v203, 0xffff0000, v164
	v_lshlrev_b32_e32 v204, 16, v165
	v_and_b32_e32 v205, 0xffff0000, v165
	v_pk_fma_f32 v[168:169], v[200:201], v[200:201], v[168:169]
	v_mov_b32_e32 v179, v153
	v_mul_f32_e32 v134, v151, v151
	v_pk_add_f32 v[168:169], v[168:169], v[168:169] op_sel:[0,1] op_sel_hi:[1,0]
	v_mul_f32_e32 v138, v154, v154
	v_mov_b32_e32 v169, v134
	v_mul_f32_e32 v140, v155, v155
	v_mov_b32_e32 v150, v153
	s_waitcnt vmcnt(3)
	v_and_b32_e32 v193, 0xffff0000, v158
	v_and_b32_e32 v199, 0xffff0000, v159
	v_lshlrev_b32_e32 v192, 16, v158
	s_waitcnt vmcnt(0)
	v_lshlrev_b32_e32 v147, 16, v32
	v_and_b32_e32 v145, 0xffff0000, v32
	v_lshlrev_b32_e32 v148, 16, v33
	v_and_b32_e32 v149, 0xffff0000, v33
	global_load_dwordx2 v[170:171], v[126:127], off
	global_load_dwordx2 v[174:175], v[126:127], off offset:512
	global_load_dwordx2 v[172:173], v[126:127], off offset:1024
	global_load_dwordx2 v[32:33], v[126:127], off offset:1536
	v_lshlrev_b32_e32 v198, 16, v159
	v_and_b32_e32 v189, 0xffff0000, v157
	v_and_b32_e32 v188, 0xffff0000, v156
	v_lshlrev_b32_e32 v182, 16, v130
	v_and_b32_e32 v183, 0xffff0000, v130
	v_mul_f32_e32 v130, v193, v193
	v_lshlrev_b32_e32 v185, 16, v157
	v_lshlrev_b32_e32 v184, 16, v156
	v_pk_mul_f32 v[156:157], v[188:189], v[188:189]
	v_lshlrev_b32_e32 v190, 16, v131
	v_and_b32_e32 v191, 0xffff0000, v131
	v_pk_fma_f32 v[130:131], v[192:193], v[192:193], v[130:131] op_sel_hi:[1,1,0]
	v_pk_fma_f32 v[156:157], v[184:185], v[184:185], v[156:157]
	v_mov_b32_e32 v146, v130
	v_pk_add_f32 v[156:157], v[156:157], v[156:157] op_sel:[0,1] op_sel_hi:[1,0]
	v_mul_f32_e32 v134, v148, v148
	s_waitcnt vmcnt(0)
	v_lshlrev_b32_e32 v141, 16, v32
	v_and_b32_e32 v139, 0xffff0000, v32
	v_lshlrev_b32_e32 v142, 16, v33
	v_and_b32_e32 v143, 0xffff0000, v33
	global_load_dwordx2 v[166:167], v[126:127], off offset:2048
	global_load_dwordx2 v[162:163], v[126:127], off offset:2560
	global_load_dwordx2 v[160:161], v[126:127], off offset:3072
	global_load_dwordx2 v[32:33], v[126:127], off offset:3584
	v_mov_b32_e32 v181, v141
	v_mul_f32_e32 v144, v143, v143
	s_waitcnt vmcnt(0)
; template <int NR, bool XIN16 = false, bool XOUT16 = false> ...
;     ...
;         f32x4 g[4], gy[4];
; #pragma unroll
;         for (int j = 0; j < 4; ++j) { g[j] = ((const f32x4*)gate)[lane + 64 * j]; gy[j] = ((const f32x4*)gainY)[lane + 64 * j]; }
;         float ss[NR];
; #pragma unroll
;         for (int q = 0; q < NR; ++q) { ss[q] = 0.f;
; #pragma unroll
;             for (int j = 0; j < 4; ++j) ss[q] += (yv[q][j][0] * yv[q][j][0] + yv[q][j][1] * yv[q][j][1]) + (yv[q][j][2] * yv[q][j][2] + yv[q][j][3] * yv[q][j][3]); }
; #pragma unroll
;         for (int o = 1; o < 64; o <<= 1) {
; #pragma unroll
;             for (int q = 0; q < NR; ++q) ss[q] += __shfl_xor(ss[q], o); }
	v_and_b32_e32 v133, 0xffff0000, v32
	v_pk_fma_f32 v[176:177], v[210:211], v[210:211], v[132:133] op_sel_hi:[1,1,0]
	v_mul_f32_e32 v132, v209, v209
	v_pk_fma_f32 v[164:165], v[208:209], v[208:209], v[132:133] op_sel_hi:[1,1,0]
	v_mov_b32_e32 v178, v176
	v_mov_b32_e32 v152, v164
	v_pk_add_f32 v[164:165], v[164:165], v[176:177]
	v_pk_mul_f32 v[176:177], v[152:153], v[178:179]
	v_mul_f32_e32 v132, v203, v203
	v_mov_b32_e32 v165, v177
	v_pk_add_f32 v[164:165], v[164:165], v[168:169]
	v_pk_fma_f32 v[168:169], v[202:203], v[202:203], v[132:133] op_sel_hi:[1,1,0]
	v_mul_f32_e32 v132, v205, v205
	v_pk_fma_f32 v[176:177], v[204:205], v[204:205], v[132:133] op_sel_hi:[1,1,0]
	v_mov_b32_e32 v169, v138
	v_mov_b32_e32 v177, v140
	v_mul_f32_e32 v132, v199, v199
	v_pk_add_f32 v[168:169], v[168:169], v[176:177]
	v_pk_fma_f32 v[158:159], v[198:199], v[198:199], v[132:133] op_sel_hi:[1,1,0]
	v_lshlrev_b32_e32 v135, 16, v32
	v_lshlrev_b32_e32 v136, 16, v33
	v_and_b32_e32 v137, 0xffff0000, v33
	global_load_dwordx4 v[56:59], v109, s[20:21]
	global_load_dwordx4 v[60:63], v[98:99], off
	global_load_dwordx4 v[48:51], v105, s[20:21]
	global_load_dwordx4 v[52:55], v[102:103], off
	global_load_dwordx4 v[40:43], v101, s[20:21]
	global_load_dwordx4 v[44:47], v[106:107], off
	global_load_dwordx4 v[32:35], v97, s[20:21]
	global_load_dwordx4 v[36:39], v[110:111], off
	v_pk_add_f32 v[212:213], v[164:165], v[168:169]
	v_mov_b32_e32 v164, v158
	v_mov_b32_e32 v165, v147
	v_mul_f32_e32 v132, v145, v145
	v_pk_add_f32 v[130:131], v[130:131], v[158:159]
	v_pk_mul_f32 v[158:159], v[146:147], v[164:165]
	v_mov_b32_e32 v157, v132
	v_mov_b32_e32 v131, v159
	v_mul_f32_e32 v132, v183, v183
	v_pk_add_f32 v[130:131], v[130:131], v[156:157]
	v_pk_fma_f32 v[156:157], v[182:183], v[182:183], v[132:133] op_sel_hi:[1,1,0]
	v_mul_f32_e32 v132, v191, v191
	v_mul_f32_e32 v138, v149, v149
	v_pk_fma_f32 v[158:159], v[190:191], v[190:191], v[132:133] op_sel_hi:[1,1,0]
	v_mov_b32_e32 v157, v134
	v_mov_b32_e32 v159, v138
	v_and_b32_e32 v179, 0xffff0000, v171
	v_pk_add_f32 v[156:157], v[156:157], v[158:159]
	v_and_b32_e32 v177, 0xffff0000, v170
	v_lshlrev_b32_e32 v178, 16, v171
	v_mul_f32_e32 v132, v179, v179
	v_pk_add_f32 v[130:131], v[130:131], v[156:157]
	v_lshlrev_b32_e32 v176, 16, v170
	v_pk_fma_f32 v[156:157], v[178:179], v[178:179], v[132:133] op_sel_hi:[1,1,0]
	v_lshlrev_b32_e32 v171, 16, v175
	v_lshlrev_b32_e32 v170, 16, v174
	v_and_b32_e32 v175, 0xffff0000, v175
	v_and_b32_e32 v174, 0xffff0000, v174
	v_mul_f32_e32 v132, v177, v177
	v_pk_mul_f32 v[158:159], v[174:175], v[174:175]
	v_pk_fma_f32 v[164:165], v[176:177], v[176:177], v[132:133] op_sel_hi:[1,1,0]
	v_pk_fma_f32 v[158:159], v[170:171], v[170:171], v[158:159]
	v_mov_b32_e32 v140, v164
	v_mov_b32_e32 v180, v156
	v_and_b32_e32 v169, 0xffff0000, v172
	v_mul_f32_e32 v134, v139, v139
	v_pk_add_f32 v[156:157], v[164:165], v[156:157]
	v_pk_mul_f32 v[164:165], v[140:141], v[180:181]
	v_pk_add_f32 v[158:159], v[158:159], v[158:159] op_sel:[0,1] op_sel_hi:[1,0]
	v_lshlrev_b32_e32 v168, 16, v172
	v_lshlrev_b32_e32 v172, 16, v173
	v_and_b32_e32 v173, 0xffff0000, v173
	v_mov_b32_e32 v157, v165
	v_mov_b32_e32 v159, v134
	v_mul_f32_e32 v132, v169, v169
	v_pk_add_f32 v[156:157], v[156:157], v[158:159]
	v_pk_fma_f32 v[158:159], v[168:169], v[168:169], v[132:133] op_sel_hi:[1,1,0]
	v_mul_f32_e32 v132, v173, v173
	v_mul_f32_e32 v138, v142, v142
	v_pk_fma_f32 v[164:165], v[172:173], v[172:173], v[132:133] op_sel_hi:[1,1,0]
	v_mov_b32_e32 v159, v138
	v_mov_b32_e32 v165, v144
	v_pk_add_f32 v[158:159], v[158:159], v[164:165]
	v_lshlrev_b32_e32 v164, 16, v166
	v_and_b32_e32 v165, 0xffff0000, v166
	v_lshlrev_b32_e32 v166, 16, v167
	v_and_b32_e32 v167, 0xffff0000, v167
	v_mul_f32_e32 v132, v167, v167
	v_pk_add_f32 v[180:181], v[156:157], v[158:159]
	v_pk_fma_f32 v[186:187], v[166:167], v[166:167], v[132:133] op_sel_hi:[1,1,0]
	v_lshlrev_b32_e32 v159, 16, v163
	v_lshlrev_b32_e32 v158, 16, v162
	v_and_b32_e32 v163, 0xffff0000, v163
	v_and_b32_e32 v162, 0xffff0000, v162
	v_mul_f32_e32 v132, v165, v165
	v_pk_mul_f32 v[156:157], v[162:163], v[162:163]
	v_pk_fma_f32 v[216:217], v[164:165], v[164:165], v[132:133] op_sel_hi:[1,1,0]
	v_pk_fma_f32 v[214:215], v[158:159], v[158:159], v[156:157]
	v_mov_b32_e32 v134, v216
	v_mov_b32_e32 v218, v186
	v_mov_b32_e32 v219, v135
	v_and_b32_e32 v157, 0xffff0000, v160
	v_mul_f32_e32 v138, v133, v133
	v_pk_add_f32 v[186:187], v[216:217], v[186:187]
	v_pk_mul_f32 v[216:217], v[134:135], v[218:219]
	v_pk_add_f32 v[214:215], v[214:215], v[214:215] op_sel:[0,1] op_sel_hi:[1,0]
	v_lshlrev_b32_e32 v156, 16, v160
	v_lshlrev_b32_e32 v160, 16, v161
	v_and_b32_e32 v161, 0xffff0000, v161
	v_mov_b32_e32 v187, v217
	v_mov_b32_e32 v215, v138
	v_mul_f32_e32 v132, v157, v157
	v_pk_add_f32 v[186:187], v[186:187], v[214:215]
	v_pk_fma_f32 v[214:215], v[156:157], v[156:157], v[132:133] op_sel_hi:[1,1,0]
	v_mul_f32_e32 v132, v161, v161
	v_pk_fma_f32 v[216:217], v[160:161], v[160:161], v[132:133] op_sel_hi:[1,1,0]
	v_and_b32_e32 v132, 64, v240
	v_add_u32_e32 v132, 64, v132
	v_xor_b32_e32 v134, 1, v240
	v_cmp_lt_i32_e32 vcc, v134, v132
	v_mov_b32_e32 v220, v130
	v_mov_b32_e32 v221, v212
	v_cndmask_b32_e32 v134, v240, v134, vcc
	v_mov_b32_e32 v212, v131
	v_lshlrev_b32_e32 v219, 2, v134
	v_pk_add_f32 v[130:131], v[220:221], v[212:213]
	v_xor_b32_e32 v134, 2, v240
	v_cmp_lt_i32_e32 vcc, v134, v132
	v_mul_f32_e32 v140, v136, v136
	v_mul_f32_e32 v144, v137, v137
	v_cndmask_b32_e32 v134, v240, v134, vcc
	v_lshlrev_b32_e32 v218, 2, v134
	s_nop 1
	v_add_f32_dpp v130, v130, v130 quad_perm:[1,0,3,2] row_mask:0xf bank_mask:0xf
; __device__ __forceinline__ f32x4 unpack4(u32x2 w) { return (f32x4){bf_lo(w.x), bf_hi(w.x), bf_lo(w.y), bf_hi(w.y)}; }
; __device__ __forceinline__ u32x2 pack4(f32x4 v) { u32x2 w; w.x = pk2(v[0], v[1]); w.y = pk2(v[2], v[3]); return w; }
; template <int NR, bool XIN16 = false, bool XOUT16 = false> ...
;     ...
;         for (int o = 1; o < 64; o <<= 1) {
; #pragma unroll
;             for (int q = 0; q < NR; ++q) ss[q] += __shfl_xor(ss[q], o); }
; #pragma unroll
;         for (int q = 0; q < NR; ++q) { const float rstd = rsqrtf(ss[q] * (1.f / DM) + EPS);
;             if (XOUT16) { u32x2* xo = (u32x2*)((bf16_t*)xout + (size_t)(row + q * rstride) * DM) + lane;
; #pragma unroll
;                 for (int j = 0; j < 4; ++j) { xv[q][j] = xv[q][j] + g[j] * (yv[q][j] * rstd * gy[j]); xo[64 * j] = pack4(xv[q][j]); xv[q][j] = unpack4(pack4(xv[q][j])); } }
	v_add_f32_dpp v131, v131, v131 quad_perm:[1,0,3,2] row_mask:0xf bank_mask:0xf
	v_xor_b32_e32 v134, 4, v240
	v_cmp_lt_i32_e32 vcc, v134, v132
	v_mov_b32_e32 v215, v140
	v_mov_b32_e32 v217, v144
	v_cndmask_b32_e32 v134, v240, v134, vcc
	v_pk_add_f32 v[214:215], v[214:215], v[216:217]
	v_lshlrev_b32_e32 v217, 2, v134
	s_nop 1
	v_add_f32_dpp v130, v130, v130 quad_perm:[2,3,0,1] row_mask:0xf bank_mask:0xf
	v_add_f32_dpp v131, v131, v131 quad_perm:[2,3,0,1] row_mask:0xf bank_mask:0xf
	v_xor_b32_e32 v134, 8, v240
	v_cmp_lt_i32_e32 vcc, v134, v132
	v_pk_add_f32 v[186:187], v[186:187], v[214:215]
	v_mov_b32_e32 v144, v147
	v_cndmask_b32_e32 v134, v240, v134, vcc
	v_lshlrev_b32_e32 v216, 2, v134
	s_nop 1
	v_add_f32_dpp v130, v130, v130 row_half_mirror row_mask:0xf bank_mask:0xf
	v_add_f32_dpp v131, v131, v131 row_half_mirror row_mask:0xf bank_mask:0xf
	v_xor_b32_e32 v134, 16, v240
	v_cmp_lt_i32_e32 vcc, v134, v132
	v_mov_b32_e32 v138, v141
	s_nop 1
	v_add_f32_dpp v130, v130, v130 row_mirror row_mask:0xf bank_mask:0xf
	v_add_f32_dpp v131, v131, v131 row_mirror row_mask:0xf bank_mask:0xf
	v_cndmask_b32_e32 v134, v240, v134, vcc
	v_lshlrev_b32_e32 v215, 2, v134
	v_xor_b32_e32 v134, 32, v240
	v_cmp_lt_i32_e32 vcc, v134, v132
	s_nop 1
	v_readlane_b32 s98, v130, 0
	v_readlane_b32 s99, v130, 16
	v_readlane_b32 s100, v130, 32
	v_readlane_b32 s101, v130, 48
	s_nop 1
	v_mov_b32_e32 v228, s98
	v_add_f32_e32 v228, s99, v228
	v_mov_b32_e32 v229, s100
	v_add_f32_e32 v229, s101, v229
	v_add_f32_e32 v130, v228, v229
	v_readlane_b32 s98, v131, 0
	v_readlane_b32 s99, v131, 16
	v_readlane_b32 s100, v131, 32
	v_readlane_b32 s101, v131, 48
	s_nop 1
	v_mov_b32_e32 v228, s98
	v_add_f32_e32 v228, s99, v228
	v_mov_b32_e32 v229, s100
	v_add_f32_e32 v229, s101, v229
	v_add_f32_e32 v131, v228, v229
	v_cndmask_b32_e32 v132, v240, v134, vcc
	v_lshlrev_b32_e32 v214, 2, v132
	v_mov_b32_e32 v212, v130
	v_mov_b32_e32 v213, v131
	v_mov_b64_e32 v[130:131], s[36:37]
	v_pk_fma_f32 v[212:213], v[212:213], s[82:83], v[130:131] op_sel_hi:[1,0,0]
	s_nop 0
	v_mul_f32_e32 v132, 0x4b800000, v213
	v_cmp_gt_f32_e64 s[8:9], s72, v213
	v_cmp_gt_f32_e32 vcc, s72, v212
	s_nop 0
	v_cndmask_b32_e64 v132, v213, v132, s[8:9]
	v_rsq_f32_e32 v132, v132
	s_nop 0
	v_mul_f32_e32 v134, 0x45800000, v132
	v_cndmask_b32_e64 v132, v132, v134, s[8:9]
	v_pk_mul_f32 v[208:209], v[132:133], v[208:209] op_sel_hi:[0,1]
	v_pk_mul_f32 v[210:211], v[132:133], v[210:211] op_sel_hi:[0,1]
	s_waitcnt vmcnt(6)
	v_pk_mul_f32 v[208:209], v[60:61], v[208:209]
	v_pk_mul_f32 v[210:211], v[62:63], v[210:211]
	v_pk_fma_f32 v[92:93], v[56:57], v[208:209], v[92:93]
	v_add_co_u32_e64 v208, s[8:9], s84, v124
	v_pk_fma_f32 v[94:95], v[58:59], v[210:211], v[94:95]
	s_nop 0
	v_addc_co_u32_e64 v209, s[8:9], 0, v125, s[8:9]
	v_cvt_pk_bf16_f32 v92, v92, v93
	v_cvt_pk_bf16_f32 v93, v94, v95
	v_add_co_u32_e64 v94, s[8:9], s0, v124
	v_mov_b32_e32 v124, v201
	s_nop 0
	v_addc_co_u32_e64 v95, s[8:9], 0, v125, s[8:9]
	v_mov_b32_e32 v125, v207
	v_mov_b32_e32 v201, v206
	v_pk_mul_f32 v[124:125], v[132:133], v[124:125] op_sel_hi:[0,1]
	v_pk_mul_f32 v[200:201], v[132:133], v[200:201] op_sel_hi:[0,1]
	s_waitcnt vmcnt(4)
	v_pk_mul_f32 v[200:201], v[52:53], v[200:201]
	v_pk_mul_f32 v[124:125], v[54:55], v[124:125]
	v_pk_fma_f32 v[88:89], v[48:49], v[200:201], v[88:89]
	v_pk_fma_f32 v[90:91], v[50:51], v[124:125], v[90:91]
	v_cvt_pk_bf16_f32 v88, v88, v89
	v_cvt_pk_bf16_f32 v89, v90, v91
	v_pk_mul_f32 v[90:91], v[132:133], v[204:205] op_sel_hi:[0,1]
	v_pk_mul_f32 v[124:125], v[132:133], v[202:203] op_sel_hi:[0,1]
	s_waitcnt vmcnt(2)
	v_pk_mul_f32 v[124:125], v[44:45], v[124:125]
	v_pk_mul_f32 v[90:91], v[46:47], v[90:91]
	v_pk_fma_f32 v[84:85], v[40:41], v[124:125], v[84:85]
	v_pk_fma_f32 v[90:91], v[42:43], v[90:91], v[86:87]
	v_pk_mul_f32 v[124:125], v[132:133], v[150:151] op_sel_hi:[0,1]
	v_cvt_pk_bf16_f32 v87, v90, v91
	v_pk_mul_f32 v[90:91], v[132:133], v[154:155] op_sel_hi:[0,1]
	s_waitcnt vmcnt(0)
	v_pk_mul_f32 v[124:125], v[36:37], v[124:125]
	v_pk_mul_f32 v[90:91], v[38:39], v[90:91]
	v_pk_fma_f32 v[80:81], v[32:33], v[124:125], v[80:81]
	v_pk_fma_f32 v[82:83], v[34:35], v[90:91], v[82:83]
	v_cvt_pk_bf16_f32 v90, v80, v81
	v_mul_f32_e32 v81, 0x4b800000, v212
	v_cndmask_b32_e32 v81, v212, v81, vcc
	v_rsq_f32_e32 v81, v81
	v_cvt_pk_bf16_f32 v86, v84, v85
	global_store_dwordx2 v[208:209], v[86:87], off offset:1024
	v_lshlrev_b32_e32 v84, 16, v86
	v_and_b32_e32 v85, 0xffff0000, v86
	v_mul_f32_e32 v86, 0x45800000, v81
	v_cvt_pk_bf16_f32 v91, v82, v83
	v_cndmask_b32_e32 v86, v81, v86, vcc
	global_store_dwordx2 v[208:209], v[90:91], off offset:1536
	v_lshlrev_b32_e32 v80, 16, v90
	v_and_b32_e32 v200, 0xffff0000, v90
	v_lshlrev_b32_e32 v82, 16, v91
	v_and_b32_e32 v83, 0xffff0000, v91
	v_pk_mul_f32 v[90:91], v[86:87], v[198:199] op_sel_hi:[0,1]
	v_pk_mul_f32 v[124:125], v[86:87], v[192:193] op_sel_hi:[0,1]
	v_pk_mul_f32 v[124:125], v[60:61], v[124:125]
	v_pk_mul_f32 v[90:91], v[62:63], v[90:91]
	v_pk_fma_f32 v[76:77], v[56:57], v[124:125], v[76:77]
	v_pk_fma_f32 v[78:79], v[58:59], v[90:91], v[78:79]
	v_cvt_pk_bf16_f32 v76, v76, v77
	v_cvt_pk_bf16_f32 v77, v78, v79
	v_mov_b32_e32 v78, v185
	v_mov_b32_e32 v185, v188
	v_mov_b32_e32 v79, v189
	v_pk_mul_f32 v[90:91], v[86:87], v[184:185] op_sel_hi:[0,1]
	v_pk_mul_f32 v[78:79], v[86:87], v[78:79] op_sel_hi:[0,1]
	v_pk_mul_f32 v[90:91], v[52:53], v[90:91]
	v_pk_mul_f32 v[78:79], v[54:55], v[78:79]
	v_pk_fma_f32 v[72:73], v[48:49], v[90:91], v[72:73]
	v_pk_fma_f32 v[74:75], v[50:51], v[78:79], v[74:75]
	v_cvt_pk_bf16_f32 v78, v72, v73
	v_pk_mul_f32 v[72:73], v[86:87], v[190:191] op_sel_hi:[0,1]
; __device__ __forceinline__ f32x4 unpack4(u32x2 w) { return (f32x4){bf_lo(w.x), bf_hi(w.x), bf_lo(w.y), bf_hi(w.y)}; }
; __device__ __forceinline__ u32x2 pack4(f32x4 v) { u32x2 w; w.x = pk2(v[0], v[1]); w.y = pk2(v[2], v[3]); return w; }
; template <int NR, bool XIN16 = false, bool XOUT16 = false> ...
;     ...
;         for (int o = 1; o < 64; o <<= 1) {
; #pragma unroll
;             for (int q = 0; q < NR; ++q) ss[q] += __shfl_xor(ss[q], o); }
; #pragma unroll
;         for (int q = 0; q < NR; ++q) { const float rstd = rsqrtf(ss[q] * (1.f / DM) + EPS);
;             if (XOUT16) { u32x2* xo = (u32x2*)((bf16_t*)xout + (size_t)(row + q * rstride) * DM) + lane;
; #pragma unroll
;                 for (int j = 0; j < 4; ++j) { xv[q][j] = xv[q][j] + g[j] * (yv[q][j] * rstd * gy[j]); xo[64 * j] = pack4(xv[q][j]); xv[q][j] = unpack4(pack4(xv[q][j])); } }
	v_cvt_pk_bf16_f32 v79, v74, v75
	v_pk_mul_f32 v[74:75], v[86:87], v[182:183] op_sel_hi:[0,1]
	v_pk_mul_f32 v[72:73], v[46:47], v[72:73]
	v_pk_mul_f32 v[74:75], v[44:45], v[74:75]
	v_pk_fma_f32 v[70:71], v[42:43], v[72:73], v[70:71]
	v_pk_fma_f32 v[68:69], v[40:41], v[74:75], v[68:69]
	v_cvt_pk_bf16_f32 v73, v70, v71
	v_pk_mul_f32 v[70:71], v[86:87], v[148:149] op_sel_hi:[0,1]
	v_pk_mul_f32 v[74:75], v[86:87], v[144:145] op_sel_hi:[0,1]
	v_pk_mul_f32 v[74:75], v[36:37], v[74:75]
	v_pk_mul_f32 v[70:71], v[38:39], v[70:71]
	v_pk_fma_f32 v[64:65], v[32:33], v[74:75], v[64:65]
	v_pk_fma_f32 v[66:67], v[34:35], v[70:71], v[66:67]
	v_cvt_pk_bf16_f32 v70, v64, v65
	v_cvt_pk_bf16_f32 v71, v66, v67
	global_store_dwordx2 v[208:209], v[70:71], off offset:3584
	v_lshlrev_b32_e32 v64, 16, v70
	v_and_b32_e32 v182, 0xffff0000, v70
	v_lshlrev_b32_e32 v66, 16, v71
	v_and_b32_e32 v67, 0xffff0000, v71
	v_mov_b32_e32 v70, v186
	v_mov_b32_e32 v71, v180
	v_mov_b32_e32 v180, v187
	v_pk_add_f32 v[70:71], v[70:71], v[180:181]
	v_cvt_pk_bf16_f32 v72, v68, v69
	global_store_dwordx2 v[208:209], v[72:73], off offset:3072
	v_lshlrev_b32_e32 v68, 16, v72
	v_and_b32_e32 v69, 0xffff0000, v72
	s_nop 1
	v_add_f32_dpp v70, v70, v70 quad_perm:[1,0,3,2] row_mask:0xf bank_mask:0xf
	v_add_f32_dpp v71, v71, v71 quad_perm:[1,0,3,2] row_mask:0xf bank_mask:0xf
	v_mov_b32_e32 v132, v135
	global_store_dwordx2 v[94:95], v[92:93], off offset:-4096
	global_store_dwordx2 v[208:209], v[88:89], off offset:512
	global_store_dwordx2 v[208:209], v[76:77], off offset:2048
	s_nop 1
	v_add_f32_dpp v70, v70, v70 quad_perm:[2,3,0,1] row_mask:0xf bank_mask:0xf
	v_add_f32_dpp v71, v71, v71 quad_perm:[2,3,0,1] row_mask:0xf bank_mask:0xf
	global_store_dwordx2 v[208:209], v[78:79], off offset:2560
	v_and_b32_e32 v149, 0xffff0000, v93
	v_and_b32_e32 v148, 0xffff0000, v92
	v_and_b32_e32 v145, 0xffff0000, v89
	s_nop 1
	v_add_f32_dpp v70, v70, v70 row_half_mirror row_mask:0xf bank_mask:0xf
	v_add_f32_dpp v71, v71, v71 row_half_mirror row_mask:0xf bank_mask:0xf
	v_and_b32_e32 v144, 0xffff0000, v88
	v_lshlrev_b32_e32 v147, 16, v93
	v_lshlrev_b32_e32 v146, 16, v92
	v_lshlrev_b32_e32 v140, 16, v87
	s_nop 1
	v_add_f32_dpp v70, v70, v70 row_mirror row_mask:0xf bank_mask:0xf
	v_add_f32_dpp v71, v71, v71 row_mirror row_mask:0xf bank_mask:0xf
	v_mul_f32_e32 v81, v84, v84
	v_and_b32_e32 v141, 0xffff0000, v87
	v_lshlrev_b32_e32 v135, 16, v77
	v_lshlrev_b32_e32 v134, 16, v76
	s_nop 1
	v_readlane_b32 s98, v70, 0
	v_readlane_b32 s99, v70, 16
	v_readlane_b32 s100, v70, 32
	v_readlane_b32 s101, v70, 48
	s_nop 1
	v_mov_b32_e32 v228, s98
	v_add_f32_e32 v228, s99, v228
	v_mov_b32_e32 v229, s100
	v_add_f32_e32 v229, s101, v229
	v_add_f32_e32 v70, v228, v229
	v_readlane_b32 s98, v71, 0
	v_readlane_b32 s99, v71, 16
	v_readlane_b32 s100, v71, 32
	v_readlane_b32 s101, v71, 48
	s_nop 1
	v_mov_b32_e32 v228, s98
	v_add_f32_e32 v228, s99, v228
	v_mov_b32_e32 v229, s100
	v_add_f32_e32 v229, s101, v229
	v_add_f32_e32 v71, v228, v229
	s_nop 0
	v_pk_fma_f32 v[124:125], v[70:71], s[82:83], v[130:131] op_sel_hi:[1,0,0]
	s_nop 0
	v_mul_f32_e32 v65, 0x4b800000, v125
	v_cmp_gt_f32_e64 s[8:9], s72, v125
	v_cmp_gt_f32_e32 vcc, s72, v124
	s_nop 0
	v_cndmask_b32_e64 v65, v125, v65, s[8:9]
	v_rsq_f32_e32 v65, v65
	v_lshlrev_b32_e32 v125, 16, v79
	v_mul_f32_e32 v70, 0x45800000, v65
	v_cndmask_b32_e64 v72, v65, v70, s[8:9]
	v_pk_mul_f32 v[74:75], v[72:73], v[176:177] op_sel_hi:[0,1]
	v_pk_mul_f32 v[70:71], v[72:73], v[178:179] op_sel_hi:[0,1]
	v_pk_mul_f32 v[74:75], v[60:61], v[74:75]
	v_pk_mul_f32 v[70:71], v[62:63], v[70:71]
	v_pk_fma_f32 v[28:29], v[56:57], v[74:75], v[28:29]
	v_pk_fma_f32 v[30:31], v[58:59], v[70:71], v[30:31]
	v_cvt_pk_bf16_f32 v90, v28, v29
	v_mov_b32_e32 v28, v171
	v_mov_b32_e32 v29, v175
	v_mov_b32_e32 v171, v174
	v_cvt_pk_bf16_f32 v91, v30, v31
	v_pk_mul_f32 v[28:29], v[72:73], v[28:29] op_sel_hi:[0,1]
	v_pk_mul_f32 v[30:31], v[72:73], v[170:171] op_sel_hi:[0,1]
	v_pk_mul_f32 v[30:31], v[52:53], v[30:31]
	v_pk_mul_f32 v[28:29], v[54:55], v[28:29]
	v_pk_fma_f32 v[24:25], v[48:49], v[30:31], v[24:25]
	v_pk_fma_f32 v[26:27], v[50:51], v[28:29], v[26:27]
	v_cvt_pk_bf16_f32 v152, v24, v25
	v_cvt_pk_bf16_f32 v153, v26, v27
	v_pk_mul_f32 v[24:25], v[72:73], v[172:173] op_sel_hi:[0,1]
	v_pk_mul_f32 v[26:27], v[72:73], v[168:169] op_sel_hi:[0,1]
	v_pk_mul_f32 v[26:27], v[44:45], v[26:27]
	v_pk_mul_f32 v[24:25], v[46:47], v[24:25]
	v_pk_fma_f32 v[20:21], v[40:41], v[26:27], v[20:21]
	v_pk_fma_f32 v[22:23], v[42:43], v[24:25], v[22:23]
	v_cvt_pk_bf16_f32 v154, v20, v21
	v_cvt_pk_bf16_f32 v155, v22, v23
	v_pk_mul_f32 v[20:21], v[72:73], v[142:143] op_sel_hi:[0,1]
	v_pk_mul_f32 v[22:23], v[72:73], v[138:139] op_sel_hi:[0,1]
	v_pk_mul_f32 v[22:23], v[36:37], v[22:23]
	v_pk_mul_f32 v[20:21], v[38:39], v[20:21]
	v_pk_fma_f32 v[16:17], v[32:33], v[22:23], v[16:17]
	v_pk_fma_f32 v[18:19], v[34:35], v[20:21], v[18:19]
	v_cvt_pk_bf16_f32 v16, v16, v17
	v_cvt_pk_bf16_f32 v17, v18, v19
	global_store_dwordx2 v[94:95], v[154:155], off offset:1024
	v_lshlrev_b32_e32 v70, 16, v154
	v_and_b32_e32 v71, 0xffff0000, v154
	global_store_dwordx2 v[94:95], v[16:17], off offset:1536
	v_lshlrev_b32_e32 v72, 16, v16
	v_and_b32_e32 v154, 0xffff0000, v16
	v_mul_f32_e32 v16, 0x4b800000, v124
	v_cndmask_b32_e32 v16, v124, v16, vcc
	v_rsq_f32_e32 v16, v16
	v_lshlrev_b32_e32 v74, 16, v17
	v_and_b32_e32 v75, 0xffff0000, v17
	global_store_dwordx2 v[94:95], v[90:91], off
	v_mul_f32_e32 v17, 0x45800000, v16
	v_cndmask_b32_e32 v16, v16, v17, vcc
	v_pk_mul_f32 v[20:21], v[16:17], v[164:165] op_sel_hi:[0,1]
	v_pk_mul_f32 v[18:19], v[16:17], v[166:167] op_sel_hi:[0,1]
; __device__ __forceinline__ f32x4 unpack4(u32x2 w) { return (f32x4){bf_lo(w.x), bf_hi(w.x), bf_lo(w.y), bf_hi(w.y)}; }
; __device__ __forceinline__ u32x2 pack4(f32x4 v) { u32x2 w; w.x = pk2(v[0], v[1]); w.y = pk2(v[2], v[3]); return w; }
; template <int NR, bool XIN16 = false, bool XOUT16 = false> ...
;     ...
;             if (XOUT16) { u32x2* xo = (u32x2*)((bf16_t*)xout + (size_t)(row + q * rstride) * DM) + lane;
; #pragma unroll
;                 for (int j = 0; j < 4; ++j) { xv[q][j] = xv[q][j] + g[j] * (yv[q][j] * rstd * gy[j]); xo[64 * j] = pack4(xv[q][j]); xv[q][j] = unpack4(pack4(xv[q][j])); } }
;             else { f32x4* xo = (f32x4*)(xout + (size_t)(row + q * rstride) * DM) + lane;
; #pragma unroll
;                 for (int j = 0; j < 4; ++j) { xv[q][j] = xv[q][j] + g[j] * (yv[q][j] * rstd * gy[j]); xo[64 * j] = xv[q][j]; } } }
;     }
;     if (hout) {
;         f32x4 gh[4], s1[4], s0[4];
; #pragma unroll
;         for (int j = 0; j < 4; ++j) { gh[j] = ((const f32x4*)gainH)[lane + 64 * j]; s1[j] = ((const f32x4*)sc)[lane + 64 * j]; s0[j] = ((const f32x4*)sh)[lane + 64 * j]; }
;         float ss[NR];
; #pragma unroll
;         for (int q = 0; q < NR; ++q) { ss[q] = 0.f;
; #pragma unroll
;             for (int j = 0; j < 4; ++j) ss[q] += (xv[q][j][0] * xv[q][j][0] + xv[q][j][1] * xv[q][j][1]) + (xv[q][j][2] * xv[q][j][2] + xv[q][j][3] * xv[q][j][3]); }
	v_pk_mul_f32 v[20:21], v[60:61], v[20:21]
	v_pk_mul_f32 v[18:19], v[62:63], v[18:19]
	v_pk_fma_f32 v[12:13], v[56:57], v[20:21], v[12:13]
	v_pk_fma_f32 v[14:15], v[58:59], v[18:19], v[14:15]
	v_cvt_pk_bf16_f32 v56, v12, v13
	v_mov_b32_e32 v12, v159
	v_mov_b32_e32 v13, v163
	v_mov_b32_e32 v159, v162
	v_cvt_pk_bf16_f32 v57, v14, v15
	v_pk_mul_f32 v[12:13], v[16:17], v[12:13] op_sel_hi:[0,1]
	v_pk_mul_f32 v[14:15], v[16:17], v[158:159] op_sel_hi:[0,1]
	v_pk_mul_f32 v[14:15], v[52:53], v[14:15]
	v_pk_mul_f32 v[12:13], v[54:55], v[12:13]
	v_pk_fma_f32 v[8:9], v[48:49], v[14:15], v[8:9]
	v_pk_fma_f32 v[10:11], v[50:51], v[12:13], v[10:11]
	v_cvt_pk_bf16_f32 v58, v8, v9
	v_cvt_pk_bf16_f32 v59, v10, v11
	v_pk_mul_f32 v[8:9], v[16:17], v[160:161] op_sel_hi:[0,1]
	v_pk_mul_f32 v[10:11], v[16:17], v[156:157] op_sel_hi:[0,1]
	v_pk_mul_f32 v[10:11], v[44:45], v[10:11]
	v_pk_mul_f32 v[8:9], v[46:47], v[8:9]
	v_pk_fma_f32 v[4:5], v[40:41], v[10:11], v[4:5]
	v_pk_fma_f32 v[6:7], v[42:43], v[8:9], v[6:7]
	v_cvt_pk_bf16_f32 v42, v4, v5
	v_cvt_pk_bf16_f32 v43, v6, v7
	v_pk_mul_f32 v[4:5], v[16:17], v[136:137] op_sel_hi:[0,1]
	v_pk_mul_f32 v[6:7], v[16:17], v[132:133] op_sel_hi:[0,1]
	v_pk_mul_f32 v[6:7], v[36:37], v[6:7]
	v_pk_mul_f32 v[4:5], v[38:39], v[4:5]
	v_pk_fma_f32 v[0:1], v[32:33], v[6:7], v[0:1]
	v_pk_fma_f32 v[2:3], v[34:35], v[4:5], v[2:3]
	v_cvt_pk_bf16_f32 v0, v0, v1
	v_cvt_pk_bf16_f32 v1, v2, v3
	global_store_dwordx2 v[94:95], v[152:153], off offset:512
	global_store_dwordx2 v[94:95], v[56:57], off offset:2048
	global_store_dwordx2 v[94:95], v[58:59], off offset:2560
	global_store_dwordx2 v[94:95], v[42:43], off offset:3072
	global_store_dwordx2 v[94:95], v[0:1], off offset:3584
	v_lshlrev_b32_e32 v32, 16, v0
	v_and_b32_e32 v156, 0xffff0000, v0
	v_lshlrev_b32_e32 v34, 16, v1
	v_and_b32_e32 v35, 0xffff0000, v1
	global_load_dwordx4 v[24:27], v[114:115], off
	global_load_dwordx4 v[36:39], v109, s[6:7]
	global_load_dwordx4 v[28:31], v109, s[18:19]
	global_load_dwordx4 v[16:19], v[116:117], off
	global_load_dwordx4 v[52:55], v105, s[6:7]
	global_load_dwordx4 v[20:23], v105, s[18:19]
	global_load_dwordx4 v[8:11], v[118:119], off
	global_load_dwordx4 v[158:161], v101, s[6:7]
	global_load_dwordx4 v[12:15], v101, s[18:19]
	global_load_dwordx4 v[0:3], v[120:121], off
	global_load_dwordx4 v[162:165], v97, s[6:7]
	global_load_dwordx4 v[4:7], v97, s[18:19]
	v_pk_mul_f32 v[44:45], v[148:149], v[148:149]
	v_lshlrev_b32_e32 v143, 16, v89
	v_lshlrev_b32_e32 v142, 16, v88
	v_pk_mul_f32 v[46:47], v[144:145], v[144:145]
	v_lshlrev_b32_e32 v40, 16, v42
	v_and_b32_e32 v41, 0xffff0000, v42
	v_pk_fma_f32 v[44:45], v[146:147], v[146:147], v[44:45]
	v_pk_fma_f32 v[46:47], v[142:143], v[142:143], v[46:47]
	v_mul_f32_e32 v49, v85, v85
	v_mul_f32_e32 v42, v140, v140
	v_mov_b32_e32 v48, v80
	v_pk_add_f32 v[44:45], v[44:45], v[44:45] op_sel_hi:[0,1]
	v_pk_add_f32 v[46:47], v[46:47], v[46:47] op_sel_hi:[0,1]
	v_pk_fma_f32 v[50:51], v[140:141], v[140:141], v[42:43] op_sel_hi:[1,1,0]
	v_pk_add_f32 v[48:49], v[80:81], v[48:49]
	v_mul_f32_e32 v50, v200, v200
	v_mul_f32_e32 v44, v82, v82
	v_mul_f32_e32 v46, v83, v83
	v_mul_f32_e32 v60, v80, v80
	v_mov_b32_e32 v61, v49
	v_pk_add_f32 v[48:49], v[60:61], v[50:51]
	v_pk_add_f32 v[44:45], v[44:45], v[46:47]
	v_and_b32_e32 v139, 0xffff0000, v77
	v_and_b32_e32 v138, 0xffff0000, v76
	v_and_b32_e32 v133, 0xffff0000, v79
	v_and_b32_e32 v132, 0xffff0000, v78
	v_pk_add_f32 v[150:151], v[48:49], v[44:45]
	v_pk_mul_f32 v[44:45], v[138:139], v[138:139]
	v_lshlrev_b32_e32 v124, 16, v78
	v_pk_mul_f32 v[46:47], v[132:133], v[132:133]
	v_lshlrev_b32_e32 v136, 16, v73
	v_pk_fma_f32 v[44:45], v[134:135], v[134:135], v[44:45]
	v_pk_fma_f32 v[46:47], v[124:125], v[124:125], v[46:47]
	v_mul_f32_e32 v65, v68, v68
	v_mul_f32_e32 v49, v69, v69
	v_and_b32_e32 v137, 0xffff0000, v73
	v_mul_f32_e32 v42, v136, v136
	v_mov_b32_e32 v48, v64
	v_pk_add_f32 v[44:45], v[44:45], v[44:45] op_sel_hi:[0,1]
	v_pk_add_f32 v[46:47], v[46:47], v[46:47] op_sel_hi:[0,1]
	v_pk_fma_f32 v[50:51], v[136:137], v[136:137], v[42:43] op_sel_hi:[1,1,0]
	v_pk_add_f32 v[48:49], v[64:65], v[48:49]
	v_mul_f32_e32 v50, v182, v182
	v_mul_f32_e32 v44, v66, v66
	v_mul_f32_e32 v46, v67, v67
	v_mul_f32_e32 v60, v64, v64
	v_mov_b32_e32 v61, v49
	v_pk_add_f32 v[48:49], v[60:61], v[50:51]
	v_pk_add_f32 v[44:45], v[44:45], v[46:47]
	v_lshlrev_b32_e32 v77, 16, v153
	v_pk_add_f32 v[166:167], v[48:49], v[44:45]
	v_lshlrev_b32_e32 v76, 16, v152
	v_and_b32_e32 v79, 0xffff0000, v153
	v_and_b32_e32 v78, 0xffff0000, v152
	v_mov_b32_e32 v152, v166
	v_mov_b32_e32 v153, v150
	v_mov_b32_e32 v150, v167
	v_pk_add_f32 v[150:151], v[152:153], v[150:151]
	v_lshlrev_b32_e32 v86, 16, v155
	v_mul_f32_e32 v73, v70, v70
	v_mul_f32_e32 v49, v71, v71
	v_and_b32_e32 v87, 0xffff0000, v155
	s_nop 1
	v_add_f32_dpp v150, v150, v150 quad_perm:[1,0,3,2] row_mask:0xf bank_mask:0xf
	v_add_f32_dpp v151, v151, v151 quad_perm:[1,0,3,2] row_mask:0xf bank_mask:0xf
	v_mul_f32_e32 v42, v86, v86
	v_mov_b32_e32 v48, v72
	v_pk_fma_f32 v[50:51], v[86:87], v[86:87], v[42:43] op_sel_hi:[1,1,0]
	v_pk_add_f32 v[48:49], v[72:73], v[48:49]
	s_nop 1
	v_add_f32_dpp v150, v150, v150 quad_perm:[2,3,0,1] row_mask:0xf bank_mask:0xf
	v_add_f32_dpp v151, v151, v151 quad_perm:[2,3,0,1] row_mask:0xf bank_mask:0xf
	v_lshlrev_b32_e32 v89, 16, v91
	v_lshlrev_b32_e32 v88, 16, v90
	v_and_b32_e32 v91, 0xffff0000, v91
	v_and_b32_e32 v90, 0xffff0000, v90
	s_nop 1
	v_add_f32_dpp v150, v150, v150 row_half_mirror row_mask:0xf bank_mask:0xf
	v_add_f32_dpp v151, v151, v151 row_half_mirror row_mask:0xf bank_mask:0xf
	v_mul_f32_e32 v50, v154, v154
	v_mul_f32_e32 v60, v72, v72
; __device__ __forceinline__ u32x2 pack4(f32x4 v) { u32x2 w; w.x = pk2(v[0], v[1]); w.y = pk2(v[2], v[3]); return w; }
; template <int NR, bool XIN16 = false, bool XOUT16 = false> ...
;     ...
;         float ss[NR];
; #pragma unroll
;         for (int q = 0; q < NR; ++q) { ss[q] = 0.f;
; #pragma unroll
;             for (int j = 0; j < 4; ++j) ss[q] += (xv[q][j][0] * xv[q][j][0] + xv[q][j][1] * xv[q][j][1]) + (xv[q][j][2] * xv[q][j][2] + xv[q][j][3] * xv[q][j][3]); }
; #pragma unroll
;         for (int o = 1; o < 64; o <<= 1) {
; #pragma unroll
;             for (int q = 0; q < NR; ++q) ss[q] += __shfl_xor(ss[q], o); }
; #pragma unroll
;         for (int q = 0; q < NR; ++q) { const float rstd = rsqrtf(ss[q] * (1.f / DM) + EPS);
;             u32x2* ho = (u32x2*)(hout + (size_t)(row + q * rstride) * DM) + lane;
; #pragma unroll
;             for (int j = 0; j < 4; ++j) { const f32x4 hv = (xv[q][j] * rstd * gh[j]) * (1.f + s1[j]) + s0[j]; ho[64 * j] = pack4(hv); } }
	v_mov_b32_e32 v61, v49
	v_pk_mul_f32 v[44:45], v[90:91], v[90:91]
	s_nop 1
	v_add_f32_dpp v150, v150, v150 row_mirror row_mask:0xf bank_mask:0xf
	v_add_f32_dpp v151, v151, v151 row_mirror row_mask:0xf bank_mask:0xf
	v_pk_mul_f32 v[46:47], v[78:79], v[78:79]
	v_pk_add_f32 v[48:49], v[60:61], v[50:51]
	v_mul_f32_e32 v33, v40, v40
	v_mul_f32_e32 v61, v41, v41
	s_nop 1
	v_readlane_b32 s98, v150, 0
	v_readlane_b32 s99, v150, 16
	v_readlane_b32 s100, v150, 32
	v_readlane_b32 s101, v150, 48
	s_nop 1
	v_mov_b32_e32 v228, s98
	v_add_f32_e32 v228, s99, v228
	v_mov_b32_e32 v229, s100
	v_add_f32_e32 v229, s101, v229
	v_add_f32_e32 v150, v228, v229
	v_readlane_b32 s98, v151, 0
	v_readlane_b32 s99, v151, 16
	v_readlane_b32 s100, v151, 32
	v_readlane_b32 s101, v151, 48
	s_nop 1
	v_mov_b32_e32 v228, s98
	v_add_f32_e32 v228, s99, v228
	v_mov_b32_e32 v229, s100
	v_add_f32_e32 v229, s101, v229
	v_add_f32_e32 v151, v228, v229
	v_mov_b32_e32 v60, v32
	v_pk_fma_f32 v[44:45], v[88:89], v[88:89], v[44:45]
	v_pk_fma_f32 v[46:47], v[76:77], v[76:77], v[46:47]
	v_pk_add_f32 v[60:61], v[32:33], v[60:61]
	v_pk_add_f32 v[44:45], v[44:45], v[44:45] op_sel_hi:[0,1]
	v_pk_fma_f32 v[150:151], v[150:151], s[82:83], v[130:131] op_sel_hi:[1,0,0]
	v_pk_add_f32 v[46:47], v[46:47], v[46:47] op_sel_hi:[0,1]
	v_mul_f32_e32 v33, 0x4b800000, v151
	v_cmp_gt_f32_e64 s[8:9], s72, v151
	v_mul_f32_e32 v44, v74, v74
	v_mul_f32_e32 v46, v75, v75
	v_cndmask_b32_e64 v33, v151, v33, s[8:9]
	v_rsq_f32_e32 v33, v33
	v_pk_add_f32 v[44:45], v[44:45], v[46:47]
	v_and_b32_e32 v51, 0xffff0000, v57
	v_and_b32_e32 v50, 0xffff0000, v56
	v_pk_add_f32 v[92:93], v[48:49], v[44:45]
	v_lshlrev_b32_e32 v49, 16, v57
	v_lshlrev_b32_e32 v48, 16, v56
	v_pk_mul_f32 v[44:45], v[50:51], v[50:51]
	v_and_b32_e32 v47, 0xffff0000, v59
	v_pk_fma_f32 v[44:45], v[48:49], v[48:49], v[44:45]
	v_and_b32_e32 v46, 0xffff0000, v58
	v_pk_add_f32 v[56:57], v[44:45], v[44:45] op_sel_hi:[0,1]
	v_lshlrev_b32_e32 v45, 16, v59
	v_lshlrev_b32_e32 v44, 16, v58
	v_pk_mul_f32 v[58:59], v[46:47], v[46:47]
	v_lshlrev_b32_e32 v42, 16, v43
	v_mul_f32_e32 v65, 0x45800000, v33
	v_pk_fma_f32 v[58:59], v[44:45], v[44:45], v[58:59]
	v_and_b32_e32 v43, 0xffff0000, v43
	v_mul_f32_e32 v56, v42, v42
	v_cmp_gt_f32_e32 vcc, s72, v150
	v_cndmask_b32_e64 v152, v33, v65, s[8:9]
	v_mul_f32_e32 v33, 0x4b800000, v150
	v_pk_add_f32 v[58:59], v[58:59], v[58:59] op_sel_hi:[0,1]
	v_pk_fma_f32 v[62:63], v[42:43], v[42:43], v[56:57] op_sel_hi:[1,1,0]
	v_cndmask_b32_e32 v33, v150, v33, vcc
	v_mul_f32_e32 v62, v156, v156
	v_mul_f32_e32 v56, v34, v34
	v_mul_f32_e32 v58, v35, v35
	v_mul_f32_e32 v94, v32, v32
	v_mov_b32_e32 v95, v61
	v_mov_b32_e32 v81, v200
	v_rsq_f32_e32 v33, v33
	v_pk_add_f32 v[60:61], v[94:95], v[62:63]
	v_pk_add_f32 v[56:57], v[56:57], v[58:59]
	v_pk_mul_f32 v[82:83], v[152:153], v[82:83] op_sel_hi:[0,1]
	v_pk_mul_f32 v[80:81], v[152:153], v[80:81] op_sel_hi:[0,1]
	v_pk_add_f32 v[94:95], v[60:61], v[56:57]
	s_waitcnt vmcnt(10)
	v_pk_add_f32 v[60:61], v[38:39], 1.0 op_sel_hi:[1,0]
	v_pk_add_f32 v[62:63], v[36:37], 1.0 op_sel_hi:[1,0]
	s_waitcnt vmcnt(1)
	v_pk_add_f32 v[36:37], v[164:165], 1.0 op_sel_hi:[1,0]
	v_pk_add_f32 v[38:39], v[162:163], 1.0 op_sel_hi:[1,0]
	v_pk_mul_f32 v[80:81], v[0:1], v[80:81]
	v_pk_mul_f32 v[82:83], v[2:3], v[82:83]
	s_waitcnt vmcnt(0)
	v_pk_fma_f32 v[80:81], v[38:39], v[80:81], v[4:5]
	v_pk_fma_f32 v[82:83], v[36:37], v[82:83], v[6:7]
	v_cvt_pk_bf16_f32 v80, v80, v81
	v_cvt_pk_bf16_f32 v81, v82, v83
	v_mul_f32_e32 v65, 0x45800000, v33
	global_store_dwordx2 v[128:129], v[80:81], off offset:1536
	v_cndmask_b32_e32 v80, v33, v65, vcc
	v_mov_b32_e32 v65, v182
	v_pk_mul_f32 v[66:67], v[80:81], v[66:67] op_sel_hi:[0,1]
	v_pk_mul_f32 v[64:65], v[80:81], v[64:65] op_sel_hi:[0,1]
	v_pk_mul_f32 v[64:65], v[0:1], v[64:65]
	v_pk_mul_f32 v[66:67], v[2:3], v[66:67]
	v_pk_fma_f32 v[64:65], v[38:39], v[64:65], v[4:5]
	v_pk_fma_f32 v[66:67], v[36:37], v[66:67], v[6:7]
	v_cvt_pk_bf16_f32 v64, v64, v65
	v_cvt_pk_bf16_f32 v65, v66, v67
	global_store_dwordx2 v[128:129], v[64:65], off offset:3584
	v_mov_b32_e32 v64, v94
	v_mov_b32_e32 v65, v92
	v_mov_b32_e32 v92, v95
	v_pk_add_f32 v[64:65], v[64:65], v[92:93]
	v_pk_mul_f32 v[140:141], v[152:153], v[140:141] op_sel_hi:[0,1]
	v_pk_mul_f32 v[84:85], v[152:153], v[84:85] op_sel_hi:[0,1]
	v_pk_add_f32 v[56:57], v[54:55], 1.0 op_sel_hi:[1,0]
	v_pk_add_f32 v[58:59], v[52:53], 1.0 op_sel_hi:[1,0]
	s_nop 1
	v_add_f32_dpp v64, v64, v64 quad_perm:[1,0,3,2] row_mask:0xf bank_mask:0xf
	v_add_f32_dpp v65, v65, v65 quad_perm:[1,0,3,2] row_mask:0xf bank_mask:0xf
	v_pk_add_f32 v[52:53], v[160:161], 1.0 op_sel_hi:[1,0]
	v_pk_add_f32 v[54:55], v[158:159], 1.0 op_sel_hi:[1,0]
	v_pk_mul_f32 v[84:85], v[8:9], v[84:85]
	v_pk_mul_f32 v[140:141], v[10:11], v[140:141]
	s_nop 1
	v_add_f32_dpp v64, v64, v64 quad_perm:[2,3,0,1] row_mask:0xf bank_mask:0xf
	v_add_f32_dpp v65, v65, v65 quad_perm:[2,3,0,1] row_mask:0xf bank_mask:0xf
	v_pk_fma_f32 v[140:141], v[52:53], v[140:141], v[14:15]
	v_pk_fma_f32 v[84:85], v[54:55], v[84:85], v[12:13]
	v_mov_b32_e32 v82, v135
	v_cvt_pk_bf16_f32 v84, v84, v85
	s_nop 1
	v_add_f32_dpp v64, v64, v64 row_half_mirror row_mask:0xf bank_mask:0xf
	v_add_f32_dpp v65, v65, v65 row_half_mirror row_mask:0xf bank_mask:0xf
	v_cvt_pk_bf16_f32 v85, v140, v141
	v_mov_b32_e32 v83, v139
	v_mov_b32_e32 v135, v138
	global_store_dwordx2 v[128:129], v[84:85], off offset:1024
	s_nop 1
	v_add_f32_dpp v64, v64, v64 row_mirror row_mask:0xf bank_mask:0xf
	v_add_f32_dpp v65, v65, v65 row_mirror row_mask:0xf bank_mask:0xf
	v_pk_mul_f32 v[82:83], v[80:81], v[82:83] op_sel_hi:[0,1]
	v_pk_mul_f32 v[84:85], v[80:81], v[134:135] op_sel_hi:[0,1]
; __device__ __forceinline__ u32x2 pack4(f32x4 v) { u32x2 w; w.x = pk2(v[0], v[1]); w.y = pk2(v[2], v[3]); return w; }
; template <int NR, bool XIN16 = false, bool XOUT16 = false> ...
;     ...
;         for (int o = 1; o < 64; o <<= 1) {
; #pragma unroll
;             for (int q = 0; q < NR; ++q) ss[q] += __shfl_xor(ss[q], o); }
; #pragma unroll
;         for (int q = 0; q < NR; ++q) { const float rstd = rsqrtf(ss[q] * (1.f / DM) + EPS);
;             u32x2* ho = (u32x2*)(hout + (size_t)(row + q * rstride) * DM) + lane;
; #pragma unroll
;             for (int j = 0; j < 4; ++j) { const f32x4 hv = (xv[q][j] * rstd * gh[j]) * (1.f + s1[j]) + s0[j]; ho[64 * j] = pack4(hv); } }
	v_pk_mul_f32 v[84:85], v[24:25], v[84:85]
	v_pk_mul_f32 v[82:83], v[26:27], v[82:83]
	s_nop 1
	v_readlane_b32 s98, v64, 0
	v_readlane_b32 s99, v64, 16
	v_readlane_b32 s100, v64, 32
	v_readlane_b32 s101, v64, 48
	s_nop 1
	v_mov_b32_e32 v228, s98
	v_add_f32_e32 v228, s99, v228
	v_mov_b32_e32 v229, s100
	v_add_f32_e32 v229, s101, v229
	v_add_f32_e32 v64, v228, v229
	v_readlane_b32 s98, v65, 0
	v_readlane_b32 s99, v65, 16
	v_readlane_b32 s100, v65, 32
	v_readlane_b32 s101, v65, 48
	s_nop 1
	v_mov_b32_e32 v228, s98
	v_add_f32_e32 v228, s99, v228
	v_mov_b32_e32 v229, s100
	v_add_f32_e32 v229, s101, v229
	v_add_f32_e32 v65, v228, v229
	v_pk_fma_f32 v[82:83], v[60:61], v[82:83], v[30:31]
	v_pk_fma_f32 v[84:85], v[62:63], v[84:85], v[28:29]
	v_pk_mul_f32 v[68:69], v[80:81], v[68:69] op_sel_hi:[0,1]
	v_cvt_pk_bf16_f32 v84, v84, v85
	v_cvt_pk_bf16_f32 v85, v82, v83
	v_mov_b32_e32 v82, v125
	v_mov_b32_e32 v83, v133
	v_mov_b32_e32 v125, v132
	v_pk_fma_f32 v[64:65], v[64:65], s[82:83], v[130:131] op_sel_hi:[1,0,0]
	global_store_dwordx2 v[128:129], v[84:85], off offset:2048
	v_pk_mul_f32 v[82:83], v[80:81], v[82:83] op_sel_hi:[0,1]
	v_pk_mul_f32 v[84:85], v[80:81], v[124:125] op_sel_hi:[0,1]
	v_mul_f32_e32 v33, 0x4b800000, v65
	v_cmp_gt_f32_e64 s[8:9], s72, v65
	v_pk_mul_f32 v[84:85], v[16:17], v[84:85]
	v_pk_mul_f32 v[82:83], v[18:19], v[82:83]
	v_cndmask_b32_e64 v33, v65, v33, s[8:9]
	v_pk_fma_f32 v[82:83], v[56:57], v[82:83], v[22:23]
	v_pk_fma_f32 v[84:85], v[58:59], v[84:85], v[20:21]
	v_rsq_f32_e32 v33, v33
	v_cvt_pk_bf16_f32 v84, v84, v85
	v_cvt_pk_bf16_f32 v85, v82, v83
	v_pk_mul_f32 v[82:83], v[80:81], v[136:137] op_sel_hi:[0,1]
	v_pk_mul_f32 v[68:69], v[8:9], v[68:69]
	v_pk_mul_f32 v[82:83], v[10:11], v[82:83]
	v_pk_fma_f32 v[68:69], v[54:55], v[68:69], v[12:13]
	v_pk_fma_f32 v[82:83], v[52:53], v[82:83], v[14:15]
	v_cvt_pk_bf16_f32 v68, v68, v69
	v_cvt_pk_bf16_f32 v69, v82, v83
	v_mul_f32_e32 v65, 0x45800000, v33
	global_store_dwordx2 v[128:129], v[68:69], off offset:3072
	v_cndmask_b32_e64 v66, v33, v65, s[8:9]
	v_mov_b32_e32 v68, v89
	v_mov_b32_e32 v69, v91
	v_mov_b32_e32 v89, v90
	v_pk_mul_f32 v[68:69], v[66:67], v[68:69] op_sel_hi:[0,1]
	v_pk_mul_f32 v[80:81], v[66:67], v[88:89] op_sel_hi:[0,1]
	v_pk_mul_f32 v[80:81], v[24:25], v[80:81]
	v_pk_mul_f32 v[68:69], v[26:27], v[68:69]
	v_pk_fma_f32 v[80:81], v[62:63], v[80:81], v[28:29]
	v_pk_fma_f32 v[68:69], v[60:61], v[68:69], v[30:31]
	v_cvt_pk_bf16_f32 v80, v80, v81
	v_cvt_pk_bf16_f32 v81, v68, v69
	v_mov_b32_e32 v68, v77
	v_mov_b32_e32 v69, v79
	v_mov_b32_e32 v77, v78
	v_pk_mul_f32 v[68:69], v[66:67], v[68:69] op_sel_hi:[0,1]
	v_pk_mul_f32 v[76:77], v[66:67], v[76:77] op_sel_hi:[0,1]
	v_pk_mul_f32 v[76:77], v[16:17], v[76:77]
	v_pk_mul_f32 v[68:69], v[18:19], v[68:69]
	v_pk_fma_f32 v[76:77], v[58:59], v[76:77], v[20:21]
	v_pk_fma_f32 v[68:69], v[56:57], v[68:69], v[22:23]
	v_cmp_gt_f32_e32 vcc, s72, v64
	v_cvt_pk_bf16_f32 v76, v76, v77
	v_cvt_pk_bf16_f32 v77, v68, v69
	v_pk_mul_f32 v[68:69], v[66:67], v[86:87] op_sel_hi:[0,1]
	v_pk_mul_f32 v[70:71], v[66:67], v[70:71] op_sel_hi:[0,1]
	v_mul_f32_e32 v33, 0x4b800000, v64
	v_pk_mul_f32 v[70:71], v[8:9], v[70:71]
	v_pk_mul_f32 v[68:69], v[10:11], v[68:69]
	v_cndmask_b32_e32 v33, v64, v33, vcc
	v_pk_fma_f32 v[68:69], v[52:53], v[68:69], v[14:15]
	v_pk_fma_f32 v[70:71], v[54:55], v[70:71], v[12:13]
	v_mov_b32_e32 v73, v154
	v_rsq_f32_e32 v33, v33
	v_cvt_pk_bf16_f32 v70, v70, v71
	v_cvt_pk_bf16_f32 v71, v68, v69
	v_pk_mul_f32 v[68:69], v[66:67], v[74:75] op_sel_hi:[0,1]
	v_pk_mul_f32 v[66:67], v[66:67], v[72:73] op_sel_hi:[0,1]
; __device__ __forceinline__ u32x2 pack4(f32x4 v) { u32x2 w; w.x = pk2(v[0], v[1]); w.y = pk2(v[2], v[3]); return w; }
; template <int NR, bool XIN16 = false, bool XOUT16 = false> ...
;     ...
;         for (int q = 0; q < NR; ++q) { const float rstd = rsqrtf(ss[q] * (1.f / DM) + EPS);
;             u32x2* ho = (u32x2*)(hout + (size_t)(row + q * rstride) * DM) + lane;
; #pragma unroll
;             for (int j = 0; j < 4; ++j) { const f32x4 hv = (xv[q][j] * rstd * gh[j]) * (1.f + s1[j]) + s0[j]; ho[64 * j] = pack4(hv); } }
	v_pk_mul_f32 v[66:67], v[0:1], v[66:67]
	v_pk_mul_f32 v[68:69], v[2:3], v[68:69]
	v_pk_fma_f32 v[66:67], v[38:39], v[66:67], v[4:5]
	v_pk_fma_f32 v[68:69], v[36:37], v[68:69], v[6:7]
	v_cvt_pk_bf16_f32 v66, v66, v67
	v_cvt_pk_bf16_f32 v67, v68, v69
	v_mul_f32_e32 v64, 0x45800000, v33
	v_mov_b32_e32 v158, v147
	v_mov_b32_e32 v159, v149
	v_mov_b32_e32 v147, v148
	global_store_dwordx2 v[126:127], v[66:67], off offset:1536
	v_cndmask_b32_e32 v64, v33, v64, vcc
	v_mov_b32_e32 v66, v49
	v_mov_b32_e32 v67, v51
	v_mov_b32_e32 v49, v50
	v_pk_mul_f32 v[158:159], v[152:153], v[158:159] op_sel_hi:[0,1]
	v_pk_mul_f32 v[146:147], v[152:153], v[146:147] op_sel_hi:[0,1]
	v_pk_mul_f32 v[66:67], v[64:65], v[66:67] op_sel_hi:[0,1]
	v_pk_mul_f32 v[48:49], v[64:65], v[48:49] op_sel_hi:[0,1]
	v_pk_mul_f32 v[146:147], v[24:25], v[146:147]
	v_pk_mul_f32 v[148:149], v[26:27], v[158:159]
	v_pk_mul_f32 v[24:25], v[24:25], v[48:49]
	v_pk_mul_f32 v[26:27], v[26:27], v[66:67]
	v_pk_fma_f32 v[148:149], v[60:61], v[148:149], v[30:31]
	v_pk_fma_f32 v[146:147], v[62:63], v[146:147], v[28:29]
	v_pk_fma_f32 v[26:27], v[60:61], v[26:27], v[30:31]
	v_pk_fma_f32 v[24:25], v[62:63], v[24:25], v[28:29]
	v_cvt_pk_bf16_f32 v146, v146, v147
	v_cvt_pk_bf16_f32 v147, v148, v149
	v_cvt_pk_bf16_f32 v24, v24, v25
	v_cvt_pk_bf16_f32 v25, v26, v27
	global_store_dwordx2 v[128:129], v[146:147], off
	v_mov_b32_e32 v146, v143
	v_mov_b32_e32 v147, v145
	v_mov_b32_e32 v143, v144
	global_store_dwordx2 v[126:127], v[24:25], off offset:2048
	v_mov_b32_e32 v24, v45
	v_mov_b32_e32 v25, v47
	v_mov_b32_e32 v45, v46
	v_pk_mul_f32 v[146:147], v[152:153], v[146:147] op_sel_hi:[0,1]
	v_pk_mul_f32 v[142:143], v[152:153], v[142:143] op_sel_hi:[0,1]
	v_pk_mul_f32 v[24:25], v[64:65], v[24:25] op_sel_hi:[0,1]
	v_pk_mul_f32 v[26:27], v[64:65], v[44:45] op_sel_hi:[0,1]
	v_pk_mul_f32 v[142:143], v[16:17], v[142:143]
	v_pk_mul_f32 v[144:145], v[18:19], v[146:147]
	v_pk_mul_f32 v[16:17], v[16:17], v[26:27]
	v_pk_mul_f32 v[18:19], v[18:19], v[24:25]
	v_pk_fma_f32 v[16:17], v[58:59], v[16:17], v[20:21]
	v_pk_fma_f32 v[18:19], v[56:57], v[18:19], v[22:23]
	v_cvt_pk_bf16_f32 v16, v16, v17
	v_cvt_pk_bf16_f32 v17, v18, v19
	global_store_dwordx2 v[126:127], v[16:17], off offset:2560
	v_pk_mul_f32 v[16:17], v[64:65], v[42:43] op_sel_hi:[0,1]
	v_pk_mul_f32 v[18:19], v[64:65], v[40:41] op_sel_hi:[0,1]
	v_pk_mul_f32 v[8:9], v[8:9], v[18:19]
	v_pk_mul_f32 v[10:11], v[10:11], v[16:17]
	v_pk_fma_f32 v[8:9], v[54:55], v[8:9], v[12:13]
	v_pk_fma_f32 v[10:11], v[52:53], v[10:11], v[14:15]
	v_cvt_pk_bf16_f32 v8, v8, v9
	v_cvt_pk_bf16_f32 v9, v10, v11
	v_mov_b32_e32 v33, v156
	global_store_dwordx2 v[126:127], v[8:9], off offset:3072
	v_pk_mul_f32 v[8:9], v[64:65], v[34:35] op_sel_hi:[0,1]
	v_pk_mul_f32 v[10:11], v[64:65], v[32:33] op_sel_hi:[0,1]
	v_pk_mul_f32 v[0:1], v[0:1], v[10:11]
	v_pk_mul_f32 v[2:3], v[2:3], v[8:9]
	v_pk_fma_f32 v[144:145], v[56:57], v[144:145], v[22:23]
	v_pk_fma_f32 v[142:143], v[58:59], v[142:143], v[20:21]
	v_pk_fma_f32 v[2:3], v[36:37], v[2:3], v[6:7]
	v_pk_fma_f32 v[0:1], v[38:39], v[0:1], v[4:5]
	v_cvt_pk_bf16_f32 v142, v142, v143
	v_cvt_pk_bf16_f32 v143, v144, v145
	v_cvt_pk_bf16_f32 v0, v0, v1
	v_cvt_pk_bf16_f32 v1, v2, v3
	global_store_dwordx2 v[128:129], v[142:143], off offset:512
	global_store_dwordx2 v[128:129], v[84:85], off offset:2560
	global_store_dwordx2 v[126:127], v[80:81], off
	global_store_dwordx2 v[126:127], v[76:77], off offset:512
	global_store_dwordx2 v[126:127], v[70:71], off offset:1024
	global_store_dwordx2 v[126:127], v[0:1], off offset:3584
	s_branch .LBB0_1044

; __device__ __forceinline__ f32x4 unpack4(u32x2 w) { return (f32x4){bf_lo(w.x), bf_hi(w.x), bf_lo(w.y), bf_hi(w.y)}; }
; template <int NR, bool XIN16 = false, bool XOUT16 = false> ...
;     ...
;     for (int q = 0; q < NR; ++q) {
;         if (XIN16) { const u32x2* xr = (const u32x2*)((const bf16_t*)xin + (size_t)(row + q * rstride) * DM) + lane;
; #pragma unroll
;             for (int j = 0; j < 4; ++j) xv[q][j] = unpack4(xr[64 * j]); }
;         else { const f32x4* xr = (const f32x4*)(xin + (size_t)(row + q * rstride) * DM) + lane;
; #pragma unroll
;             for (int j = 0; j < 4; ++j) xv[q][j] = xr[64 * j]; } }
;     if (y) {
; #pragma unroll
;         for (int q = 0; q < NR; ++q) { const u32x2* yr = (const u32x2*)(y + (size_t)(row + q * rstride) * DM) + lane;
; #pragma unroll
;             for (int j = 0; j < 4; ++j) yv[q][j] = unpack4(yr[64 * j]); }
;         f32x4 g[4], gy[4];
; #pragma unroll
;         for (int j = 0; j < 4; ++j) { g[j] = ((const f32x4*)gate)[lane + 64 * j]; gy[j] = ((const f32x4*)gainY)[lane + 64 * j]; }
;         float ss[NR];
; #pragma unroll
;         for (int q = 0; q < NR; ++q) { ss[q] = 0.f;
; #pragma unroll
;             for (int j = 0; j < 4; ++j) ss[q] += (yv[q][j][0] * yv[q][j][0] + yv[q][j][1] * yv[q][j][1]) + (yv[q][j][2] * yv[q][j][2] + yv[q][j][3] * yv[q][j][3]); }
.LBB0_1369:
	s_ashr_i32 s4, s8, 12
	s_mul_hi_i32 s5, s4, 0x1800
	s_mulk_i32 s4, 0x1800
	s_lshl_b64 s[4:5], s[4:5], 2
	s_add_u32 s27, s1, s4
	s_addc_u32 s9, s24, s5
	s_mov_b64 s[14:15], -1
	s_and_b64 vcc, exec, s[6:7]
	v_lshl_add_u64 v[68:69], s[10:11], 0, v[112:113]
	v_lshlrev_b32_e32 v204, 4, v48
	v_lshlrev_b32_e32 v61, 4, v52
	v_lshlrev_b32_e32 v57, 4, v56
	v_lshlrev_b32_e32 v53, 4, v60
	s_cbranch_vccz .LBB0_1371
	v_add_co_u32_e32 v0, vcc, s84, v68
	s_mov_b32 s14, 0x7401000
	s_nop 0
	v_addc_co_u32_e32 v1, vcc, 0, v69, vcc
	v_add_co_u32_e32 v14, vcc, s14, v68
	global_load_dwordx2 v[2:3], v[0:1], off offset:512
	global_load_dwordx2 v[4:5], v[0:1], off offset:1024
	global_load_dwordx2 v[6:7], v[0:1], off offset:1536
	global_load_dwordx2 v[8:9], v[0:1], off offset:2048
	global_load_dwordx2 v[10:11], v[0:1], off offset:2560
	global_load_dwordx2 v[12:13], v[0:1], off offset:3072
	v_addc_co_u32_e32 v15, vcc, 0, v69, vcc
	v_add_co_u32_e32 v72, vcc, s28, v68
	global_load_dwordx2 v[0:1], v[0:1], off offset:3584
	s_nop 0
	v_addc_co_u32_e32 v73, vcc, 0, v69, vcc
	v_add_co_u32_e32 v70, vcc, s29, v68
	global_load_dwordx2 v[16:17], v[14:15], off offset:-4096
	global_load_dwordx2 v[18:19], v[14:15], off
	global_load_dwordx2 v[20:21], v[14:15], off offset:512
	global_load_dwordx2 v[22:23], v[14:15], off offset:1024
	global_load_dwordx2 v[24:25], v[14:15], off offset:1536
	v_addc_co_u32_e32 v71, vcc, 0, v69, vcc
	global_load_dwordx2 v[26:27], v[14:15], off offset:2048
	global_load_dwordx2 v[28:29], v[14:15], off offset:2560
	global_load_dwordx2 v[30:31], v[14:15], off offset:3072
	s_nop 0
	global_load_dwordx2 v[14:15], v[14:15], off offset:3584
	s_nop 0
	global_load_dwordx2 v[140:141], v[72:73], off offset:1024
	global_load_dwordx2 v[40:41], v[72:73], off offset:1536
	global_load_dwordx2 v[142:143], v[70:71], off
	global_load_dwordx2 v[144:145], v[70:71], off offset:512
	global_load_dwordx2 v[138:139], v[70:71], off offset:1024
	global_load_dwordx2 v[42:43], v[70:71], off offset:1536
	global_load_dwordx2 v[148:149], v[72:73], off offset:3072
	global_load_dwordx2 v[46:47], v[72:73], off offset:3584
	global_load_dwordx2 v[136:137], v[70:71], off offset:2048
	global_load_dwordx2 v[132:133], v[70:71], off offset:2560
	global_load_dwordx2 v[74:75], v[70:71], off offset:3072
	global_load_dwordx2 v[150:151], v[70:71], off offset:3584
	global_load_dwordx2 v[152:153], v[72:73], off offset:512
	global_load_dwordx2 v[160:161], v[72:73], off offset:2048
	global_load_dwordx2 v[162:163], v[72:73], off offset:2560
	global_load_dwordx2 v[156:157], v[70:71], off offset:-4096
	s_add_u32 s14, s25, s4
	s_addc_u32 s15, s26, s5
	s_add_u32 s4, s27, 0x5000
	s_addc_u32 s5, s9, 0
	s_add_u32 s20, s14, 0x1000
	s_addc_u32 s21, s15, 0
	s_waitcnt vmcnt(31)
	v_lshlrev_b32_e32 v154, 16, v2
	v_and_b32_e32 v155, 0xffff0000, v2
	v_lshlrev_b32_e32 v158, 16, v3
	v_and_b32_e32 v159, 0xffff0000, v3
	s_waitcnt vmcnt(30)
	v_lshlrev_b32_e32 v86, 16, v4
	v_and_b32_e32 v87, 0xffff0000, v4
	v_lshlrev_b32_e32 v146, 16, v5
	v_and_b32_e32 v147, 0xffff0000, v5
	s_waitcnt vmcnt(29)
	v_lshlrev_b32_e32 v98, 16, v6
	s_waitcnt vmcnt(15)
	v_lshlrev_b32_e32 v186, 16, v140
	s_waitcnt vmcnt(14)
	v_lshlrev_b32_e32 v171, 16, v40
	v_and_b32_e32 v169, 0xffff0000, v40
	v_lshlrev_b32_e32 v172, 16, v41
	v_and_b32_e32 v173, 0xffff0000, v41
	s_waitcnt vmcnt(10)
	v_lshlrev_b32_e32 v106, 16, v43
	v_and_b32_e32 v107, 0xffff0000, v43
	s_waitcnt vmcnt(8)
	v_lshlrev_b32_e32 v121, 16, v46
	v_and_b32_e32 v119, 0xffff0000, v46
	v_lshlrev_b32_e32 v122, 16, v47
	v_and_b32_e32 v123, 0xffff0000, v47
	s_waitcnt vmcnt(4)
	v_and_b32_e32 v41, 0xffff0000, v150
	v_lshlrev_b32_e32 v43, 16, v150
	v_lshlrev_b32_e32 v46, 16, v151
	v_and_b32_e32 v47, 0xffff0000, v151
	s_waitcnt vmcnt(0)
	v_and_b32_e32 v203, 0xffff0000, v157
	v_and_b32_e32 v201, 0xffff0000, v156
	v_lshlrev_b32_e32 v202, 16, v157
	v_mul_f32_e32 v40, v203, v203
	v_lshlrev_b32_e32 v200, 16, v156
	v_pk_fma_f32 v[150:151], v[202:203], v[202:203], v[40:41] op_sel_hi:[1,1,0]
	v_mul_f32_e32 v40, v201, v201
	v_and_b32_e32 v193, 0xffff0000, v153
	v_and_b32_e32 v192, 0xffff0000, v152
	v_and_b32_e32 v187, 0xffff0000, v140
	v_lshlrev_b32_e32 v188, 16, v141
	v_and_b32_e32 v189, 0xffff0000, v141
	v_pk_fma_f32 v[140:141], v[200:201], v[200:201], v[40:41] op_sel_hi:[1,1,0]
	v_lshlrev_b32_e32 v191, 16, v153
	v_lshlrev_b32_e32 v190, 16, v152
	v_pk_mul_f32 v[152:153], v[192:193], v[192:193]
	v_mov_b32_e32 v170, v140
	v_mov_b32_e32 v156, v150
	v_mov_b32_e32 v157, v171
	v_pk_fma_f32 v[152:153], v[190:191], v[190:191], v[152:153]
	v_pk_add_f32 v[140:141], v[140:141], v[150:151]
	v_pk_mul_f32 v[150:151], v[170:171], v[156:157]
	v_lshlrev_b32_e32 v91, 16, v42
	v_and_b32_e32 v105, 0xffff0000, v42
	v_mul_f32_e32 v42, v169, v169
	v_mov_b32_e32 v141, v151
	v_pk_add_f32 v[150:151], v[152:153], v[152:153] op_sel:[0,1] op_sel_hi:[1,0]
	v_mul_f32_e32 v40, v187, v187
	v_mov_b32_e32 v151, v42
	v_pk_add_f32 v[140:141], v[140:141], v[150:151]
	v_pk_fma_f32 v[150:151], v[186:187], v[186:187], v[40:41] op_sel_hi:[1,1,0]
	v_mul_f32_e32 v40, v189, v189
	v_mul_f32_e32 v90, v172, v172
	v_mul_f32_e32 v104, v173, v173
	v_pk_fma_f32 v[152:153], v[188:189], v[188:189], v[40:41] op_sel_hi:[1,1,0]
	v_mov_b32_e32 v151, v90
	v_mov_b32_e32 v153, v104
	v_and_b32_e32 v185, 0xffff0000, v161
	v_pk_add_f32 v[150:151], v[150:151], v[152:153]
	v_and_b32_e32 v183, 0xffff0000, v160
	v_lshlrev_b32_e32 v184, 16, v161
	v_mul_f32_e32 v40, v185, v185
	v_pk_add_f32 v[206:207], v[140:141], v[150:151]
	v_lshlrev_b32_e32 v182, 16, v160
	v_pk_fma_f32 v[140:141], v[184:185], v[184:185], v[40:41] op_sel_hi:[1,1,0]
	v_mul_f32_e32 v40, v183, v183
; __device__ __forceinline__ f32x4 unpack4(u32x2 w) { return (f32x4){bf_lo(w.x), bf_hi(w.x), bf_lo(w.y), bf_hi(w.y)}; }
; template <int NR, bool XIN16 = false, bool XOUT16 = false> ...
;     ...
;         if (XIN16) { const u32x2* xr = (const u32x2*)((const bf16_t*)xin + (size_t)(row + q * rstride) * DM) + lane;
; #pragma unroll
;             for (int j = 0; j < 4; ++j) xv[q][j] = unpack4(xr[64 * j]); }
;         else { const f32x4* xr = (const f32x4*)(xin + (size_t)(row + q * rstride) * DM) + lane;
; #pragma unroll
;             for (int j = 0; j < 4; ++j) xv[q][j] = xr[64 * j]; } }
;     if (y) {
; #pragma unroll
;         for (int q = 0; q < NR; ++q) { const u32x2* yr = (const u32x2*)(y + (size_t)(row + q * rstride) * DM) + lane;
; #pragma unroll
;             for (int j = 0; j < 4; ++j) yv[q][j] = unpack4(yr[64 * j]); }
;         f32x4 g[4], gy[4];
; #pragma unroll
;         for (int j = 0; j < 4; ++j) { g[j] = ((const f32x4*)gate)[lane + 64 * j]; gy[j] = ((const f32x4*)gainY)[lane + 64 * j]; }
;         float ss[NR];
; #pragma unroll
;         for (int q = 0; q < NR; ++q) { ss[q] = 0.f;
; #pragma unroll
;             for (int j = 0; j < 4; ++j) ss[q] += (yv[q][j][0] * yv[q][j][0] + yv[q][j][1] * yv[q][j][1]) + (yv[q][j][2] * yv[q][j][2] + yv[q][j][3] * yv[q][j][3]); }
	v_and_b32_e32 v99, 0xffff0000, v6
	v_lshlrev_b32_e32 v134, 16, v7
	v_and_b32_e32 v135, 0xffff0000, v7
	v_lshlrev_b32_e32 v128, 16, v8
	v_and_b32_e32 v129, 0xffff0000, v8
	v_lshlrev_b32_e32 v130, 16, v9
	v_and_b32_e32 v131, 0xffff0000, v9
	v_lshlrev_b32_e32 v124, 16, v10
	v_and_b32_e32 v125, 0xffff0000, v10
	v_lshlrev_b32_e32 v126, 16, v11
	v_and_b32_e32 v127, 0xffff0000, v11
	v_lshlrev_b32_e32 v94, 16, v12
	v_and_b32_e32 v95, 0xffff0000, v12
	v_lshlrev_b32_e32 v116, 16, v13
	v_and_b32_e32 v117, 0xffff0000, v13
	v_lshlrev_b32_e32 v102, 16, v0
	v_and_b32_e32 v103, 0xffff0000, v0
	v_lshlrev_b32_e32 v174, 16, v16
	v_and_b32_e32 v175, 0xffff0000, v16
	v_lshlrev_b32_e32 v176, 16, v17
	v_and_b32_e32 v177, 0xffff0000, v17
	v_lshlrev_b32_e32 v110, 16, v1
	v_and_b32_e32 v111, 0xffff0000, v1
	v_lshlrev_b32_e32 v108, 16, v18
	v_and_b32_e32 v109, 0xffff0000, v18
	v_lshlrev_b32_e32 v114, 16, v19
	v_and_b32_e32 v115, 0xffff0000, v19
	v_lshlrev_b32_e32 v96, 16, v20
	v_and_b32_e32 v97, 0xffff0000, v20
	v_lshlrev_b32_e32 v100, 16, v21
	v_and_b32_e32 v101, 0xffff0000, v21
	v_lshlrev_b32_e32 v88, 16, v22
	v_and_b32_e32 v89, 0xffff0000, v22
	v_lshlrev_b32_e32 v92, 16, v23
	v_and_b32_e32 v93, 0xffff0000, v23
	v_lshlrev_b32_e32 v82, 16, v24
	v_and_b32_e32 v83, 0xffff0000, v24
	v_lshlrev_b32_e32 v84, 16, v25
	v_and_b32_e32 v85, 0xffff0000, v25
	v_lshlrev_b32_e32 v78, 16, v26
	v_and_b32_e32 v79, 0xffff0000, v26
	v_lshlrev_b32_e32 v80, 16, v27
	v_and_b32_e32 v81, 0xffff0000, v27
	v_lshlrev_b32_e32 v44, 16, v28
	v_and_b32_e32 v45, 0xffff0000, v28
	v_lshlrev_b32_e32 v76, 16, v29
	v_and_b32_e32 v77, 0xffff0000, v29
	v_lshlrev_b32_e32 v36, 16, v30
	v_and_b32_e32 v37, 0xffff0000, v30
	v_lshlrev_b32_e32 v38, 16, v31
	v_and_b32_e32 v39, 0xffff0000, v31
	v_lshlrev_b32_e32 v32, 16, v14
	v_and_b32_e32 v33, 0xffff0000, v14
	v_lshlrev_b32_e32 v34, 16, v15
	v_and_b32_e32 v35, 0xffff0000, v15
	global_load_dwordx4 v[24:27], v204, s[4:5]
	global_load_dwordx4 v[16:19], v61, s[4:5]
	global_load_dwordx4 v[28:31], v[50:51], off
	global_load_dwordx4 v[20:23], v[54:55], off
	global_load_dwordx4 v[8:11], v57, s[4:5]
	global_load_dwordx4 v[0:3], v53, s[4:5]
	global_load_dwordx4 v[12:15], v[58:59], off
	global_load_dwordx4 v[4:7], v[62:63], off
	v_and_b32_e32 v181, 0xffff0000, v163
	v_and_b32_e32 v180, 0xffff0000, v162
	v_lshlrev_b32_e32 v164, 16, v148
	v_and_b32_e32 v165, 0xffff0000, v148
	v_lshlrev_b32_e32 v166, 16, v149
	v_and_b32_e32 v167, 0xffff0000, v149
	v_pk_fma_f32 v[148:149], v[182:183], v[182:183], v[40:41] op_sel_hi:[1,1,0]
	v_lshlrev_b32_e32 v179, 16, v163
	v_lshlrev_b32_e32 v178, 16, v162
	v_pk_mul_f32 v[150:151], v[180:181], v[180:181]
	v_mov_b32_e32 v120, v148
	v_mov_b32_e32 v152, v140
	v_mov_b32_e32 v153, v121
	v_pk_fma_f32 v[150:151], v[178:179], v[178:179], v[150:151]
	v_pk_add_f32 v[140:141], v[148:149], v[140:141]
	v_pk_mul_f32 v[148:149], v[120:121], v[152:153]
	v_mul_f32_e32 v42, v119, v119
	v_mov_b32_e32 v141, v149
	v_pk_add_f32 v[148:149], v[150:151], v[150:151] op_sel:[0,1] op_sel_hi:[1,0]
	v_mul_f32_e32 v40, v165, v165
	v_mov_b32_e32 v149, v42
	v_pk_add_f32 v[140:141], v[140:141], v[148:149]
	v_pk_fma_f32 v[148:149], v[164:165], v[164:165], v[40:41] op_sel_hi:[1,1,0]
	v_mul_f32_e32 v40, v167, v167
	v_mul_f32_e32 v90, v122, v122
	v_mul_f32_e32 v104, v123, v123
	v_pk_fma_f32 v[150:151], v[166:167], v[166:167], v[40:41] op_sel_hi:[1,1,0]
	v_mov_b32_e32 v149, v90
	v_mov_b32_e32 v151, v104
	v_and_b32_e32 v163, 0xffff0000, v143
	v_pk_add_f32 v[148:149], v[148:149], v[150:151]
	v_and_b32_e32 v161, 0xffff0000, v142
	v_lshlrev_b32_e32 v162, 16, v143
	v_mul_f32_e32 v40, v163, v163
	v_pk_add_f32 v[208:209], v[140:141], v[148:149]
	v_lshlrev_b32_e32 v160, 16, v142
	v_pk_fma_f32 v[140:141], v[162:163], v[162:163], v[40:41] op_sel_hi:[1,1,0]
	v_mul_f32_e32 v40, v161, v161
	v_and_b32_e32 v157, 0xffff0000, v145
	v_and_b32_e32 v156, 0xffff0000, v144
	v_lshlrev_b32_e32 v148, 16, v138
	v_and_b32_e32 v149, 0xffff0000, v138
	v_lshlrev_b32_e32 v152, 16, v139
	v_and_b32_e32 v153, 0xffff0000, v139
	v_pk_fma_f32 v[138:139], v[160:161], v[160:161], v[40:41] op_sel_hi:[1,1,0]
	v_lshlrev_b32_e32 v151, 16, v145
	v_lshlrev_b32_e32 v150, 16, v144
	v_pk_mul_f32 v[142:143], v[156:157], v[156:157]
	v_mov_b32_e32 v90, v138
	v_mov_b32_e32 v144, v140
	v_mov_b32_e32 v145, v91
	v_pk_fma_f32 v[142:143], v[150:151], v[150:151], v[142:143]
	v_pk_add_f32 v[138:139], v[138:139], v[140:141]
	v_pk_mul_f32 v[140:141], v[90:91], v[144:145]
	v_mul_f32_e32 v42, v105, v105
	v_mov_b32_e32 v139, v141
	v_pk_add_f32 v[140:141], v[142:143], v[142:143] op_sel:[0,1] op_sel_hi:[1,0]
	v_mul_f32_e32 v40, v149, v149
	v_mov_b32_e32 v141, v42
	v_pk_add_f32 v[138:139], v[138:139], v[140:141]
	v_pk_fma_f32 v[140:141], v[148:149], v[148:149], v[40:41] op_sel_hi:[1,1,0]
	v_mul_f32_e32 v40, v153, v153
	v_mul_f32_e32 v104, v106, v106
	v_mul_f32_e32 v118, v107, v107
	v_pk_fma_f32 v[142:143], v[152:153], v[152:153], v[40:41] op_sel_hi:[1,1,0]
	v_mov_b32_e32 v141, v104
	v_mov_b32_e32 v143, v118
	v_pk_add_f32 v[140:141], v[140:141], v[142:143]
	v_and_b32_e32 v145, 0xffff0000, v137
	v_pk_add_f32 v[198:199], v[138:139], v[140:141]
	v_and_b32_e32 v143, 0xffff0000, v136
	v_lshlrev_b32_e32 v144, 16, v137
	v_mul_f32_e32 v40, v145, v145
	v_and_b32_e32 v141, 0xffff0000, v133
	v_and_b32_e32 v140, 0xffff0000, v132
	v_lshlrev_b32_e32 v142, 16, v136
	v_pk_fma_f32 v[210:211], v[144:145], v[144:145], v[40:41] op_sel_hi:[1,1,0]
	v_lshlrev_b32_e32 v137, 16, v133
	v_lshlrev_b32_e32 v136, 16, v132
	v_pk_mul_f32 v[132:133], v[140:141], v[140:141]
	v_mul_f32_e32 v40, v143, v143
	v_pk_fma_f32 v[212:213], v[136:137], v[136:137], v[132:133]
; __device__ __forceinline__ f32x4 unpack4(u32x2 w) { return (f32x4){bf_lo(w.x), bf_hi(w.x), bf_lo(w.y), bf_hi(w.y)}; }
; __device__ __forceinline__ u32x2 pack4(f32x4 v) { u32x2 w; w.x = pk2(v[0], v[1]); w.y = pk2(v[2], v[3]); return w; }
; template <int NR, bool XIN16 = false, bool XOUT16 = false> ...
;     ...
;         for (int o = 1; o < 64; o <<= 1) {
; #pragma unroll
;             for (int q = 0; q < NR; ++q) ss[q] += __shfl_xor(ss[q], o); }
; #pragma unroll
;         for (int q = 0; q < NR; ++q) { const float rstd = rsqrtf(ss[q] * (1.f / DM) + EPS);
;             if (XOUT16) { u32x2* xo = (u32x2*)((bf16_t*)xout + (size_t)(row + q * rstride) * DM) + lane;
; #pragma unroll
;                 for (int j = 0; j < 4; ++j) { xv[q][j] = xv[q][j] + g[j] * (yv[q][j] * rstd * gy[j]); xo[64 * j] = pack4(xv[q][j]); xv[q][j] = unpack4(pack4(xv[q][j])); } }
	v_lshlrev_b32_e32 v132, 16, v74
	v_and_b32_e32 v133, 0xffff0000, v74
	v_lshlrev_b32_e32 v138, 16, v75
	v_and_b32_e32 v139, 0xffff0000, v75
	v_pk_fma_f32 v[74:75], v[142:143], v[142:143], v[40:41] op_sel_hi:[1,1,0]
	v_mov_b32_e32 v214, v210
	v_mov_b32_e32 v42, v74
	v_mov_b32_e32 v215, v43
	v_pk_add_f32 v[74:75], v[74:75], v[210:211]
	v_pk_mul_f32 v[210:211], v[42:43], v[214:215]
	v_mul_f32_e32 v40, v133, v133
	v_mov_b32_e32 v75, v211
	v_pk_add_f32 v[210:211], v[212:213], v[212:213] op_sel:[0,1] op_sel_hi:[1,0]
	v_pk_fma_f32 v[212:213], v[132:133], v[132:133], v[40:41] op_sel_hi:[1,1,0]
	v_and_b32_e32 v40, 64, v240
	v_mul_f32_e32 v90, v41, v41
	v_add_u32_e32 v40, 64, v40
	v_xor_b32_e32 v42, 1, v240
	v_mov_b32_e32 v211, v90
	v_cmp_lt_i32_e32 vcc, v42, v40
	v_pk_add_f32 v[210:211], v[74:75], v[210:211]
	v_mov_b32_e32 v74, v208
	v_cndmask_b32_e32 v42, v240, v42, vcc
	v_mov_b32_e32 v75, v206
	v_mov_b32_e32 v206, v209
	v_lshlrev_b32_e32 v170, 2, v42
	v_pk_add_f32 v[74:75], v[74:75], v[206:207]
	v_xor_b32_e32 v42, 2, v240
	v_cmp_lt_i32_e32 vcc, v42, v40
	v_mul_f32_e32 v104, v46, v46
	v_mul_f32_e32 v118, v47, v47
	v_cndmask_b32_e32 v42, v240, v42, vcc
	v_lshlrev_b32_e32 v205, 2, v42
	s_nop 1
	v_add_f32_dpp v74, v74, v74 quad_perm:[1,0,3,2] row_mask:0xf bank_mask:0xf
	v_add_f32_dpp v75, v75, v75 quad_perm:[1,0,3,2] row_mask:0xf bank_mask:0xf
	v_xor_b32_e32 v42, 4, v240
	v_cmp_lt_i32_e32 vcc, v42, v40
	v_mov_b32_e32 v213, v104
	s_brev_b32 s4, 32
	v_cndmask_b32_e32 v42, v240, v42, vcc
	v_lshlrev_b32_e32 v206, 2, v42
	s_nop 1
	v_add_f32_dpp v74, v74, v74 quad_perm:[2,3,0,1] row_mask:0xf bank_mask:0xf
	v_add_f32_dpp v75, v75, v75 quad_perm:[2,3,0,1] row_mask:0xf bank_mask:0xf
	v_xor_b32_e32 v42, 8, v240
	v_cmp_lt_i32_e32 vcc, v42, v40
	v_mov_b32_e32 v168, v171
	v_mov_b32_e32 v104, v91
	v_cndmask_b32_e32 v42, v240, v42, vcc
	v_lshlrev_b32_e32 v207, 2, v42
	s_nop 1
	v_add_f32_dpp v74, v74, v74 row_half_mirror row_mask:0xf bank_mask:0xf
	v_add_f32_dpp v75, v75, v75 row_half_mirror row_mask:0xf bank_mask:0xf
	v_xor_b32_e32 v42, 16, v240
	v_cmp_lt_i32_e32 vcc, v42, v40
	s_nop 1
	v_add_f32_dpp v74, v74, v74 row_mirror row_mask:0xf bank_mask:0xf
	v_add_f32_dpp v75, v75, v75 row_mirror row_mask:0xf bank_mask:0xf
	v_cndmask_b32_e32 v42, v240, v42, vcc
	v_lshlrev_b32_e32 v208, 2, v42
	v_xor_b32_e32 v42, 32, v240
	v_cmp_lt_i32_e32 vcc, v42, v40
	s_nop 1
	v_readlane_b32 s98, v74, 0
	v_readlane_b32 s99, v74, 16
	v_readlane_b32 s100, v74, 32
	v_readlane_b32 s101, v74, 48
	s_nop 1
	v_mov_b32_e32 v228, s98
	v_add_f32_e32 v228, s99, v228
	v_mov_b32_e32 v229, s100
	v_add_f32_e32 v229, s101, v229
	v_add_f32_e32 v74, v228, v229
	v_readlane_b32 s98, v75, 0
	v_readlane_b32 s99, v75, 16
	v_readlane_b32 s100, v75, 32
	v_readlane_b32 s101, v75, 48
	s_nop 1
	v_mov_b32_e32 v228, s98
	v_add_f32_e32 v228, s99, v228
	v_mov_b32_e32 v229, s100
	v_add_f32_e32 v229, s101, v229
	v_add_f32_e32 v75, v228, v229
	v_cndmask_b32_e32 v40, v240, v42, vcc
	v_lshlrev_b32_e32 v209, 2, v40
	v_mul_f32_e32 v40, v139, v139
	v_pk_fma_f32 v[216:217], v[138:139], v[138:139], v[40:41] op_sel_hi:[1,1,0]
	v_mov_b32_e32 v214, v74
	v_mov_b32_e32 v215, v75
	v_mov_b64_e32 v[74:75], s[36:37]
	v_pk_fma_f32 v[214:215], v[214:215], s[82:83], v[74:75] op_sel_hi:[1,0,0]
	v_mov_b32_e32 v217, v118
	v_mul_f32_e32 v40, 0x4b800000, v215
	v_cmp_gt_f32_e32 vcc, s72, v215
	v_pk_add_f32 v[212:213], v[212:213], v[216:217]
	v_mov_b32_e32 v118, v121
	v_cndmask_b32_e32 v40, v215, v40, vcc
	v_rsq_f32_e32 v40, v40
	v_pk_add_f32 v[210:211], v[210:211], v[212:213]
	v_lshl_add_u64 v[212:213], s[12:13], 0, v[112:113]
	v_mul_f32_e32 v42, 0x45800000, v40
	v_cndmask_b32_e32 v40, v40, v42, vcc
	v_pk_mul_f32 v[202:203], v[40:41], v[202:203] op_sel_hi:[0,1]
	s_waitcnt vmcnt(5)
	v_pk_mul_f32 v[202:203], v[30:31], v[202:203]
	v_pk_mul_f32 v[200:201], v[40:41], v[200:201] op_sel_hi:[0,1]
	v_pk_fma_f32 v[176:177], v[26:27], v[202:203], v[176:177]
	v_mov_b32_e32 v202, v191
	v_mov_b32_e32 v203, v193
	v_mov_b32_e32 v191, v192
	v_pk_mul_f32 v[202:203], v[40:41], v[202:203] op_sel_hi:[0,1]
	v_pk_mul_f32 v[190:191], v[40:41], v[190:191] op_sel_hi:[0,1]
	v_pk_mul_f32 v[200:201], v[28:29], v[200:201]
	s_waitcnt vmcnt(4)
	v_pk_mul_f32 v[190:191], v[20:21], v[190:191]
	v_pk_mul_f32 v[192:193], v[22:23], v[202:203]
	v_pk_fma_f32 v[174:175], v[24:25], v[200:201], v[174:175]
	v_add_co_u32_e32 v200, vcc, s4, v212
	v_pk_fma_f32 v[158:159], v[18:19], v[192:193], v[158:159]
	v_pk_fma_f32 v[154:155], v[16:17], v[190:191], v[154:155]
	v_addc_co_u32_e32 v201, vcc, 0, v213, vcc
	s_mov_b32 s4, 0x4001000
	v_cvt_pk_bf16_f32 v154, v154, v155
	v_cvt_pk_bf16_f32 v155, v158, v159
	v_pk_mul_f32 v[158:159], v[40:41], v[188:189] op_sel_hi:[0,1]
	v_cvt_pk_bf16_f32 v174, v174, v175
	v_cvt_pk_bf16_f32 v175, v176, v177
	v_add_co_u32_e32 v176, vcc, s4, v212
	s_waitcnt vmcnt(1)
	v_pk_mul_f32 v[158:159], v[14:15], v[158:159]
	v_addc_co_u32_e32 v177, vcc, 0, v213, vcc
	v_pk_fma_f32 v[158:159], v[10:11], v[158:159], v[146:147]
	v_pk_mul_f32 v[186:187], v[40:41], v[186:187] op_sel_hi:[0,1]
	v_cvt_pk_bf16_f32 v147, v158, v159
	v_pk_mul_f32 v[158:159], v[40:41], v[172:173] op_sel_hi:[0,1]
	v_pk_mul_f32 v[168:169], v[40:41], v[168:169] op_sel_hi:[0,1]
	v_mul_f32_e32 v40, 0x4b800000, v214
	v_cmp_gt_f32_e32 vcc, s72, v214
	s_waitcnt vmcnt(0)
; __device__ __forceinline__ f32x4 unpack4(u32x2 w) { return (f32x4){bf_lo(w.x), bf_hi(w.x), bf_lo(w.y), bf_hi(w.y)}; }
; __device__ __forceinline__ u32x2 pack4(f32x4 v) { u32x2 w; w.x = pk2(v[0], v[1]); w.y = pk2(v[2], v[3]); return w; }
; template <int NR, bool XIN16 = false, bool XOUT16 = false> ...
;     ...
;         for (int o = 1; o < 64; o <<= 1) {
; #pragma unroll
;             for (int q = 0; q < NR; ++q) ss[q] += __shfl_xor(ss[q], o); }
; #pragma unroll
;         for (int q = 0; q < NR; ++q) { const float rstd = rsqrtf(ss[q] * (1.f / DM) + EPS);
;             if (XOUT16) { u32x2* xo = (u32x2*)((bf16_t*)xout + (size_t)(row + q * rstride) * DM) + lane;
; #pragma unroll
;                 for (int j = 0; j < 4; ++j) { xv[q][j] = xv[q][j] + g[j] * (yv[q][j] * rstd * gy[j]); xo[64 * j] = pack4(xv[q][j]); xv[q][j] = unpack4(pack4(xv[q][j])); } }
	v_pk_mul_f32 v[168:169], v[4:5], v[168:169]
	v_pk_mul_f32 v[158:159], v[6:7], v[158:159]
	v_cndmask_b32_e32 v40, v214, v40, vcc
	v_rsq_f32_e32 v40, v40
	v_pk_fma_f32 v[134:135], v[2:3], v[158:159], v[134:135]
	v_pk_fma_f32 v[98:99], v[0:1], v[168:169], v[98:99]
	v_pk_mul_f32 v[186:187], v[12:13], v[186:187]
	v_mul_f32_e32 v42, 0x45800000, v40
	v_cndmask_b32_e32 v40, v40, v42, vcc
	v_cvt_pk_bf16_f32 v98, v98, v99
	v_cvt_pk_bf16_f32 v99, v134, v135
	v_pk_mul_f32 v[134:135], v[40:41], v[184:185] op_sel_hi:[0,1]
	v_pk_mul_f32 v[158:159], v[40:41], v[182:183] op_sel_hi:[0,1]
	v_pk_mul_f32 v[158:159], v[28:29], v[158:159]
	v_pk_mul_f32 v[134:135], v[30:31], v[134:135]
	v_pk_fma_f32 v[128:129], v[24:25], v[158:159], v[128:129]
	v_pk_fma_f32 v[130:131], v[26:27], v[134:135], v[130:131]
	v_cvt_pk_bf16_f32 v128, v128, v129
	v_cvt_pk_bf16_f32 v129, v130, v131
	v_mov_b32_e32 v130, v179
	v_mov_b32_e32 v131, v181
	v_pk_mul_f32 v[130:131], v[40:41], v[130:131] op_sel_hi:[0,1]
	v_mov_b32_e32 v179, v180
	v_pk_mul_f32 v[130:131], v[22:23], v[130:131]
	v_pk_mul_f32 v[134:135], v[40:41], v[178:179] op_sel_hi:[0,1]
	v_pk_fma_f32 v[126:127], v[18:19], v[130:131], v[126:127]
	v_mov_b32_e32 v130, v210
	v_mov_b32_e32 v131, v198
	v_mov_b32_e32 v198, v211
	v_pk_mul_f32 v[134:135], v[20:21], v[134:135]
	v_pk_add_f32 v[130:131], v[130:131], v[198:199]
	v_pk_fma_f32 v[124:125], v[16:17], v[134:135], v[124:125]
	v_cvt_pk_bf16_f32 v124, v124, v125
	v_cvt_pk_bf16_f32 v125, v126, v127
	v_pk_mul_f32 v[126:127], v[40:41], v[166:167] op_sel_hi:[0,1]
	v_pk_mul_f32 v[126:127], v[14:15], v[126:127]
	s_nop 1
	v_add_f32_dpp v130, v130, v130 quad_perm:[1,0,3,2] row_mask:0xf bank_mask:0xf
	v_add_f32_dpp v131, v131, v131 quad_perm:[1,0,3,2] row_mask:0xf bank_mask:0xf
	v_pk_fma_f32 v[126:127], v[10:11], v[126:127], v[116:117]
	v_pk_mul_f32 v[118:119], v[40:41], v[118:119] op_sel_hi:[0,1]
	v_cvt_pk_bf16_f32 v117, v126, v127
	v_pk_mul_f32 v[118:119], v[4:5], v[118:119]
	s_nop 1
	v_add_f32_dpp v130, v130, v130 quad_perm:[2,3,0,1] row_mask:0xf bank_mask:0xf
	v_add_f32_dpp v131, v131, v131 quad_perm:[2,3,0,1] row_mask:0xf bank_mask:0xf
	v_pk_fma_f32 v[102:103], v[0:1], v[118:119], v[102:103]
	v_pk_mul_f32 v[122:123], v[40:41], v[122:123] op_sel_hi:[0,1]
	v_pk_mul_f32 v[122:123], v[6:7], v[122:123]
	v_pk_mul_f32 v[158:159], v[40:41], v[164:165] op_sel_hi:[0,1]
	s_nop 1
	v_add_f32_dpp v126, v130, v130 row_half_mirror row_mask:0xf bank_mask:0xf
	v_add_f32_dpp v127, v131, v131 row_half_mirror row_mask:0xf bank_mask:0xf
	v_pk_fma_f32 v[110:111], v[2:3], v[122:123], v[110:111]
	v_pk_mul_f32 v[158:159], v[12:13], v[158:159]
	v_cvt_pk_bf16_f32 v123, v110, v111
	v_cvt_pk_bf16_f32 v122, v102, v103
	s_nop 1
	v_add_f32_dpp v120, v126, v126 row_mirror row_mask:0xf bank_mask:0xf
	v_add_f32_dpp v121, v127, v127 row_mirror row_mask:0xf bank_mask:0xf
	v_pk_fma_f32 v[94:95], v[8:9], v[158:159], v[94:95]
	global_store_dwordx2 v[200:201], v[122:123], off offset:3584
	v_lshlrev_b32_e32 v102, 16, v122
	v_and_b32_e32 v158, 0xffff0000, v122
	s_nop 1
	v_readlane_b32 s98, v120, 0
	v_readlane_b32 s99, v120, 16
	v_readlane_b32 s100, v120, 32
	v_readlane_b32 s101, v120, 48
	s_nop 1
	v_mov_b32_e32 v228, s98
	v_add_f32_e32 v228, s99, v228
	v_mov_b32_e32 v229, s100
	v_add_f32_e32 v229, s101, v229
	v_add_f32_e32 v118, v228, v229
	v_readlane_b32 s98, v121, 0
	v_readlane_b32 s99, v121, 16
	v_readlane_b32 s100, v121, 32
	v_readlane_b32 s101, v121, 48
	s_nop 1
	v_mov_b32_e32 v228, s98
	v_add_f32_e32 v228, s99, v228
	v_mov_b32_e32 v229, s100
	v_add_f32_e32 v229, s101, v229
	v_add_f32_e32 v119, v228, v229
	v_pk_fma_f32 v[86:87], v[8:9], v[186:187], v[86:87]
	v_cvt_pk_bf16_f32 v116, v94, v95
	v_cvt_pk_bf16_f32 v146, v86, v87
	global_store_dwordx2 v[176:177], v[174:175], off offset:-4096
	v_mov_b32_e32 v110, v118
	v_mov_b32_e32 v111, v119
	global_store_dwordx2 v[200:201], v[154:155], off offset:512
	v_pk_fma_f32 v[118:119], v[110:111], s[82:83], v[74:75] op_sel_hi:[1,0,0]
	v_lshlrev_b32_e32 v110, 16, v123
	v_mul_f32_e32 v40, 0x4b800000, v119
	v_cmp_gt_f32_e32 vcc, s72, v119
	v_and_b32_e32 v111, 0xffff0000, v123
	global_store_dwordx2 v[200:201], v[146:147], off offset:1024
	v_cndmask_b32_e32 v40, v119, v40, vcc
	v_rsq_f32_e32 v40, v40
	global_store_dwordx2 v[200:201], v[98:99], off offset:1536
	global_store_dwordx2 v[200:201], v[128:129], off offset:2048
	global_store_dwordx2 v[200:201], v[124:125], off offset:2560
	v_mul_f32_e32 v42, 0x45800000, v40
	v_cndmask_b32_e32 v40, v40, v42, vcc
	v_pk_mul_f32 v[120:121], v[40:41], v[162:163] op_sel_hi:[0,1]
	v_pk_mul_f32 v[122:123], v[40:41], v[160:161] op_sel_hi:[0,1]
	v_pk_mul_f32 v[122:123], v[28:29], v[122:123]
	v_pk_mul_f32 v[120:121], v[30:31], v[120:121]
	v_pk_fma_f32 v[108:109], v[24:25], v[122:123], v[108:109]
	v_pk_fma_f32 v[114:115], v[26:27], v[120:121], v[114:115]
	v_cvt_pk_bf16_f32 v108, v108, v109
	v_cvt_pk_bf16_f32 v109, v114, v115
	v_mov_b32_e32 v114, v151
	v_mov_b32_e32 v115, v157
	v_mov_b32_e32 v151, v156
	v_pk_mul_f32 v[114:115], v[40:41], v[114:115] op_sel_hi:[0,1]
	v_pk_mul_f32 v[120:121], v[40:41], v[150:151] op_sel_hi:[0,1]
	v_pk_mul_f32 v[120:121], v[20:21], v[120:121]
	v_pk_mul_f32 v[114:115], v[22:23], v[114:115]
	v_pk_fma_f32 v[96:97], v[16:17], v[120:121], v[96:97]
	v_pk_fma_f32 v[100:101], v[18:19], v[114:115], v[100:101]
	v_cvt_pk_bf16_f32 v96, v96, v97
	v_cvt_pk_bf16_f32 v97, v100, v101
	v_pk_mul_f32 v[100:101], v[40:41], v[152:153] op_sel_hi:[0,1]
	v_pk_mul_f32 v[100:101], v[14:15], v[100:101]
	v_pk_mul_f32 v[114:115], v[40:41], v[148:149] op_sel_hi:[0,1]
	v_pk_fma_f32 v[100:101], v[10:11], v[100:101], v[92:93]
	v_pk_mul_f32 v[104:105], v[40:41], v[104:105] op_sel_hi:[0,1]
; __device__ __forceinline__ f32x4 unpack4(u32x2 w) { return (f32x4){bf_lo(w.x), bf_hi(w.x), bf_lo(w.y), bf_hi(w.y)}; }
; __device__ __forceinline__ u32x2 pack4(f32x4 v) { u32x2 w; w.x = pk2(v[0], v[1]); w.y = pk2(v[2], v[3]); return w; }
; template <int NR, bool XIN16 = false, bool XOUT16 = false> ...
;     ...
;             if (XOUT16) { u32x2* xo = (u32x2*)((bf16_t*)xout + (size_t)(row + q * rstride) * DM) + lane;
; #pragma unroll
;                 for (int j = 0; j < 4; ++j) { xv[q][j] = xv[q][j] + g[j] * (yv[q][j] * rstd * gy[j]); xo[64 * j] = pack4(xv[q][j]); xv[q][j] = unpack4(pack4(xv[q][j])); } }
;             else { f32x4* xo = (f32x4*)(xout + (size_t)(row + q * rstride) * DM) + lane;
; #pragma unroll
;                 for (int j = 0; j < 4; ++j) { xv[q][j] = xv[q][j] + g[j] * (yv[q][j] * rstd * gy[j]); xo[64 * j] = xv[q][j]; } } }
;     }
;     if (hout) {
;         f32x4 gh[4], s1[4], s0[4];
; #pragma unroll
;         for (int j = 0; j < 4; ++j) { gh[j] = ((const f32x4*)gainH)[lane + 64 * j]; s1[j] = ((const f32x4*)sc)[lane + 64 * j]; s0[j] = ((const f32x4*)sh)[lane + 64 * j]; }
;         float ss[NR];
; #pragma unroll
;         for (int q = 0; q < NR; ++q) { ss[q] = 0.f;
; #pragma unroll
;             for (int j = 0; j < 4; ++j) ss[q] += (xv[q][j][0] * xv[q][j][0] + xv[q][j][1] * xv[q][j][1]) + (xv[q][j][2] * xv[q][j][2] + xv[q][j][3] * xv[q][j][3]); }
	v_cvt_pk_bf16_f32 v93, v100, v101
	v_pk_mul_f32 v[100:101], v[40:41], v[106:107] op_sel_hi:[0,1]
	v_mul_f32_e32 v40, 0x4b800000, v118
	v_cmp_gt_f32_e32 vcc, s72, v118
	v_pk_mul_f32 v[104:105], v[4:5], v[104:105]
	v_pk_mul_f32 v[100:101], v[6:7], v[100:101]
	v_cndmask_b32_e32 v40, v118, v40, vcc
	v_rsq_f32_e32 v40, v40
	v_pk_fma_f32 v[84:85], v[2:3], v[100:101], v[84:85]
	v_pk_fma_f32 v[82:83], v[0:1], v[104:105], v[82:83]
	v_cvt_pk_bf16_f32 v101, v84, v85
	v_mul_f32_e32 v42, 0x45800000, v40
	v_cndmask_b32_e32 v42, v40, v42, vcc
	v_cvt_pk_bf16_f32 v100, v82, v83
	v_pk_mul_f32 v[104:105], v[42:43], v[142:143] op_sel_hi:[0,1]
	global_store_dwordx2 v[176:177], v[100:101], off offset:1536
	v_lshlrev_b32_e32 v82, 16, v100
	v_and_b32_e32 v148, 0xffff0000, v100
	v_lshlrev_b32_e32 v84, 16, v101
	v_and_b32_e32 v85, 0xffff0000, v101
	v_pk_mul_f32 v[100:101], v[42:43], v[144:145] op_sel_hi:[0,1]
	v_pk_mul_f32 v[28:29], v[28:29], v[104:105]
	v_pk_mul_f32 v[30:31], v[30:31], v[100:101]
	v_pk_fma_f32 v[24:25], v[24:25], v[28:29], v[78:79]
	v_pk_fma_f32 v[26:27], v[26:27], v[30:31], v[80:81]
	v_cvt_pk_bf16_f32 v104, v24, v25
	v_mov_b32_e32 v24, v137
	v_mov_b32_e32 v25, v141
	v_mov_b32_e32 v137, v140
	v_cvt_pk_bf16_f32 v105, v26, v27
	v_pk_mul_f32 v[24:25], v[42:43], v[24:25] op_sel_hi:[0,1]
	v_pk_mul_f32 v[26:27], v[42:43], v[136:137] op_sel_hi:[0,1]
	v_pk_mul_f32 v[20:21], v[20:21], v[26:27]
	v_pk_mul_f32 v[22:23], v[22:23], v[24:25]
	v_pk_fma_f32 v[16:17], v[16:17], v[20:21], v[44:45]
	v_pk_fma_f32 v[18:19], v[18:19], v[22:23], v[76:77]
	v_cvt_pk_bf16_f32 v150, v16, v17
	v_cvt_pk_bf16_f32 v151, v18, v19
	v_pk_mul_f32 v[16:17], v[42:43], v[138:139] op_sel_hi:[0,1]
	v_pk_mul_f32 v[18:19], v[42:43], v[132:133] op_sel_hi:[0,1]
	v_pk_mul_f32 v[114:115], v[12:13], v[114:115]
	v_pk_mul_f32 v[12:13], v[12:13], v[18:19]
	v_pk_mul_f32 v[14:15], v[14:15], v[16:17]
	v_pk_fma_f32 v[88:89], v[8:9], v[114:115], v[88:89]
	v_pk_fma_f32 v[10:11], v[10:11], v[14:15], v[38:39]
	v_pk_fma_f32 v[8:9], v[8:9], v[12:13], v[36:37]
	v_mov_b32_e32 v40, v43
	v_cvt_pk_bf16_f32 v144, v8, v9
	v_cvt_pk_bf16_f32 v145, v10, v11
	v_pk_mul_f32 v[8:9], v[42:43], v[46:47] op_sel_hi:[0,1]
	v_pk_mul_f32 v[10:11], v[42:43], v[40:41] op_sel_hi:[0,1]
	v_pk_mul_f32 v[4:5], v[4:5], v[10:11]
	v_pk_mul_f32 v[6:7], v[6:7], v[8:9]
	v_pk_fma_f32 v[0:1], v[0:1], v[4:5], v[32:33]
	v_pk_fma_f32 v[2:3], v[2:3], v[6:7], v[34:35]
	v_cvt_pk_bf16_f32 v92, v88, v89
	v_cvt_pk_bf16_f32 v0, v0, v1
	v_cvt_pk_bf16_f32 v1, v2, v3
	global_store_dwordx2 v[200:201], v[116:117], off offset:3072
	global_store_dwordx2 v[176:177], v[108:109], off
	global_store_dwordx2 v[176:177], v[96:97], off offset:512
	global_store_dwordx2 v[176:177], v[92:93], off offset:1024
	global_store_dwordx2 v[176:177], v[104:105], off offset:2048
	global_store_dwordx2 v[176:177], v[150:151], off offset:2560
	global_store_dwordx2 v[176:177], v[144:145], off offset:3072
	global_store_dwordx2 v[176:177], v[0:1], off offset:3584
	v_lshlrev_b32_e32 v76, 16, v144
	v_and_b32_e32 v77, 0xffff0000, v144
	v_lshlrev_b32_e32 v78, 16, v0
	v_and_b32_e32 v144, 0xffff0000, v0
	v_lshlrev_b32_e32 v80, 16, v1
	v_and_b32_e32 v81, 0xffff0000, v1
	global_load_dwordx4 v[24:27], v[64:65], off
	global_load_dwordx4 v[16:19], v[64:65], off offset:1024
	global_load_dwordx4 v[44:47], v204, s[20:21]
	global_load_dwordx4 v[40:43], v61, s[20:21]
	global_load_dwordx4 v[28:31], v204, s[14:15]
	global_load_dwordx4 v[20:23], v204, s[14:15] offset:1024
	global_load_dwordx4 v[8:11], v[64:65], off offset:2048
	global_load_dwordx4 v[0:3], v[64:65], off offset:3072
	global_load_dwordx4 v[36:39], v57, s[20:21]
	global_load_dwordx4 v[32:35], v53, s[20:21]
	global_load_dwordx4 v[12:15], v204, s[14:15] offset:2048
	global_load_dwordx4 v[4:7], v204, s[14:15] offset:3072
	v_and_b32_e32 v141, 0xffff0000, v175
	v_and_b32_e32 v140, 0xffff0000, v174
	v_and_b32_e32 v137, 0xffff0000, v155
	v_and_b32_e32 v136, 0xffff0000, v154
	v_lshlrev_b32_e32 v86, 16, v146
	v_and_b32_e32 v87, 0xffff0000, v146
	v_lshlrev_b32_e32 v90, 16, v98
	v_lshlrev_b32_e32 v139, 16, v175
	v_lshlrev_b32_e32 v138, 16, v174
	v_pk_mul_f32 v[100:101], v[140:141], v[140:141]
	v_lshlrev_b32_e32 v135, 16, v155
	v_lshlrev_b32_e32 v134, 16, v154
	v_pk_mul_f32 v[106:107], v[136:137], v[136:137]
	v_lshlrev_b32_e32 v132, 16, v147
	v_lshlrev_b32_e32 v88, 16, v92
	v_and_b32_e32 v89, 0xffff0000, v92
	v_pk_fma_f32 v[100:101], v[138:139], v[138:139], v[100:101]
	v_pk_fma_f32 v[106:107], v[134:135], v[134:135], v[106:107]
	v_mul_f32_e32 v91, v86, v86
	v_mul_f32_e32 v115, v87, v87
	v_and_b32_e32 v133, 0xffff0000, v147
	v_mul_f32_e32 v92, v132, v132
	v_mov_b32_e32 v114, v90
	v_and_b32_e32 v146, 0xffff0000, v98
	v_lshlrev_b32_e32 v98, 16, v99
	v_and_b32_e32 v99, 0xffff0000, v99
	v_pk_add_f32 v[100:101], v[100:101], v[100:101] op_sel_hi:[0,1]
	v_pk_add_f32 v[106:107], v[106:107], v[106:107] op_sel_hi:[0,1]
	v_pk_fma_f32 v[118:119], v[132:133], v[132:133], v[92:93] op_sel_hi:[1,1,0]
	v_pk_add_f32 v[114:115], v[90:91], v[114:115]
	v_mul_f32_e32 v118, v146, v146
	v_mul_f32_e32 v100, v98, v98
	v_mul_f32_e32 v106, v99, v99
	v_mul_f32_e32 v120, v90, v90
	v_mov_b32_e32 v121, v115
	v_pk_add_f32 v[114:115], v[120:121], v[118:119]
	v_pk_add_f32 v[100:101], v[100:101], v[106:107]
	v_lshlrev_b32_e32 v131, 16, v129
	v_lshlrev_b32_e32 v130, 16, v128
	v_and_b32_e32 v129, 0xffff0000, v129
	v_and_b32_e32 v128, 0xffff0000, v128
	v_and_b32_e32 v127, 0xffff0000, v125
	v_and_b32_e32 v126, 0xffff0000, v124
	v_lshlrev_b32_e32 v94, 16, v116
	v_and_b32_e32 v95, 0xffff0000, v116
	v_pk_add_f32 v[152:153], v[114:115], v[100:101]
	v_pk_mul_f32 v[100:101], v[128:129], v[128:129]
; __device__ __forceinline__ u32x2 pack4(f32x4 v) { u32x2 w; w.x = pk2(v[0], v[1]); w.y = pk2(v[2], v[3]); return w; }
; template <int NR, bool XIN16 = false, bool XOUT16 = false> ...
;     ...
;         float ss[NR];
; #pragma unroll
;         for (int q = 0; q < NR; ++q) { ss[q] = 0.f;
; #pragma unroll
;             for (int j = 0; j < 4; ++j) ss[q] += (xv[q][j][0] * xv[q][j][0] + xv[q][j][1] * xv[q][j][1]) + (xv[q][j][2] * xv[q][j][2] + xv[q][j][3] * xv[q][j][3]); }
; #pragma unroll
;         for (int o = 1; o < 64; o <<= 1) {
; #pragma unroll
;             for (int q = 0; q < NR; ++q) ss[q] += __shfl_xor(ss[q], o); }
; #pragma unroll
;         for (int q = 0; q < NR; ++q) { const float rstd = rsqrtf(ss[q] * (1.f / DM) + EPS);
;             u32x2* ho = (u32x2*)(hout + (size_t)(row + q * rstride) * DM) + lane;
; #pragma unroll
;             for (int j = 0; j < 4; ++j) { const f32x4 hv = (xv[q][j] * rstd * gh[j]) * (1.f + s1[j]) + s0[j]; ho[64 * j] = pack4(hv); } }
	v_lshlrev_b32_e32 v123, 16, v125
	v_lshlrev_b32_e32 v122, 16, v124
	v_pk_mul_f32 v[106:107], v[126:127], v[126:127]
	v_lshlrev_b32_e32 v120, 16, v117
	v_pk_fma_f32 v[100:101], v[130:131], v[130:131], v[100:101]
	v_pk_fma_f32 v[106:107], v[122:123], v[122:123], v[106:107]
	v_mul_f32_e32 v103, v94, v94
	v_mul_f32_e32 v115, v95, v95
	v_and_b32_e32 v121, 0xffff0000, v117
	v_mul_f32_e32 v92, v120, v120
	v_mov_b32_e32 v114, v102
	v_pk_add_f32 v[100:101], v[100:101], v[100:101] op_sel_hi:[0,1]
	v_pk_add_f32 v[106:107], v[106:107], v[106:107] op_sel_hi:[0,1]
	v_pk_fma_f32 v[116:117], v[120:121], v[120:121], v[92:93] op_sel_hi:[1,1,0]
	v_pk_add_f32 v[114:115], v[102:103], v[114:115]
	v_mul_f32_e32 v116, v158, v158
	v_mul_f32_e32 v100, v110, v110
	v_mul_f32_e32 v106, v111, v111
	v_mul_f32_e32 v118, v102, v102
	v_mov_b32_e32 v119, v115
	v_pk_add_f32 v[114:115], v[118:119], v[116:117]
	v_pk_add_f32 v[100:101], v[100:101], v[106:107]
	v_lshlrev_b32_e32 v117, 16, v109
	v_lshlrev_b32_e32 v116, 16, v108
	v_and_b32_e32 v119, 0xffff0000, v109
	v_and_b32_e32 v118, 0xffff0000, v108
	v_and_b32_e32 v109, 0xffff0000, v97
	v_and_b32_e32 v108, 0xffff0000, v96
	v_pk_add_f32 v[124:125], v[114:115], v[100:101]
	v_pk_mul_f32 v[100:101], v[118:119], v[118:119]
	v_lshlrev_b32_e32 v107, 16, v97
	v_lshlrev_b32_e32 v106, 16, v96
	v_pk_mul_f32 v[96:97], v[108:109], v[108:109]
	v_lshlrev_b32_e32 v114, 16, v93
	v_pk_fma_f32 v[100:101], v[116:117], v[116:117], v[100:101]
	v_pk_fma_f32 v[96:97], v[106:107], v[106:107], v[96:97]
	v_mul_f32_e32 v83, v88, v88
	v_mul_f32_e32 v143, v89, v89
	v_and_b32_e32 v115, 0xffff0000, v93
	v_mul_f32_e32 v92, v114, v114
	v_mov_b32_e32 v142, v82
	v_pk_add_f32 v[100:101], v[100:101], v[100:101] op_sel_hi:[0,1]
	v_pk_add_f32 v[96:97], v[96:97], v[96:97] op_sel_hi:[0,1]
	v_pk_fma_f32 v[92:93], v[114:115], v[114:115], v[92:93] op_sel_hi:[1,1,0]
	v_pk_add_f32 v[142:143], v[82:83], v[142:143]
	v_mul_f32_e32 v92, v148, v148
	v_mul_f32_e32 v100, v84, v84
	v_mul_f32_e32 v96, v85, v85
	v_mul_f32_e32 v154, v82, v82
	v_mov_b32_e32 v155, v143
	v_pk_add_f32 v[92:93], v[154:155], v[92:93]
	v_pk_add_f32 v[96:97], v[100:101], v[96:97]
	v_lshlrev_b32_e32 v101, 16, v105
	v_lshlrev_b32_e32 v100, 16, v104
	v_and_b32_e32 v105, 0xffff0000, v105
	v_and_b32_e32 v104, 0xffff0000, v104
	v_pk_add_f32 v[142:143], v[92:93], v[96:97]
	v_pk_mul_f32 v[92:93], v[104:105], v[104:105]
	v_and_b32_e32 v97, 0xffff0000, v151
	v_pk_fma_f32 v[92:93], v[100:101], v[100:101], v[92:93]
	v_and_b32_e32 v96, 0xffff0000, v150
	v_pk_add_f32 v[154:155], v[92:93], v[92:93] op_sel_hi:[0,1]
	v_lshlrev_b32_e32 v93, 16, v151
	v_lshlrev_b32_e32 v92, 16, v150
	v_mov_b32_e32 v150, v124
	v_mov_b32_e32 v151, v152
	v_mov_b32_e32 v152, v125
	v_pk_add_f32 v[124:125], v[150:151], v[152:153]
	v_pk_mul_f32 v[152:153], v[96:97], v[96:97]
	v_mul_f32_e32 v154, v80, v80
	v_pk_fma_f32 v[152:153], v[92:93], v[92:93], v[152:153]
	v_mul_f32_e32 v79, v76, v76
	s_nop 1
	v_add_f32_dpp v150, v124, v124 quad_perm:[1,0,3,2] row_mask:0xf bank_mask:0xf
	v_add_f32_dpp v151, v125, v125 quad_perm:[1,0,3,2] row_mask:0xf bank_mask:0xf
	v_pk_add_f32 v[152:153], v[152:153], v[152:153] op_sel_hi:[0,1]
	v_lshlrev_b32_e32 v124, 16, v145
	v_and_b32_e32 v125, 0xffff0000, v145
	v_mul_f32_e32 v152, v124, v124
	s_nop 1
	v_add_f32_dpp v150, v150, v150 quad_perm:[2,3,0,1] row_mask:0xf bank_mask:0xf
	v_add_f32_dpp v151, v151, v151 quad_perm:[2,3,0,1] row_mask:0xf bank_mask:0xf
	v_pk_fma_f32 v[162:163], v[124:125], v[124:125], v[152:153] op_sel_hi:[1,1,0]
	v_mul_f32_e32 v152, v81, v81
	v_pk_add_f32 v[152:153], v[154:155], v[152:153]
	v_mul_f32_e32 v161, v77, v77
	s_nop 1
	v_add_f32_dpp v150, v150, v150 row_half_mirror row_mask:0xf bank_mask:0xf
	v_add_f32_dpp v151, v151, v151 row_half_mirror row_mask:0xf bank_mask:0xf
	v_mov_b32_e32 v160, v78
	v_pk_add_f32 v[160:161], v[78:79], v[160:161]
	s_waitcnt vmcnt(3)
	v_pk_add_f32 v[38:39], v[38:39], 1.0 op_sel_hi:[1,0]
	v_pk_add_f32 v[36:37], v[36:37], 1.0 op_sel_hi:[1,0]
	s_nop 1
	v_add_f32_dpp v150, v150, v150 row_mirror row_mask:0xf bank_mask:0xf
	v_add_f32_dpp v151, v151, v151 row_mirror row_mask:0xf bank_mask:0xf
	v_mov_b32_e32 v91, v146
	s_waitcnt vmcnt(2)
	v_pk_add_f32 v[34:35], v[34:35], 1.0 op_sel_hi:[1,0]
	v_pk_add_f32 v[32:33], v[32:33], 1.0 op_sel_hi:[1,0]
	v_mul_f32_e32 v162, v144, v144
	s_nop 1
	v_readlane_b32 s98, v150, 0
	v_readlane_b32 s99, v150, 16
	v_readlane_b32 s100, v150, 32
	v_readlane_b32 s101, v150, 48
	s_nop 1
	v_mov_b32_e32 v228, s98
	v_add_f32_e32 v228, s99, v228
	v_mov_b32_e32 v229, s100
	v_add_f32_e32 v229, s101, v229
	v_add_f32_e32 v150, v228, v229
	v_readlane_b32 s98, v151, 0
	v_readlane_b32 s99, v151, 16
	v_readlane_b32 s100, v151, 32
	v_readlane_b32 s101, v151, 48
	s_nop 1
	v_mov_b32_e32 v228, s98
	v_add_f32_e32 v228, s99, v228
	v_mov_b32_e32 v229, s100
	v_add_f32_e32 v229, s101, v229
	v_add_f32_e32 v151, v228, v229
	v_mul_f32_e32 v164, v78, v78
	v_mov_b32_e32 v165, v161
	v_pk_add_f32 v[46:47], v[46:47], 1.0 op_sel_hi:[1,0]
	v_pk_add_f32 v[44:45], v[44:45], 1.0 op_sel_hi:[1,0]
	v_pk_add_f32 v[160:161], v[164:165], v[162:163]
	v_pk_fma_f32 v[150:151], v[150:151], s[82:83], v[74:75] op_sel_hi:[1,0,0]
	v_pk_add_f32 v[152:153], v[160:161], v[152:153]
	v_mul_f32_e32 v79, 0x4b800000, v151
	v_cmp_gt_f32_e32 vcc, s72, v151
	v_pk_add_f32 v[42:43], v[42:43], 1.0 op_sel_hi:[1,0]
	v_pk_add_f32 v[40:41], v[40:41], 1.0 op_sel_hi:[1,0]
	v_cndmask_b32_e32 v79, v151, v79, vcc
	v_rsq_f32_e32 v79, v79
	v_mov_b32_e32 v156, v139
	v_mov_b32_e32 v157, v141
	v_mov_b32_e32 v139, v140
	v_mul_f32_e32 v83, 0x45800000, v79
	v_cndmask_b32_e32 v154, v79, v83, vcc
	v_pk_mul_f32 v[132:133], v[154:155], v[132:133] op_sel_hi:[0,1]
	v_pk_mul_f32 v[86:87], v[154:155], v[86:87] op_sel_hi:[0,1]
	v_pk_mul_f32 v[86:87], v[8:9], v[86:87]
	v_pk_mul_f32 v[132:133], v[10:11], v[132:133]
	v_mul_f32_e32 v79, 0x4b800000, v150
	v_cmp_gt_f32_e32 vcc, s72, v150
	s_waitcnt vmcnt(1)
; __device__ __forceinline__ u32x2 pack4(f32x4 v) { u32x2 w; w.x = pk2(v[0], v[1]); w.y = pk2(v[2], v[3]); return w; }
; template <int NR, bool XIN16 = false, bool XOUT16 = false> ...
;     ...
;         for (int o = 1; o < 64; o <<= 1) {
; #pragma unroll
;             for (int q = 0; q < NR; ++q) ss[q] += __shfl_xor(ss[q], o); }
; #pragma unroll
;         for (int q = 0; q < NR; ++q) { const float rstd = rsqrtf(ss[q] * (1.f / DM) + EPS);
;             u32x2* ho = (u32x2*)(hout + (size_t)(row + q * rstride) * DM) + lane;
; #pragma unroll
;             for (int j = 0; j < 4; ++j) { const f32x4 hv = (xv[q][j] * rstd * gh[j]) * (1.f + s1[j]) + s0[j]; ho[64 * j] = pack4(hv); } }
	v_pk_fma_f32 v[132:133], v[38:39], v[132:133], v[14:15]
	v_pk_fma_f32 v[86:87], v[36:37], v[86:87], v[12:13]
	v_cndmask_b32_e32 v79, v150, v79, vcc
	v_cvt_pk_bf16_f32 v86, v86, v87
	v_cvt_pk_bf16_f32 v87, v132, v133
	v_rsq_f32_e32 v79, v79
	global_store_dwordx2 v[72:73], v[86:87], off offset:1024
	v_pk_mul_f32 v[86:87], v[154:155], v[98:99] op_sel_hi:[0,1]
	v_pk_mul_f32 v[90:91], v[154:155], v[90:91] op_sel_hi:[0,1]
	v_pk_mul_f32 v[90:91], v[0:1], v[90:91]
	v_pk_mul_f32 v[86:87], v[2:3], v[86:87]
	s_waitcnt vmcnt(1)
	v_pk_fma_f32 v[90:91], v[32:33], v[90:91], v[4:5]
	v_pk_fma_f32 v[86:87], v[34:35], v[86:87], v[6:7]
	v_cvt_pk_bf16_f32 v90, v90, v91
	v_cvt_pk_bf16_f32 v91, v86, v87
	v_mul_f32_e32 v83, 0x45800000, v79
	global_store_dwordx2 v[72:73], v[90:91], off offset:1536
	v_cndmask_b32_e32 v86, v79, v83, vcc
	v_mov_b32_e32 v90, v131
	v_mov_b32_e32 v91, v129
	v_mov_b32_e32 v131, v128
	v_pk_mul_f32 v[90:91], v[86:87], v[90:91] op_sel_hi:[0,1]
	v_pk_mul_f32 v[98:99], v[86:87], v[130:131] op_sel_hi:[0,1]
	v_pk_mul_f32 v[98:99], v[24:25], v[98:99]
	v_pk_mul_f32 v[90:91], v[26:27], v[90:91]
	v_pk_fma_f32 v[98:99], v[44:45], v[98:99], v[28:29]
	v_pk_fma_f32 v[90:91], v[46:47], v[90:91], v[30:31]
	v_cvt_pk_bf16_f32 v98, v98, v99
	v_cvt_pk_bf16_f32 v99, v90, v91
	global_store_dwordx2 v[72:73], v[98:99], off offset:2048
	v_mov_b32_e32 v98, v152
	v_mov_b32_e32 v99, v142
	v_mov_b32_e32 v142, v153
	v_pk_add_f32 v[98:99], v[98:99], v[142:143]
	v_mov_b32_e32 v90, v123
	v_mov_b32_e32 v91, v127
	v_mov_b32_e32 v123, v126
	v_pk_mul_f32 v[90:91], v[86:87], v[90:91] op_sel_hi:[0,1]
	v_pk_mul_f32 v[122:123], v[86:87], v[122:123] op_sel_hi:[0,1]
	v_pk_mul_f32 v[122:123], v[16:17], v[122:123]
	v_pk_mul_f32 v[90:91], v[18:19], v[90:91]
	s_nop 1
	v_add_f32_dpp v98, v98, v98 quad_perm:[1,0,3,2] row_mask:0xf bank_mask:0xf
	v_add_f32_dpp v99, v99, v99 quad_perm:[1,0,3,2] row_mask:0xf bank_mask:0xf
	v_pk_fma_f32 v[90:91], v[42:43], v[90:91], v[22:23]
	v_pk_fma_f32 v[122:123], v[40:41], v[122:123], v[20:21]
	v_pk_mul_f32 v[156:157], v[154:155], v[156:157] op_sel_hi:[0,1]
	v_cvt_pk_bf16_f32 v122, v122, v123
	v_cvt_pk_bf16_f32 v123, v90, v91
	s_nop 1
	v_add_f32_dpp v90, v98, v98 quad_perm:[2,3,0,1] row_mask:0xf bank_mask:0xf
	v_add_f32_dpp v91, v99, v99 quad_perm:[2,3,0,1] row_mask:0xf bank_mask:0xf
	v_pk_mul_f32 v[138:139], v[154:155], v[138:139] op_sel_hi:[0,1]
	v_pk_mul_f32 v[138:139], v[24:25], v[138:139]
	v_pk_mul_f32 v[140:141], v[26:27], v[156:157]
	v_pk_mul_f32 v[120:121], v[86:87], v[120:121] op_sel_hi:[0,1]
	s_nop 1
	v_add_f32_dpp v90, v90, v90 row_half_mirror row_mask:0xf bank_mask:0xf
	v_add_f32_dpp v91, v91, v91 row_half_mirror row_mask:0xf bank_mask:0xf
	v_pk_mul_f32 v[94:95], v[86:87], v[94:95] op_sel_hi:[0,1]
	v_pk_fma_f32 v[140:141], v[46:47], v[140:141], v[30:31]
	v_pk_fma_f32 v[138:139], v[44:45], v[138:139], v[28:29]
	v_pk_mul_f32 v[94:95], v[8:9], v[94:95]
	s_nop 1
	v_add_f32_dpp v90, v90, v90 row_mirror row_mask:0xf bank_mask:0xf
	v_add_f32_dpp v91, v91, v91 row_mirror row_mask:0xf bank_mask:0xf
	v_pk_mul_f32 v[120:121], v[10:11], v[120:121]
	v_cvt_pk_bf16_f32 v138, v138, v139
	v_cvt_pk_bf16_f32 v139, v140, v141
	v_pk_fma_f32 v[120:121], v[38:39], v[120:121], v[14:15]
	s_nop 1
	v_readlane_b32 s98, v90, 0
	v_readlane_b32 s99, v90, 16
	v_readlane_b32 s100, v90, 32
	v_readlane_b32 s101, v90, 48
	s_nop 1
	v_mov_b32_e32 v228, s98
	v_add_f32_e32 v228, s99, v228
	v_mov_b32_e32 v229, s100
	v_add_f32_e32 v229, s101, v229
	v_add_f32_e32 v90, v228, v229
	v_readlane_b32 s98, v91, 0
	v_readlane_b32 s99, v91, 16
	v_readlane_b32 s100, v91, 32
	v_readlane_b32 s101, v91, 48
	s_nop 1
	v_mov_b32_e32 v228, s98
	v_add_f32_e32 v228, s99, v228
	v_mov_b32_e32 v229, s100
	v_add_f32_e32 v229, s101, v229
	v_add_f32_e32 v91, v228, v229
	v_pk_fma_f32 v[94:95], v[36:37], v[94:95], v[12:13]
	global_store_dwordx2 v[70:71], v[138:139], off offset:-4096
	v_mov_b32_e32 v138, v135
	v_mov_b32_e32 v139, v137
	v_mov_b32_e32 v135, v136
	v_pk_fma_f32 v[74:75], v[90:91], s[82:83], v[74:75] op_sel_hi:[1,0,0]
	v_cvt_pk_bf16_f32 v94, v94, v95
	v_mul_f32_e32 v79, 0x4b800000, v75
	v_cmp_gt_f32_e32 vcc, s72, v75
	v_cvt_pk_bf16_f32 v95, v120, v121
	v_mov_b32_e32 v103, v158
	v_cndmask_b32_e32 v75, v75, v79, vcc
	v_pk_mul_f32 v[138:139], v[154:155], v[138:139] op_sel_hi:[0,1]
	v_pk_mul_f32 v[134:135], v[154:155], v[134:135] op_sel_hi:[0,1]
	global_store_dwordx2 v[72:73], v[94:95], off offset:3072
	v_pk_mul_f32 v[94:95], v[86:87], v[110:111] op_sel_hi:[0,1]
	v_pk_mul_f32 v[86:87], v[86:87], v[102:103] op_sel_hi:[0,1]
	v_rsq_f32_e32 v75, v75
	v_pk_mul_f32 v[134:135], v[16:17], v[134:135]
	v_pk_mul_f32 v[136:137], v[18:19], v[138:139]
	v_pk_mul_f32 v[86:87], v[0:1], v[86:87]
	v_pk_mul_f32 v[94:95], v[2:3], v[94:95]
	v_pk_fma_f32 v[136:137], v[42:43], v[136:137], v[22:23]
	v_pk_fma_f32 v[134:135], v[40:41], v[134:135], v[20:21]
	v_pk_fma_f32 v[94:95], v[34:35], v[94:95], v[6:7]
	v_pk_fma_f32 v[86:87], v[32:33], v[86:87], v[4:5]
	v_cvt_pk_bf16_f32 v134, v134, v135
	v_cvt_pk_bf16_f32 v135, v136, v137
	v_cvt_pk_bf16_f32 v86, v86, v87
	v_cvt_pk_bf16_f32 v87, v94, v95
	global_store_dwordx2 v[72:73], v[134:135], off offset:512
	global_store_dwordx2 v[72:73], v[122:123], off offset:2560
	global_store_dwordx2 v[72:73], v[86:87], off offset:3584
	v_mul_f32_e32 v72, 0x45800000, v75
	v_cndmask_b32_e32 v72, v75, v72, vcc
	v_mov_b32_e32 v86, v117
	v_mov_b32_e32 v87, v119
	v_mov_b32_e32 v117, v118
	v_pk_mul_f32 v[86:87], v[72:73], v[86:87] op_sel_hi:[0,1]
	v_pk_mul_f32 v[90:91], v[72:73], v[116:117] op_sel_hi:[0,1]
	v_pk_mul_f32 v[90:91], v[24:25], v[90:91]
	v_pk_mul_f32 v[86:87], v[26:27], v[86:87]
; __device__ __forceinline__ f32x4 unpack4(u32x2 w) { return (f32x4){bf_lo(w.x), bf_hi(w.x), bf_lo(w.y), bf_hi(w.y)}; }
; __device__ __forceinline__ u32x2 pack4(f32x4 v) { u32x2 w; w.x = pk2(v[0], v[1]); w.y = pk2(v[2], v[3]); return w; }
; template <int NR, bool XIN16 = false, bool XOUT16 = false> ...
;     ...
;     for (int q = 0; q < NR; ++q) {
;         if (XIN16) { const u32x2* xr = (const u32x2*)((const bf16_t*)xin + (size_t)(row + q * rstride) * DM) + lane;
; #pragma unroll
;             for (int j = 0; j < 4; ++j) xv[q][j] = unpack4(xr[64 * j]); }
;         else { const f32x4* xr = (const f32x4*)(xin + (size_t)(row + q * rstride) * DM) + lane;
; #pragma unroll
;             for (int j = 0; j < 4; ++j) xv[q][j] = xr[64 * j]; } }
;     if (y) {
; #pragma unroll
;         for (int q = 0; q < NR; ++q) { const u32x2* yr = (const u32x2*)(y + (size_t)(row + q * rstride) * DM) + lane;
; #pragma unroll
;             for (int j = 0; j < 4; ++j) yv[q][j] = unpack4(yr[64 * j]); }
;     ...
;         for (int q = 0; q < NR; ++q) { const float rstd = rsqrtf(ss[q] * (1.f / DM) + EPS);
;             u32x2* ho = (u32x2*)(hout + (size_t)(row + q * rstride) * DM) + lane;
; #pragma unroll
;             for (int j = 0; j < 4; ++j) { const f32x4 hv = (xv[q][j] * rstd * gh[j]) * (1.f + s1[j]) + s0[j]; ho[64 * j] = pack4(hv); } }
	v_pk_fma_f32 v[90:91], v[44:45], v[90:91], v[28:29]
	v_pk_fma_f32 v[86:87], v[46:47], v[86:87], v[30:31]
	v_cvt_pk_bf16_f32 v90, v90, v91
	v_cvt_pk_bf16_f32 v91, v86, v87
	v_mov_b32_e32 v86, v107
	v_mov_b32_e32 v87, v109
	v_mov_b32_e32 v107, v108
	global_store_dwordx2 v[70:71], v[90:91], off
	v_pk_mul_f32 v[86:87], v[72:73], v[86:87] op_sel_hi:[0,1]
	v_pk_mul_f32 v[90:91], v[72:73], v[106:107] op_sel_hi:[0,1]
	v_pk_mul_f32 v[90:91], v[16:17], v[90:91]
	v_pk_mul_f32 v[86:87], v[18:19], v[86:87]
	v_mul_f32_e32 v75, 0x4b800000, v74
	v_cmp_gt_f32_e32 vcc, s72, v74
	v_pk_fma_f32 v[86:87], v[42:43], v[86:87], v[22:23]
	v_pk_fma_f32 v[90:91], v[40:41], v[90:91], v[20:21]
	v_mov_b32_e32 v83, v148
	v_cndmask_b32_e32 v74, v74, v75, vcc
	v_cvt_pk_bf16_f32 v90, v90, v91
	v_cvt_pk_bf16_f32 v91, v86, v87
	v_pk_mul_f32 v[86:87], v[72:73], v[114:115] op_sel_hi:[0,1]
	v_pk_mul_f32 v[88:89], v[72:73], v[88:89] op_sel_hi:[0,1]
	v_pk_mul_f32 v[84:85], v[72:73], v[84:85] op_sel_hi:[0,1]
	v_pk_mul_f32 v[72:73], v[72:73], v[82:83] op_sel_hi:[0,1]
	v_rsq_f32_e32 v74, v74
	v_pk_mul_f32 v[72:73], v[0:1], v[72:73]
	v_pk_mul_f32 v[82:83], v[2:3], v[84:85]
	v_pk_fma_f32 v[72:73], v[32:33], v[72:73], v[4:5]
	v_pk_fma_f32 v[82:83], v[34:35], v[82:83], v[6:7]
	v_cvt_pk_bf16_f32 v72, v72, v73
	v_cvt_pk_bf16_f32 v73, v82, v83
	global_store_dwordx2 v[70:71], v[72:73], off offset:1536
	v_mul_f32_e32 v72, 0x45800000, v74
	v_cndmask_b32_e32 v72, v74, v72, vcc
	v_mov_b32_e32 v74, v101
	v_mov_b32_e32 v75, v105
	v_mov_b32_e32 v101, v104
	v_pk_mul_f32 v[74:75], v[72:73], v[74:75] op_sel_hi:[0,1]
	v_pk_mul_f32 v[82:83], v[72:73], v[100:101] op_sel_hi:[0,1]
	v_pk_mul_f32 v[24:25], v[24:25], v[82:83]
	v_pk_mul_f32 v[26:27], v[26:27], v[74:75]
	v_pk_fma_f32 v[24:25], v[44:45], v[24:25], v[28:29]
	v_pk_fma_f32 v[26:27], v[46:47], v[26:27], v[30:31]
	v_cvt_pk_bf16_f32 v24, v24, v25
	v_cvt_pk_bf16_f32 v25, v26, v27
	global_store_dwordx2 v[70:71], v[24:25], off offset:2048
	v_mov_b32_e32 v24, v93
	v_mov_b32_e32 v25, v97
	v_mov_b32_e32 v93, v96
	v_pk_mul_f32 v[24:25], v[72:73], v[24:25] op_sel_hi:[0,1]
	v_pk_mul_f32 v[26:27], v[72:73], v[92:93] op_sel_hi:[0,1]
	v_pk_mul_f32 v[16:17], v[16:17], v[26:27]
	v_pk_mul_f32 v[18:19], v[18:19], v[24:25]
	v_pk_fma_f32 v[16:17], v[40:41], v[16:17], v[20:21]
	v_pk_fma_f32 v[18:19], v[42:43], v[18:19], v[22:23]
	v_cvt_pk_bf16_f32 v16, v16, v17
	v_cvt_pk_bf16_f32 v17, v18, v19
	global_store_dwordx2 v[70:71], v[16:17], off offset:2560
	v_pk_mul_f32 v[16:17], v[72:73], v[124:125] op_sel_hi:[0,1]
	v_pk_mul_f32 v[18:19], v[72:73], v[76:77] op_sel_hi:[0,1]
	v_pk_mul_f32 v[88:89], v[8:9], v[88:89]
	v_pk_mul_f32 v[86:87], v[10:11], v[86:87]
	v_pk_mul_f32 v[8:9], v[8:9], v[18:19]
	v_pk_mul_f32 v[10:11], v[10:11], v[16:17]
	v_pk_fma_f32 v[8:9], v[36:37], v[8:9], v[12:13]
	v_pk_fma_f32 v[10:11], v[38:39], v[10:11], v[14:15]
	v_cvt_pk_bf16_f32 v8, v8, v9
	v_cvt_pk_bf16_f32 v9, v10, v11
	v_mov_b32_e32 v79, v144
	global_store_dwordx2 v[70:71], v[8:9], off offset:3072
	v_pk_mul_f32 v[8:9], v[72:73], v[80:81] op_sel_hi:[0,1]
	v_pk_mul_f32 v[10:11], v[72:73], v[78:79] op_sel_hi:[0,1]
	v_pk_mul_f32 v[0:1], v[0:1], v[10:11]
	v_pk_mul_f32 v[2:3], v[2:3], v[8:9]
	v_pk_fma_f32 v[86:87], v[38:39], v[86:87], v[14:15]
	v_pk_fma_f32 v[88:89], v[36:37], v[88:89], v[12:13]
	v_pk_fma_f32 v[2:3], v[34:35], v[2:3], v[6:7]
	v_pk_fma_f32 v[0:1], v[32:33], v[0:1], v[4:5]
	v_cvt_pk_bf16_f32 v88, v88, v89
	v_cvt_pk_bf16_f32 v89, v86, v87
	v_cvt_pk_bf16_f32 v0, v0, v1
	v_cvt_pk_bf16_f32 v1, v2, v3
	global_store_dwordx2 v[70:71], v[90:91], off offset:512
	global_store_dwordx2 v[70:71], v[88:89], off offset:1024
	global_store_dwordx2 v[70:71], v[0:1], off offset:3584
	s_mov_b64 s[14:15], 0
.LBB0_1371:
	s_andn2_b64 vcc, exec, s[14:15]
	s_cbranch_vccnz .LBB0_1368
	v_add_co_u32_e32 v0, vcc, 0x7401000, v68
	s_add_u32 s4, s27, 0x5000
	s_nop 0
	v_addc_co_u32_e32 v1, vcc, 0, v69, vcc
	v_add_co_u32_e32 v2, vcc, s84, v68
	s_addc_u32 s5, s9, 0
	s_nop 0
	v_addc_co_u32_e32 v3, vcc, 0, v69, vcc
	v_add_co_u32_e32 v30, vcc, s28, v68
	global_load_dwordx2 v[4:5], v[2:3], off offset:3584
	global_load_dwordx2 v[6:7], v[0:1], off offset:3584
	global_load_dwordx2 v[8:9], v[0:1], off offset:3072
	global_load_dwordx2 v[10:11], v[0:1], off offset:2560
	global_load_dwordx2 v[12:13], v[0:1], off offset:2048
	global_load_dwordx2 v[14:15], v[0:1], off offset:1536
	global_load_dwordx2 v[16:17], v[0:1], off offset:1024
	global_load_dwordx2 v[18:19], v[0:1], off offset:512
	s_nop 0
	global_load_dwordx2 v[0:1], v[0:1], off
	s_nop 0
	global_load_dwordx2 v[20:21], v[2:3], off offset:3072
	global_load_dwordx2 v[22:23], v[2:3], off offset:2560
	global_load_dwordx2 v[24:25], v[2:3], off offset:2048
	global_load_dwordx2 v[26:27], v[2:3], off offset:1536
	global_load_dwordx2 v[28:29], v[2:3], off offset:1024
	v_addc_co_u32_e32 v31, vcc, 0, v69, vcc
	v_add_co_u32_e32 v32, vcc, s29, v68
	global_load_dwordx2 v[80:81], v[2:3], off offset:512
	s_nop 0
	global_load_dwordx2 v[2:3], v[2:3], off
	v_addc_co_u32_e32 v33, vcc, 0, v69, vcc
	global_load_dwordx2 v[136:137], v[30:31], off offset:512
	global_load_dwordx2 v[138:139], v[30:31], off offset:1024
	global_load_dwordx2 v[84:85], v[30:31], off offset:1536
	global_load_dwordx2 v[142:143], v[32:33], off offset:-4096
	global_load_dwordx2 v[134:135], v[30:31], off offset:2560
	global_load_dwordx2 v[132:133], v[30:31], off offset:3072
	global_load_dwordx2 v[86:87], v[30:31], off offset:3584
	global_load_dwordx2 v[130:131], v[32:33], off
	global_load_dwordx2 v[126:127], v[32:33], off offset:512
	global_load_dwordx2 v[122:123], v[32:33], off offset:1024
	global_load_dwordx2 v[96:97], v[32:33], off offset:1536
	global_load_dwordx2 v[118:119], v[32:33], off offset:2048
	global_load_dwordx2 v[116:117], v[32:33], off offset:2560
	global_load_dwordx2 v[120:121], v[32:33], off offset:3072
	global_load_dwordx2 v[144:145], v[32:33], off offset:3584
	global_load_dwordx2 v[148:149], v[30:31], off offset:2048
	v_xor_b32_e32 v92, 2, v240
	v_xor_b32_e32 v108, 8, v240
	v_xor_b32_e32 v158, 32, v240
	s_waitcnt vmcnt(31)
; __device__ __forceinline__ f32x4 unpack4(u32x2 w) { return (f32x4){bf_lo(w.x), bf_hi(w.x), bf_lo(w.y), bf_hi(w.y)}; }
; template <int NR, bool XIN16 = false, bool XOUT16 = false> ...
;     ...
;         if (XIN16) { const u32x2* xr = (const u32x2*)((const bf16_t*)xin + (size_t)(row + q * rstride) * DM) + lane;
; #pragma unroll
;             for (int j = 0; j < 4; ++j) xv[q][j] = unpack4(xr[64 * j]); }
;         else { const f32x4* xr = (const f32x4*)(xin + (size_t)(row + q * rstride) * DM) + lane;
; #pragma unroll
;             for (int j = 0; j < 4; ++j) xv[q][j] = xr[64 * j]; } }
;     if (y) {
; #pragma unroll
;         for (int q = 0; q < NR; ++q) { const u32x2* yr = (const u32x2*)(y + (size_t)(row + q * rstride) * DM) + lane;
; #pragma unroll
;             for (int j = 0; j < 4; ++j) yv[q][j] = unpack4(yr[64 * j]); }
;         f32x4 g[4], gy[4];
; #pragma unroll
;         for (int j = 0; j < 4; ++j) { g[j] = ((const f32x4*)gate)[lane + 64 * j]; gy[j] = ((const f32x4*)gainY)[lane + 64 * j]; }
;         float ss[NR];
; #pragma unroll
;         for (int q = 0; q < NR; ++q) { ss[q] = 0.f;
; #pragma unroll
;             for (int j = 0; j < 4; ++j) ss[q] += (yv[q][j][0] * yv[q][j][0] + yv[q][j][1] * yv[q][j][1]) + (yv[q][j][2] * yv[q][j][2] + yv[q][j][3] * yv[q][j][3]); }
	v_lshlrev_b32_e32 v82, 16, v4
	s_waitcnt vmcnt(30)
	v_lshlrev_b32_e32 v32, 16, v6
	v_and_b32_e32 v33, 0xffff0000, v6
	v_lshlrev_b32_e32 v34, 16, v7
	v_and_b32_e32 v35, 0xffff0000, v7
	s_waitcnt vmcnt(29)
	v_lshlrev_b32_e32 v36, 16, v8
	v_and_b32_e32 v37, 0xffff0000, v8
	s_waitcnt vmcnt(15)
	v_and_b32_e32 v185, 0xffff0000, v137
	v_and_b32_e32 v184, 0xffff0000, v136
	s_waitcnt vmcnt(13)
	v_lshlrev_b32_e32 v161, 16, v84
	s_waitcnt vmcnt(12)
	v_and_b32_e32 v191, 0xffff0000, v143
	v_and_b32_e32 v189, 0xffff0000, v142
	v_lshlrev_b32_e32 v190, 16, v143
	v_lshlrev_b32_e32 v188, 16, v142
	v_lshlrev_b32_e32 v183, 16, v137
	v_lshlrev_b32_e32 v182, 16, v136
	v_pk_mul_f32 v[136:137], v[184:185], v[184:185]
	v_lshlrev_b32_e32 v166, 16, v80
	v_and_b32_e32 v167, 0xffff0000, v80
	v_lshlrev_b32_e32 v168, 16, v81
	v_and_b32_e32 v169, 0xffff0000, v81
	s_waitcnt vmcnt(1)
	v_and_b32_e32 v81, 0xffff0000, v144
	v_mul_f32_e32 v80, v191, v191
	v_pk_fma_f32 v[142:143], v[190:191], v[190:191], v[80:81] op_sel_hi:[1,1,0]
	v_mul_f32_e32 v80, v189, v189
	v_lshlrev_b32_e32 v178, 16, v138
	v_and_b32_e32 v179, 0xffff0000, v138
	v_lshlrev_b32_e32 v180, 16, v139
	v_and_b32_e32 v181, 0xffff0000, v139
	v_pk_fma_f32 v[138:139], v[188:189], v[188:189], v[80:81] op_sel_hi:[1,1,0]
	v_and_b32_e32 v159, 0xffff0000, v84
	v_lshlrev_b32_e32 v164, 16, v85
	v_and_b32_e32 v165, 0xffff0000, v85
	v_lshlrev_b32_e32 v111, 16, v86
	v_and_b32_e32 v109, 0xffff0000, v86
	v_lshlrev_b32_e32 v114, 16, v87
	v_and_b32_e32 v115, 0xffff0000, v87
	v_lshlrev_b32_e32 v85, 16, v144
	v_lshlrev_b32_e32 v86, 16, v145
	v_and_b32_e32 v87, 0xffff0000, v145
	v_pk_fma_f32 v[136:137], v[182:183], v[182:183], v[136:137]
	v_mov_b32_e32 v160, v138
	v_mov_b32_e32 v144, v142
	v_mov_b32_e32 v145, v161
	v_lshlrev_b32_e32 v38, 16, v9
	v_and_b32_e32 v39, 0xffff0000, v9
	v_lshlrev_b32_e32 v40, 16, v10
	v_and_b32_e32 v41, 0xffff0000, v10
	v_lshlrev_b32_e32 v42, 16, v11
	v_and_b32_e32 v43, 0xffff0000, v11
	v_lshlrev_b32_e32 v44, 16, v12
	v_and_b32_e32 v45, 0xffff0000, v12
	v_lshlrev_b32_e32 v46, 16, v13
	v_and_b32_e32 v47, 0xffff0000, v13
	v_lshlrev_b32_e32 v68, 16, v14
	v_and_b32_e32 v69, 0xffff0000, v14
	v_lshlrev_b32_e32 v70, 16, v15
	v_and_b32_e32 v71, 0xffff0000, v15
	v_lshlrev_b32_e32 v72, 16, v16
	v_and_b32_e32 v73, 0xffff0000, v16
	v_lshlrev_b32_e32 v74, 16, v17
	v_and_b32_e32 v75, 0xffff0000, v17
	v_lshlrev_b32_e32 v76, 16, v18
	v_and_b32_e32 v77, 0xffff0000, v18
	v_lshlrev_b32_e32 v78, 16, v19
	v_and_b32_e32 v79, 0xffff0000, v19
	v_lshlrev_b32_e32 v88, 16, v0
	v_and_b32_e32 v89, 0xffff0000, v0
	v_lshlrev_b32_e32 v90, 16, v1
	v_and_b32_e32 v91, 0xffff0000, v1
	v_and_b32_e32 v83, 0xffff0000, v4
	v_lshlrev_b32_e32 v98, 16, v5
	v_and_b32_e32 v99, 0xffff0000, v5
	v_lshlrev_b32_e32 v100, 16, v20
	v_and_b32_e32 v101, 0xffff0000, v20
	v_lshlrev_b32_e32 v102, 16, v21
	v_and_b32_e32 v103, 0xffff0000, v21
	v_lshlrev_b32_e32 v104, 16, v22
	v_and_b32_e32 v105, 0xffff0000, v22
	v_lshlrev_b32_e32 v106, 16, v23
	v_and_b32_e32 v107, 0xffff0000, v23
	v_lshlrev_b32_e32 v124, 16, v24
	v_and_b32_e32 v125, 0xffff0000, v24
	v_lshlrev_b32_e32 v128, 16, v25
	v_and_b32_e32 v129, 0xffff0000, v25
	v_lshlrev_b32_e32 v140, 16, v26
	v_and_b32_e32 v141, 0xffff0000, v26
	v_lshlrev_b32_e32 v146, 16, v27
	v_and_b32_e32 v147, 0xffff0000, v27
	v_lshlrev_b32_e32 v156, 16, v28
	v_and_b32_e32 v157, 0xffff0000, v28
	v_lshlrev_b32_e32 v162, 16, v29
	v_and_b32_e32 v163, 0xffff0000, v29
	v_lshlrev_b32_e32 v170, 16, v2
	v_and_b32_e32 v171, 0xffff0000, v2
	v_lshlrev_b32_e32 v172, 16, v3
	v_and_b32_e32 v173, 0xffff0000, v3
	global_load_dwordx4 v[24:27], v204, s[4:5]
	global_load_dwordx4 v[16:19], v61, s[4:5]
	global_load_dwordx4 v[28:31], v[50:51], off
	global_load_dwordx4 v[20:23], v[54:55], off
	global_load_dwordx4 v[8:11], v57, s[4:5]
	global_load_dwordx4 v[0:3], v53, s[4:5]
	global_load_dwordx4 v[12:15], v[58:59], off
	global_load_dwordx4 v[4:7], v[62:63], off
	v_mul_f32_e32 v53, v159, v159
	v_pk_add_f32 v[138:139], v[138:139], v[142:143]
	v_pk_mul_f32 v[142:143], v[160:161], v[144:145]
	v_pk_add_f32 v[136:137], v[136:137], v[136:137] op_sel:[0,1] op_sel_hi:[1,0]
	v_mov_b32_e32 v139, v143
	v_mov_b32_e32 v137, v53
	v_mul_f32_e32 v80, v179, v179
	v_pk_add_f32 v[136:137], v[138:139], v[136:137]
	v_pk_fma_f32 v[138:139], v[178:179], v[178:179], v[80:81] op_sel_hi:[1,1,0]
	v_mul_f32_e32 v80, v181, v181
	v_mul_f32_e32 v57, v164, v164
	v_mul_f32_e32 v61, v165, v165
	v_pk_fma_f32 v[142:143], v[180:181], v[180:181], v[80:81] op_sel_hi:[1,1,0]
	v_mov_b32_e32 v139, v57
	v_mov_b32_e32 v143, v61
	s_waitcnt vmcnt(8)
; template <int NR, bool XIN16 = false, bool XOUT16 = false> ...
;     ...
;         for (int q = 0; q < NR; ++q) { ss[q] = 0.f;
; #pragma unroll
;             for (int j = 0; j < 4; ++j) ss[q] += (yv[q][j][0] * yv[q][j][0] + yv[q][j][1] * yv[q][j][1]) + (yv[q][j][2] * yv[q][j][2] + yv[q][j][3] * yv[q][j][3]); }
; #pragma unroll
;         for (int o = 1; o < 64; o <<= 1) {
; #pragma unroll
;             for (int q = 0; q < NR; ++q) ss[q] += __shfl_xor(ss[q], o); }
	v_and_b32_e32 v177, 0xffff0000, v149
	v_pk_add_f32 v[138:139], v[138:139], v[142:143]
	v_and_b32_e32 v175, 0xffff0000, v148
	v_lshlrev_b32_e32 v176, 16, v149
	v_mul_f32_e32 v80, v177, v177
	v_pk_add_f32 v[192:193], v[136:137], v[138:139]
	v_lshlrev_b32_e32 v174, 16, v148
	v_pk_fma_f32 v[136:137], v[176:177], v[176:177], v[80:81] op_sel_hi:[1,1,0]
	v_and_b32_e32 v155, 0xffff0000, v135
	v_and_b32_e32 v154, 0xffff0000, v134
	v_mul_f32_e32 v80, v175, v175
	v_lshlrev_b32_e32 v153, 16, v135
	v_lshlrev_b32_e32 v152, 16, v134
	v_pk_mul_f32 v[134:135], v[154:155], v[154:155]
	v_lshlrev_b32_e32 v142, 16, v132
	v_and_b32_e32 v143, 0xffff0000, v132
	v_lshlrev_b32_e32 v148, 16, v133
	v_and_b32_e32 v149, 0xffff0000, v133
	v_pk_fma_f32 v[132:133], v[174:175], v[174:175], v[80:81] op_sel_hi:[1,1,0]
	v_pk_fma_f32 v[134:135], v[152:153], v[152:153], v[134:135]
	v_mov_b32_e32 v110, v132
	v_mov_b32_e32 v138, v136
	v_mov_b32_e32 v139, v111
	v_mul_f32_e32 v53, v109, v109
	v_pk_add_f32 v[132:133], v[132:133], v[136:137]
	v_pk_mul_f32 v[136:137], v[110:111], v[138:139]
	v_pk_add_f32 v[134:135], v[134:135], v[134:135] op_sel:[0,1] op_sel_hi:[1,0]
	v_mov_b32_e32 v133, v137
	v_mov_b32_e32 v135, v53
	v_mul_f32_e32 v80, v143, v143
	v_pk_add_f32 v[132:133], v[132:133], v[134:135]
	v_pk_fma_f32 v[134:135], v[142:143], v[142:143], v[80:81] op_sel_hi:[1,1,0]
	v_mul_f32_e32 v80, v149, v149
	v_mul_f32_e32 v57, v114, v114
	v_mul_f32_e32 v61, v115, v115
	v_pk_fma_f32 v[136:137], v[148:149], v[148:149], v[80:81] op_sel_hi:[1,1,0]
	v_and_b32_e32 v151, 0xffff0000, v131
	v_mov_b32_e32 v135, v57
	v_mov_b32_e32 v137, v61
	v_and_b32_e32 v145, 0xffff0000, v130
	v_lshlrev_b32_e32 v150, 16, v131
	v_mul_f32_e32 v80, v151, v151
	v_pk_add_f32 v[134:135], v[134:135], v[136:137]
	v_lshlrev_b32_e32 v144, 16, v130
	v_pk_fma_f32 v[130:131], v[150:151], v[150:151], v[80:81] op_sel_hi:[1,1,0]
	v_and_b32_e32 v139, 0xffff0000, v127
	v_and_b32_e32 v138, 0xffff0000, v126
	v_mul_f32_e32 v80, v145, v145
	v_lshlrev_b32_e32 v95, 16, v96
	v_pk_add_f32 v[198:199], v[132:133], v[134:135]
	v_lshlrev_b32_e32 v135, 16, v127
	v_lshlrev_b32_e32 v134, 16, v126
	v_pk_mul_f32 v[126:127], v[138:139], v[138:139]
	v_lshlrev_b32_e32 v132, 16, v122
	v_and_b32_e32 v133, 0xffff0000, v122
	v_lshlrev_b32_e32 v136, 16, v123
	v_and_b32_e32 v137, 0xffff0000, v123
	v_pk_fma_f32 v[122:123], v[144:145], v[144:145], v[80:81] op_sel_hi:[1,1,0]
	v_and_b32_e32 v93, 0xffff0000, v96
	v_pk_fma_f32 v[126:127], v[134:135], v[134:135], v[126:127]
	v_mov_b32_e32 v94, v122
	v_mov_b32_e32 v186, v130
	v_mov_b32_e32 v187, v95
	v_mul_f32_e32 v53, v93, v93
	v_pk_add_f32 v[122:123], v[122:123], v[130:131]
	v_pk_mul_f32 v[130:131], v[94:95], v[186:187]
	v_pk_add_f32 v[126:127], v[126:127], v[126:127] op_sel:[0,1] op_sel_hi:[1,0]
	v_mov_b32_e32 v123, v131
	v_mov_b32_e32 v127, v53
	v_mul_f32_e32 v80, v133, v133
	v_lshlrev_b32_e32 v96, 16, v97
	v_and_b32_e32 v97, 0xffff0000, v97
	v_pk_add_f32 v[122:123], v[122:123], v[126:127]
	v_pk_fma_f32 v[126:127], v[132:133], v[132:133], v[80:81] op_sel_hi:[1,1,0]
	v_mul_f32_e32 v80, v137, v137
	v_mul_f32_e32 v57, v96, v96
	v_mul_f32_e32 v61, v97, v97
	v_pk_fma_f32 v[130:131], v[136:137], v[136:137], v[80:81] op_sel_hi:[1,1,0]
	v_mov_b32_e32 v127, v57
	v_mov_b32_e32 v131, v61
	v_pk_add_f32 v[126:127], v[126:127], v[130:131]
	v_and_b32_e32 v131, 0xffff0000, v119
	v_pk_add_f32 v[186:187], v[122:123], v[126:127]
	v_and_b32_e32 v123, 0xffff0000, v117
	v_and_b32_e32 v122, 0xffff0000, v116
	v_lshlrev_b32_e32 v126, 16, v118
	v_and_b32_e32 v127, 0xffff0000, v118
	v_lshlrev_b32_e32 v130, 16, v119
	v_mul_f32_e32 v80, v131, v131
	v_lshlrev_b32_e32 v119, 16, v117
	v_lshlrev_b32_e32 v118, 16, v116
	v_pk_mul_f32 v[116:117], v[122:123], v[122:123]
	v_pk_fma_f32 v[200:201], v[130:131], v[130:131], v[80:81] op_sel_hi:[1,1,0]
	v_pk_fma_f32 v[202:203], v[118:119], v[118:119], v[116:117]
	v_mul_f32_e32 v80, v127, v127
	v_mul_f32_e32 v53, v81, v81
	v_pk_fma_f32 v[204:205], v[126:127], v[126:127], v[80:81] op_sel_hi:[1,1,0]
	v_pk_add_f32 v[202:203], v[202:203], v[202:203] op_sel:[0,1] op_sel_hi:[1,0]
	v_mov_b32_e32 v84, v204
	v_mov_b32_e32 v206, v200
	v_mov_b32_e32 v207, v85
	v_mov_b32_e32 v203, v53
	v_and_b32_e32 v53, 64, v240
	v_pk_add_f32 v[200:201], v[204:205], v[200:201]
	v_pk_mul_f32 v[204:205], v[84:85], v[206:207]
	v_add_u32_e32 v53, 64, v53
	v_xor_b32_e32 v84, 1, v240
	v_mov_b32_e32 v201, v205
	v_cmp_lt_i32_e32 vcc, v84, v53
	v_pk_add_f32 v[200:201], v[200:201], v[202:203]
	v_mov_b32_e32 v202, v198
	v_cndmask_b32_e32 v84, v240, v84, vcc
	v_mov_b32_e32 v203, v192
	v_mov_b32_e32 v192, v199
	v_lshlrev_b32_e32 v84, 2, v84
	v_pk_add_f32 v[192:193], v[202:203], v[192:193]
	v_cmp_lt_i32_e32 vcc, v92, v53
	v_xor_b32_e32 v94, 4, v240
	v_xor_b32_e32 v110, 16, v240
	v_cndmask_b32_e32 v92, v240, v92, vcc
	v_lshlrev_b32_e32 v92, 2, v92
	s_nop 1
	v_add_f32_dpp v192, v192, v192 quad_perm:[1,0,3,2] row_mask:0xf bank_mask:0xf
	v_add_f32_dpp v193, v193, v193 quad_perm:[1,0,3,2] row_mask:0xf bank_mask:0xf
	v_cmp_lt_i32_e32 vcc, v94, v53
	v_and_b32_e32 v117, 0xffff0000, v120
	v_lshlrev_b32_e32 v116, 16, v120
	v_cndmask_b32_e32 v94, v240, v94, vcc
	v_lshlrev_b32_e32 v94, 2, v94
	s_nop 1
	v_add_f32_dpp v192, v192, v192 quad_perm:[2,3,0,1] row_mask:0xf bank_mask:0xf
	v_add_f32_dpp v193, v193, v193 quad_perm:[2,3,0,1] row_mask:0xf bank_mask:0xf
	v_cmp_lt_i32_e32 vcc, v108, v53
	v_mul_f32_e32 v80, v117, v117
	v_mul_f32_e32 v57, v86, v86
	v_cndmask_b32_e32 v108, v240, v108, vcc
	v_lshlrev_b32_e32 v108, 2, v108
	s_nop 1
	v_add_f32_dpp v192, v192, v192 row_half_mirror row_mask:0xf bank_mask:0xf
	v_add_f32_dpp v193, v193, v193 row_half_mirror row_mask:0xf bank_mask:0xf
; __device__ __forceinline__ f32x4 unpack4(u32x2 w) { return (f32x4){bf_lo(w.x), bf_hi(w.x), bf_lo(w.y), bf_hi(w.y)}; }
; __device__ __forceinline__ u32x2 pack4(f32x4 v) { u32x2 w; w.x = pk2(v[0], v[1]); w.y = pk2(v[2], v[3]); return w; }
; template <int NR, bool XIN16 = false, bool XOUT16 = false> ...
;     ...
;         for (int q = 0; q < NR; ++q) { ss[q] = 0.f;
; #pragma unroll
;             for (int j = 0; j < 4; ++j) ss[q] += (yv[q][j][0] * yv[q][j][0] + yv[q][j][1] * yv[q][j][1]) + (yv[q][j][2] * yv[q][j][2] + yv[q][j][3] * yv[q][j][3]); }
; #pragma unroll
;         for (int o = 1; o < 64; o <<= 1) {
; #pragma unroll
;             for (int q = 0; q < NR; ++q) ss[q] += __shfl_xor(ss[q], o); }
; #pragma unroll
;         for (int q = 0; q < NR; ++q) { const float rstd = rsqrtf(ss[q] * (1.f / DM) + EPS);
;             if (XOUT16) { u32x2* xo = (u32x2*)((bf16_t*)xout + (size_t)(row + q * rstride) * DM) + lane;
; #pragma unroll
;                 for (int j = 0; j < 4; ++j) { xv[q][j] = xv[q][j] + g[j] * (yv[q][j] * rstd * gy[j]); xo[64 * j] = pack4(xv[q][j]); xv[q][j] = unpack4(pack4(xv[q][j])); } }
;             else { f32x4* xo = (f32x4*)(xout + (size_t)(row + q * rstride) * DM) + lane;
; #pragma unroll
;                 for (int j = 0; j < 4; ++j) { xv[q][j] = xv[q][j] + g[j] * (yv[q][j] * rstd * gy[j]); xo[64 * j] = xv[q][j]; } } }
	v_cmp_lt_i32_e32 vcc, v110, v53
	v_pk_fma_f32 v[202:203], v[116:117], v[116:117], v[80:81] op_sel_hi:[1,1,0]
	v_lshlrev_b32_e32 v120, 16, v121
	v_cndmask_b32_e32 v110, v240, v110, vcc
	v_lshlrev_b32_e32 v110, 2, v110
	s_nop 1
	v_add_f32_dpp v192, v192, v192 row_mirror row_mask:0xf bank_mask:0xf
	v_add_f32_dpp v193, v193, v193 row_mirror row_mask:0xf bank_mask:0xf
	v_cmp_lt_i32_e32 vcc, v158, v53
	v_mov_b32_e32 v203, v57
	v_and_b32_e32 v121, 0xffff0000, v121
	v_cndmask_b32_e32 v53, v240, v158, vcc
	v_lshlrev_b32_e32 v53, 2, v53
	s_nop 1
	v_readlane_b32 s98, v192, 0
	v_readlane_b32 s99, v192, 16
	v_readlane_b32 s100, v192, 32
	v_readlane_b32 s101, v192, 48
	s_nop 1
	v_mov_b32_e32 v228, s98
	v_add_f32_e32 v228, s99, v228
	v_mov_b32_e32 v229, s100
	v_add_f32_e32 v229, s101, v229
	v_add_f32_e32 v192, v228, v229
	v_readlane_b32 s98, v193, 0
	v_readlane_b32 s99, v193, 16
	v_readlane_b32 s100, v193, 32
	v_readlane_b32 s101, v193, 48
	s_nop 1
	v_mov_b32_e32 v228, s98
	v_add_f32_e32 v228, s99, v228
	v_mov_b32_e32 v229, s100
	v_add_f32_e32 v229, s101, v229
	v_add_f32_e32 v193, v228, v229
	v_mul_f32_e32 v80, v121, v121
	v_mul_f32_e32 v61, v87, v87
	v_pk_fma_f32 v[204:205], v[120:121], v[120:121], v[80:81] op_sel_hi:[1,1,0]
	v_mov_b32_e32 v158, v161
	v_mov_b64_e32 v[198:199], s[36:37]
	v_pk_fma_f32 v[192:193], v[192:193], s[82:83], v[198:199] op_sel_hi:[1,0,0]
	v_mov_b32_e32 v205, v61
	v_mul_f32_e32 v57, 0x4b800000, v193
	v_cmp_gt_f32_e32 vcc, s72, v193
	v_pk_add_f32 v[202:203], v[202:203], v[204:205]
	s_movk_i32 s4, 0x1000
	v_cndmask_b32_e32 v57, v193, v57, vcc
	v_rsq_f32_e32 v57, v57
	v_pk_add_f32 v[200:201], v[200:201], v[202:203]
	v_mul_f32_e32 v61, 0x45800000, v57
	v_cndmask_b32_e32 v80, v57, v61, vcc
	v_pk_mul_f32 v[190:191], v[80:81], v[190:191] op_sel_hi:[0,1]
	v_pk_mul_f32 v[188:189], v[80:81], v[188:189] op_sel_hi:[0,1]
	s_waitcnt vmcnt(5)
	v_pk_mul_f32 v[188:189], v[28:29], v[188:189]
	v_pk_mul_f32 v[190:191], v[30:31], v[190:191]
	v_pk_fma_f32 v[170:171], v[24:25], v[188:189], v[170:171]
	v_pk_fma_f32 v[172:173], v[26:27], v[190:191], v[172:173]
	global_store_dwordx4 v[66:67], v[170:173], off
	v_mul_f32_e32 v57, 0x4b800000, v192
	v_cmp_gt_f32_e32 vcc, s72, v192
	v_mov_b32_e32 v170, v183
	v_mov_b32_e32 v171, v185
	v_mov_b32_e32 v183, v184
	v_pk_mul_f32 v[170:171], v[80:81], v[170:171] op_sel_hi:[0,1]
	v_pk_mul_f32 v[172:173], v[80:81], v[182:183] op_sel_hi:[0,1]
	v_cndmask_b32_e32 v57, v192, v57, vcc
	s_waitcnt vmcnt(5)
	v_pk_mul_f32 v[172:173], v[20:21], v[172:173]
	v_pk_mul_f32 v[170:171], v[22:23], v[170:171]
	v_rsq_f32_e32 v57, v57
	v_pk_fma_f32 v[168:169], v[18:19], v[170:171], v[168:169]
	v_pk_fma_f32 v[166:167], v[16:17], v[172:173], v[166:167]
	global_store_dwordx4 v[66:67], v[166:169], off offset:1024
	v_pk_mul_f32 v[158:159], v[80:81], v[158:159] op_sel_hi:[0,1]
	v_mul_f32_e32 v61, 0x45800000, v57
	v_pk_mul_f32 v[166:167], v[80:81], v[180:181] op_sel_hi:[0,1]
	v_pk_mul_f32 v[168:169], v[80:81], v[178:179] op_sel_hi:[0,1]
	s_waitcnt vmcnt(3)
	v_pk_mul_f32 v[170:171], v[12:13], v[168:169]
	v_pk_mul_f32 v[166:167], v[14:15], v[166:167]
	s_waitcnt vmcnt(2)
	v_pk_mul_f32 v[160:161], v[4:5], v[158:159]
	v_pk_fma_f32 v[168:169], v[10:11], v[166:167], v[162:163]
	v_pk_fma_f32 v[166:167], v[8:9], v[170:171], v[156:157]
	v_pk_mul_f32 v[156:157], v[80:81], v[164:165] op_sel_hi:[0,1]
	v_pk_mul_f32 v[156:157], v[6:7], v[156:157]
	v_cndmask_b32_e32 v80, v57, v61, vcc
	v_pk_fma_f32 v[158:159], v[2:3], v[156:157], v[146:147]
	v_pk_fma_f32 v[156:157], v[0:1], v[160:161], v[140:141]
	v_pk_mul_f32 v[140:141], v[80:81], v[176:177] op_sel_hi:[0,1]
	v_pk_mul_f32 v[140:141], v[30:31], v[140:141]
	global_store_dwordx4 v[66:67], v[156:159], off offset:3072
	v_pk_mul_f32 v[146:147], v[80:81], v[174:175] op_sel_hi:[0,1]
	v_pk_mul_f32 v[146:147], v[28:29], v[146:147]
	v_pk_fma_f32 v[158:159], v[26:27], v[140:141], v[128:129]
	v_mov_b32_e32 v128, v200
	v_mov_b32_e32 v129, v186
	v_mov_b32_e32 v186, v201
	v_pk_add_f32 v[128:129], v[128:129], v[186:187]
	v_pk_fma_f32 v[156:157], v[24:25], v[146:147], v[124:125]
	v_add_co_u32_e32 v124, vcc, s4, v66
	s_movk_i32 s4, 0x2000
	s_nop 1
	v_add_f32_dpp v128, v128, v128 quad_perm:[1,0,3,2] row_mask:0xf bank_mask:0xf
	v_add_f32_dpp v129, v129, v129 quad_perm:[1,0,3,2] row_mask:0xf bank_mask:0xf
	v_addc_co_u32_e32 v125, vcc, 0, v67, vcc
	v_add_co_u32_e32 v146, vcc, s4, v66
	s_nop 1
	v_add_f32_dpp v128, v128, v128 quad_perm:[2,3,0,1] row_mask:0xf bank_mask:0xf
	v_add_f32_dpp v129, v129, v129 quad_perm:[2,3,0,1] row_mask:0xf bank_mask:0xf
	v_addc_co_u32_e32 v147, vcc, 0, v67, vcc
	global_store_dwordx4 v[146:147], v[156:159], off offset:-4096
	v_mov_b32_e32 v92, v95
	s_movk_i32 s4, 0x3000
	v_mov_b32_e32 v156, v153
	v_mov_b32_e32 v157, v155
	v_mov_b32_e32 v153, v154
	v_pk_mul_f32 v[156:157], v[80:81], v[156:157] op_sel_hi:[0,1]
	v_pk_mul_f32 v[152:153], v[80:81], v[152:153] op_sel_hi:[0,1]
	v_pk_mul_f32 v[152:153], v[20:21], v[152:153]
	v_pk_mul_f32 v[154:155], v[22:23], v[156:157]
	v_pk_fma_f32 v[104:105], v[16:17], v[152:153], v[104:105]
	v_pk_fma_f32 v[106:107], v[18:19], v[154:155], v[106:107]
	global_store_dwordx4 v[124:125], v[104:107], off offset:1024
	global_store_dwordx4 v[66:67], v[166:169], off offset:2048
	s_nop 1
	v_add_f32_dpp v104, v128, v128 row_half_mirror row_mask:0xf bank_mask:0xf
; __device__ __forceinline__ f32x4 unpack4(u32x2 w) { return (f32x4){bf_lo(w.x), bf_hi(w.x), bf_lo(w.y), bf_hi(w.y)}; }
; __device__ __forceinline__ u32x2 pack4(f32x4 v) { u32x2 w; w.x = pk2(v[0], v[1]); w.y = pk2(v[2], v[3]); return w; }
; template <int NR, bool XIN16 = false, bool XOUT16 = false> ...
;     ...
;         for (int q = 0; q < NR; ++q) { ss[q] = 0.f;
; #pragma unroll
;             for (int j = 0; j < 4; ++j) ss[q] += (yv[q][j][0] * yv[q][j][0] + yv[q][j][1] * yv[q][j][1]) + (yv[q][j][2] * yv[q][j][2] + yv[q][j][3] * yv[q][j][3]); }
; #pragma unroll
;         for (int o = 1; o < 64; o <<= 1) {
; #pragma unroll
;             for (int q = 0; q < NR; ++q) ss[q] += __shfl_xor(ss[q], o); }
; #pragma unroll
;         for (int q = 0; q < NR; ++q) { const float rstd = rsqrtf(ss[q] * (1.f / DM) + EPS);
;             if (XOUT16) { u32x2* xo = (u32x2*)((bf16_t*)xout + (size_t)(row + q * rstride) * DM) + lane;
; #pragma unroll
;                 for (int j = 0; j < 4; ++j) { xv[q][j] = xv[q][j] + g[j] * (yv[q][j] * rstd * gy[j]); xo[64 * j] = pack4(xv[q][j]); xv[q][j] = unpack4(pack4(xv[q][j])); } }
;             else { f32x4* xo = (f32x4*)(xout + (size_t)(row + q * rstride) * DM) + lane;
; #pragma unroll
;                 for (int j = 0; j < 4; ++j) { xv[q][j] = xv[q][j] + g[j] * (yv[q][j] * rstd * gy[j]); xo[64 * j] = xv[q][j]; } } }
	v_add_f32_dpp v105, v129, v129 row_half_mirror row_mask:0xf bank_mask:0xf
	v_pk_mul_f32 v[128:129], v[80:81], v[148:149] op_sel_hi:[0,1]
	v_pk_mul_f32 v[140:141], v[80:81], v[142:143] op_sel_hi:[0,1]
	v_pk_mul_f32 v[140:141], v[12:13], v[140:141]
	v_pk_mul_f32 v[128:129], v[14:15], v[128:129]
	s_nop 1
	v_add_f32_dpp v104, v104, v104 row_mirror row_mask:0xf bank_mask:0xf
	v_add_f32_dpp v105, v105, v105 row_mirror row_mask:0xf bank_mask:0xf
	v_pk_fma_f32 v[102:103], v[10:11], v[128:129], v[102:103]
	v_pk_fma_f32 v[100:101], v[8:9], v[140:141], v[100:101]
	global_store_dwordx4 v[124:125], v[100:103], off offset:2048
	v_mov_b32_e32 v108, v111
	s_nop 1
	v_readlane_b32 s98, v104, 0
	v_readlane_b32 s99, v104, 16
	v_readlane_b32 s100, v104, 32
	v_readlane_b32 s101, v104, 48
	s_nop 1
	v_mov_b32_e32 v228, s98
	v_add_f32_e32 v228, s99, v228
	v_mov_b32_e32 v229, s100
	v_add_f32_e32 v229, s101, v229
	v_add_f32_e32 v102, v228, v229
	v_readlane_b32 s98, v105, 0
	v_readlane_b32 s99, v105, 16
	v_readlane_b32 s100, v105, 32
	v_readlane_b32 s101, v105, 48
	s_nop 1
	v_mov_b32_e32 v228, s98
	v_add_f32_e32 v228, s99, v228
	v_mov_b32_e32 v229, s100
	v_add_f32_e32 v229, s101, v229
	v_add_f32_e32 v103, v228, v229
	v_pk_mul_f32 v[100:101], v[80:81], v[114:115] op_sel_hi:[0,1]
	v_pk_mul_f32 v[106:107], v[80:81], v[108:109] op_sel_hi:[0,1]
	v_pk_mul_f32 v[106:107], v[4:5], v[106:107]
	v_pk_mul_f32 v[100:101], v[6:7], v[100:101]
	v_pk_fma_f32 v[100:101], v[2:3], v[100:101], v[98:99]
	v_pk_fma_f32 v[102:103], v[102:103], s[82:83], v[198:199] op_sel_hi:[1,0,0]
	v_pk_fma_f32 v[98:99], v[0:1], v[106:107], v[82:83]
	v_mul_f32_e32 v53, 0x4b800000, v103
	v_cmp_gt_f32_e32 vcc, s72, v103
	global_store_dwordx4 v[124:125], v[98:101], off offset:3072
	s_nop 0
	v_cndmask_b32_e32 v53, v103, v53, vcc
	v_rsq_f32_e32 v53, v53
	s_nop 0
	v_mul_f32_e32 v57, 0x45800000, v53
	v_cndmask_b32_e32 v80, v53, v57, vcc
	v_pk_mul_f32 v[82:83], v[80:81], v[150:151] op_sel_hi:[0,1]
	v_pk_mul_f32 v[98:99], v[80:81], v[144:145] op_sel_hi:[0,1]
	v_pk_mul_f32 v[98:99], v[28:29], v[98:99]
	v_pk_mul_f32 v[82:83], v[30:31], v[82:83]
	v_pk_fma_f32 v[88:89], v[24:25], v[98:99], v[88:89]
	v_pk_fma_f32 v[90:91], v[26:27], v[82:83], v[90:91]
	v_mov_b32_e32 v82, v135
	v_mov_b32_e32 v83, v139
	v_mov_b32_e32 v135, v138
	global_store_dwordx4 v[146:147], v[88:91], off
	v_pk_mul_f32 v[82:83], v[80:81], v[82:83] op_sel_hi:[0,1]
	v_pk_mul_f32 v[82:83], v[22:23], v[82:83]
	v_pk_mul_f32 v[88:89], v[80:81], v[134:135] op_sel_hi:[0,1]
	v_pk_mul_f32 v[88:89], v[20:21], v[88:89]
	v_pk_fma_f32 v[78:79], v[18:19], v[82:83], v[78:79]
	v_pk_fma_f32 v[76:77], v[16:17], v[88:89], v[76:77]
	v_mul_f32_e32 v53, 0x4b800000, v102
	v_cmp_gt_f32_e32 vcc, s72, v102
	global_store_dwordx4 v[146:147], v[76:79], off offset:1024
	s_nop 0
	v_cndmask_b32_e32 v53, v102, v53, vcc
	v_pk_mul_f32 v[76:77], v[80:81], v[136:137] op_sel_hi:[0,1]
	v_pk_mul_f32 v[78:79], v[80:81], v[132:133] op_sel_hi:[0,1]
	v_pk_mul_f32 v[78:79], v[12:13], v[78:79]
	v_pk_mul_f32 v[76:77], v[14:15], v[76:77]
	v_rsq_f32_e32 v53, v53
	v_pk_fma_f32 v[74:75], v[10:11], v[76:77], v[74:75]
	v_pk_fma_f32 v[72:73], v[8:9], v[78:79], v[72:73]
	global_store_dwordx4 v[146:147], v[72:75], off offset:2048
	v_mul_f32_e32 v57, 0x45800000, v53
	s_nop 0
	v_pk_mul_f32 v[72:73], v[80:81], v[96:97] op_sel_hi:[0,1]
	v_pk_mul_f32 v[74:75], v[80:81], v[92:93] op_sel_hi:[0,1]
	v_pk_mul_f32 v[74:75], v[4:5], v[74:75]
	v_pk_mul_f32 v[72:73], v[6:7], v[72:73]
	v_pk_fma_f32 v[68:69], v[0:1], v[74:75], v[68:69]
	v_pk_fma_f32 v[70:71], v[2:3], v[72:73], v[70:71]
	global_store_dwordx4 v[146:147], v[68:71], off offset:3072
	v_mov_b32_e32 v80, v85
	s_nop 0
	v_cndmask_b32_e32 v68, v53, v57, vcc
	v_pk_mul_f32 v[72:73], v[68:69], v[126:127] op_sel_hi:[0,1]
	v_pk_mul_f32 v[70:71], v[68:69], v[130:131] op_sel_hi:[0,1]
	v_pk_mul_f32 v[28:29], v[28:29], v[72:73]
	v_pk_mul_f32 v[30:31], v[30:31], v[70:71]
	v_pk_fma_f32 v[24:25], v[24:25], v[28:29], v[44:45]
	v_add_co_u32_e32 v28, vcc, s4, v66
	v_pk_fma_f32 v[26:27], v[26:27], v[30:31], v[46:47]
	s_nop 0
	v_addc_co_u32_e32 v29, vcc, 0, v67, vcc
	global_store_dwordx4 v[28:29], v[24:27], off
	s_nop 1
	v_mov_b32_e32 v24, v119
	v_mov_b32_e32 v25, v123
	v_mov_b32_e32 v119, v122
	v_pk_mul_f32 v[24:25], v[68:69], v[24:25] op_sel_hi:[0,1]
	v_pk_mul_f32 v[26:27], v[68:69], v[118:119] op_sel_hi:[0,1]
	v_pk_mul_f32 v[20:21], v[20:21], v[26:27]
	v_pk_mul_f32 v[22:23], v[22:23], v[24:25]
	v_pk_fma_f32 v[16:17], v[16:17], v[20:21], v[40:41]
	v_pk_fma_f32 v[18:19], v[18:19], v[22:23], v[42:43]
	global_store_dwordx4 v[28:29], v[16:19], off offset:1024
	s_nop 1
	v_pk_mul_f32 v[16:17], v[68:69], v[120:121] op_sel_hi:[0,1]
	v_pk_mul_f32 v[18:19], v[68:69], v[116:117] op_sel_hi:[0,1]
	v_pk_mul_f32 v[12:13], v[12:13], v[18:19]
	v_pk_mul_f32 v[14:15], v[14:15], v[16:17]
	v_pk_fma_f32 v[8:9], v[8:9], v[12:13], v[36:37]
	v_pk_fma_f32 v[10:11], v[10:11], v[14:15], v[38:39]
	global_store_dwordx4 v[28:29], v[8:11], off offset:2048
	s_nop 1
	v_pk_mul_f32 v[8:9], v[68:69], v[86:87] op_sel_hi:[0,1]
	v_pk_mul_f32 v[10:11], v[68:69], v[80:81] op_sel_hi:[0,1]
	v_pk_mul_f32 v[4:5], v[4:5], v[10:11]
	v_pk_mul_f32 v[6:7], v[6:7], v[8:9]
	v_pk_fma_f32 v[0:1], v[0:1], v[4:5], v[32:33]
	v_pk_fma_f32 v[2:3], v[2:3], v[6:7], v[34:35]
	global_store_dwordx4 v[28:29], v[0:3], off offset:3072
	s_branch .LBB0_1368
